# GEMM3 ConvGLU epilogue: final (gelu*value)*r2 multiplies packed into v_pk_mul_f32 (bit-identical), gelu polynomial constant kept in a spare VGPR pair; -96 VALU per unit
# baseline (speedup 1.0000x reference)
.LBB0_624:
	s_add_u32 s38, s12, 0x6000000
	s_mov_b64 s[40:41], 0x80
	s_addc_u32 s39, s13, 0
	s_add_i32 m0, s72, 0x18000
	v_lshl_add_u64 v[8:9], v[8:9], 0, s[40:41]
	s_lshl_b32 s12, s3, 13
	s_lshl_b32 s79, s1, 5
	s_lshl_b32 s13, s1, 12
	s_waitcnt vmcnt(2)
	s_barrier
	global_load_lds_dwordx4 v[8:9], off
	v_lshl_add_u64 v[6:7], v[6:7], 0, s[40:41]
	s_add_i32 m0, s72, 0x1a000
	s_add_i32 s82, s72, 0x8000
	s_add_i32 s83, s72, 0xa000
	global_load_lds_dwordx4 v[6:7], off
	v_lshl_add_u64 v[4:5], v[4:5], 0, s[40:41]
	s_mov_b32 m0, s82
	s_add_u32 s6, s10, 0x80080
	global_load_lds_dwordx4 v[4:5], off
	v_lshl_add_u64 v[2:3], v[2:3], 0, s[40:41]
	s_mov_b32 m0, s83
	s_addc_u32 s7, s11, 0
	global_load_lds_dwordx4 v[2:3], off
	s_add_i32 m0, s72, 0x1c000
	v_lshl_add_u64 v[2:3], s[6:7], 0, v[154:155]
	global_load_lds_dwordx4 v[2:3], off
	v_lshl_add_u64 v[2:3], s[6:7], 0, v[158:159]
	s_add_i32 m0, s72, 0x1e000
	s_movk_i32 s6, 0x3c0
	global_load_lds_dwordx4 v[2:3], off
	v_lshlrev_b32_e32 v2, 4, v193
	v_lshlrev_b32_e32 v3, 6, v1
	v_lshlrev_b32_e32 v1, 2, v1
	v_and_or_b32 v3, v3, s6, v2
	v_and_b32_e32 v1, 32, v1
	v_bitop3_b32 v3, v3, s12, v1 bitop3:0xde
	v_lshl_or_b32 v1, v192, 6, v2
	v_lshlrev_b32_e32 v2, 2, v192
	v_and_b32_e32 v2, 32, v2
	v_bitop3_b32 v196, v1, s13, v2 bitop3:0xde
	s_cmpk_lt_u32 s0, 0x100
	v_mov_b32_e32 v1, v155
	s_cselect_b64 s[42:43], -1, 0
	s_and_b32 s0, s0, 0xffffff00
	s_lshl_b32 s1, s1, 6
	s_lshl_b32 s85, s3, 7
	v_lshl_add_u64 v[160:161], s[4:5], 0, v[0:1]
	v_lshlrev_b32_e32 v0, 15, v10
	s_or_b32 s84, s1, s0
	s_add_i32 s0, s85, 0x100
	v_and_b32_e32 v0, 0xffff0000, v0
	s_cmp_gt_i32 s3, 0
	v_lshl_add_u32 v0, v11, 12, v0
	v_and_b32_e32 v1, 1, v10
	s_cselect_b64 s[44:45], -1, 0
	s_cmp_lt_i32 s3, 3
	v_lshl_or_b32 v0, v1, 6, v0
	s_cselect_b64 s[46:47], -1, 0
	s_lshl_b32 s1, s3, 9
	s_add_i32 s86, s65, 0x80
	v_lshl_add_u32 v162, v12, 1, v0
	v_lshlrev_b32_e32 v0, 15, v13
	s_cmp_gt_i32 s3, -2
	v_and_b32_e32 v0, 0xffff0000, v0
	s_waitcnt vmcnt(6)
	s_cselect_b64 s[48:49], -1, 0
	s_cmp_lt_i32 s3, 1
	v_lshl_add_u32 v0, v14, 12, v0
	v_and_b32_e32 v1, 1, v13
	s_cselect_b64 s[50:51], -1, 0
	s_add_i32 s87, s1, 0x400
	s_add_i32 s89, 0, 0x20000
	s_add_i32 s93, 0, 0x20600
	v_lshl_or_b32 v0, v1, 6, v0
	s_add_i32 s94, 0, 0x10000
	s_add_i32 s95, 0, 0x14000
	s_ashr_i32 s88, s53, 31
	s_add_i32 s90, s89, s1
	s_add_i32 s91, s93, s1
	s_add_i32 s92, s89, s87
	s_add_i32 s93, s93, s87
	v_mov_b32_e32 v163, v155
	v_lshl_add_u32 v164, v15, 1, v0
	v_mov_b32_e32 v165, v155
	v_mov_b64_e32 v[166:167], 0xaeb
	v_mov_b64_e32 v[168:169], 0xaea
	v_add_u32_e32 v197, s94, v196
	v_add_u32_e32 v198, s95, v196
	v_add_u32_e32 v199, 0, v3
	s_add_i32 s96, 0, 0x21400
	v_mov_b32_e32 v200, 0x358637bd
	s_add_i32 s97, 0, 0x20800
	s_lshl_b32 s0, s0, 2
	s_mov_b32 s52, 0x3e6d3388
	s_mov_b32 s54, 0x3f07dc22
	s_mov_b32 s56, 0xbf3a00e3
	v_mov_b32_e32 v246, s56
	s_mov_b32 s58, 0x3f35f0e3
	s_mov_b32 s60, 0xbe11a98e
	s_mov_b32 s62, 0x3e027906
	s_mov_b32 s64, 0xbf38aa3b
	s_movk_i32 s31, 0x2b00
	s_movk_i32 s80, 0x1fff
	s_movk_i32 s81, 0x1ff0
	s_movk_i32 s26, 0x1fe0
	s_movk_i32 s27, 0x1fd0
	s_barrier
	s_branch .LBB0_627

.LBB0_667:
	v_pk_mul_f32 v[206:207], v[112:113], v[182:183] op_sel_hi:[1,0]
	v_pk_mul_f32 v[150:151], v[116:117], v[186:187] op_sel_hi:[1,0]
	v_pk_mul_f32 v[144:145], v[124:125], v[184:185] op_sel_hi:[1,0]
	s_waitcnt lgkmcnt(0)
	v_mov_b32_dpp v138, v206 row_shr:1 row_mask:0xf bank_mask:0xf
	v_mov_b32_dpp v139, v207 row_shr:1 row_mask:0xf bank_mask:0xf
	v_mov_b32_dpp v190, v150 row_ror:15 row_mask:0xf bank_mask:0xf
	v_mov_b32_dpp v191, v151 row_ror:15 row_mask:0xf bank_mask:0xf
	v_mov_b32_dpp v208, v206 row_ror:1 row_mask:0xf bank_mask:0xf
	v_mov_b32_dpp v209, v207 row_ror:1 row_mask:0xf bank_mask:0xf
	v_pk_mul_f32 v[138:139], v[134:135], v[138:139]
	v_pk_mul_f32 v[140:141], v[120:121], v[180:181] op_sel_hi:[1,0]
	v_mov_b32_dpp v146, v144 row_ror:1 row_mask:0xf bank_mask:0xf
	v_mov_b32_dpp v147, v145 row_ror:1 row_mask:0xf bank_mask:0xf
	v_mov_b32_dpp v188, v150 row_ror:1 row_mask:0xf bank_mask:0xf
	v_mov_b32_dpp v189, v151 row_ror:1 row_mask:0xf bank_mask:0xf
	v_pk_fma_f32 v[138:139], v[206:207], v[136:137], v[138:139]
	v_mov_b32_dpp v208, v150 row_shr:1 row_mask:0xf bank_mask:0xf
	v_mov_b32_dpp v190, v206 row_shl:1 row_mask:0xf bank_mask:0xf
	v_mov_b32_dpp v209, v151 row_shr:1 row_mask:0xf bank_mask:0xf
	v_mov_b32_dpp v191, v207 row_shl:1 row_mask:0xf bank_mask:0xf
	v_mov_b32_dpp v148, v144 row_ror:15 row_mask:0xf bank_mask:0xf
	v_mov_b32_dpp v149, v145 row_ror:15 row_mask:0xf bank_mask:0xf
	v_pk_fma_f32 v[138:139], v[128:129], v[190:191], v[138:139]
	v_pk_mul_f32 v[190:191], v[134:135], v[208:209]
	v_mov_b32_dpp v188, v144 row_shr:1 row_mask:0xf bank_mask:0xf
	v_mov_b32_dpp v189, v145 row_shr:1 row_mask:0xf bank_mask:0xf
	v_mov_b32_dpp v146, v140 row_shr:1 row_mask:0xf bank_mask:0xf
	v_mov_b32_dpp v147, v141 row_shr:1 row_mask:0xf bank_mask:0xf
	v_pk_add_f32 v[138:139], v[130:131], v[138:139]
	v_pk_fma_f32 v[190:191], v[150:151], v[136:137], v[190:191]
	v_mov_b32_dpp v148, v150 row_shl:1 row_mask:0xf bank_mask:0xf
	v_mov_b32_dpp v149, v151 row_shl:1 row_mask:0xf bank_mask:0xf
	v_pk_mul_f32 v[150:151], v[134:135], v[188:189]
	v_pk_mul_f32 v[134:135], v[134:135], v[146:147]
	v_pk_fma_f32 v[150:151], v[144:145], v[136:137], v[150:151]
	v_pk_fma_f32 v[134:135], v[140:141], v[136:137], v[134:135]
	v_and_b32_e32 v137, 0x7fffffff, v139
	v_and_b32_e32 v136, 0x7fffffff, v138
	v_mov_b32_dpp v142, v140 row_ror:15 row_mask:0xf bank_mask:0xf
	v_mov_b32_dpp v132, v140 row_shl:1 row_mask:0xf bank_mask:0xf
	v_mov_b32_dpp v143, v141 row_ror:15 row_mask:0xf bank_mask:0xf
	v_mov_b32_dpp v133, v141 row_shl:1 row_mask:0xf bank_mask:0xf
	v_pk_fma_f32 v[140:141], v[136:137], s[52:53], 1.0 op_sel_hi:[1,0,0]
	v_mov_b32_dpp v142, v144 row_shl:1 row_mask:0xf bank_mask:0xf
	v_rcp_f32_e32 v140, v140
	v_rcp_f32_e32 v141, v141
	v_mov_b32_dpp v143, v145 row_shl:1 row_mask:0xf bank_mask:0xf
	v_pk_fma_f32 v[148:149], v[128:129], v[148:149], v[190:191]
	v_pk_fma_f32 v[142:143], v[128:129], v[142:143], v[150:151]
	v_pk_fma_f32 v[128:129], v[128:129], v[132:133], v[134:135]
	v_pk_mul_f32 v[132:133], v[138:139], v[138:139]
	v_pk_add_f32 v[148:149], v[130:131], v[148:149]
	v_pk_add_f32 v[142:143], v[130:131], v[142:143]
	v_pk_add_f32 v[130:131], v[130:131], v[128:129]
	v_pk_fma_f32 v[128:129], v[140:141], s[54:55], v[246:247] op_sel_hi:[1,0,0]
	v_pk_mul_f32 v[132:133], v[132:133], s[64:65] op_sel_hi:[1,0]
	v_pk_fma_f32 v[128:129], v[140:141], v[128:129], s[58:59] op_sel_hi:[1,1,0]
	v_exp_f32_e32 v132, v132
	v_exp_f32_e32 v133, v133
	v_pk_fma_f32 v[128:129], v[140:141], v[128:129], s[60:61] op_sel_hi:[1,1,0]
	v_max_f32_e32 v138, 0, v138
	v_pk_fma_f32 v[128:129], v[140:141], v[128:129], s[62:63] op_sel_hi:[1,1,0]
	v_max_f32_e32 v139, 0, v139
	v_pk_mul_f32 v[128:129], v[140:141], v[128:129]
	v_pk_mul_f32 v[140:141], v[148:149], v[148:149]
	v_pk_mul_f32 v[128:129], v[132:133], v[128:129]
	v_and_b32_e32 v133, 0x7fffffff, v149
	v_and_b32_e32 v132, 0x7fffffff, v148
	v_pk_fma_f32 v[128:129], v[136:137], v[128:129], v[138:139] neg_lo:[1,0,0] neg_hi:[1,0,0]
	v_pk_fma_f32 v[136:137], v[132:133], s[52:53], 1.0 op_sel_hi:[1,0,0]
	v_pk_mul_f32 v[140:141], v[140:141], s[64:65] op_sel_hi:[1,0]
	v_rcp_f32_e32 v136, v136
	v_rcp_f32_e32 v137, v137
	v_exp_f32_e32 v140, v140
	v_exp_f32_e32 v141, v141
	v_pk_mul_f32 v[144:145], v[142:143], v[142:143]
	v_pk_fma_f32 v[138:139], v[136:137], s[54:55], v[246:247] op_sel_hi:[1,0,0]
	v_pk_mul_f32 v[144:145], v[144:145], s[64:65] op_sel_hi:[1,0]
	v_pk_fma_f32 v[138:139], v[136:137], v[138:139], s[58:59] op_sel_hi:[1,1,0]
	v_exp_f32_e32 v144, v144
	v_pk_fma_f32 v[138:139], v[136:137], v[138:139], s[60:61] op_sel_hi:[1,1,0]
	v_exp_f32_e32 v145, v145
	v_pk_fma_f32 v[138:139], v[136:137], v[138:139], s[62:63] op_sel_hi:[1,1,0]
	v_pk_mul_f32 v[136:137], v[136:137], v[138:139]
	v_max_f32_e32 v138, 0, v148
	v_max_f32_e32 v139, 0, v149
	v_pk_mul_f32 v[136:137], v[140:141], v[136:137]
	v_pk_mul_f32 v[128:129], v[108:109], v[128:129]
	v_pk_fma_f32 v[132:133], v[132:133], v[136:137], v[138:139] neg_lo:[1,0,0] neg_hi:[1,0,0]
	v_and_b32_e32 v137, 0x7fffffff, v143
	v_and_b32_e32 v136, 0x7fffffff, v142
	v_pk_fma_f32 v[138:139], v[136:137], s[52:53], 1.0 op_sel_hi:[1,0,0]
	v_rcp_f32_e32 v138, v138
	v_rcp_f32_e32 v139, v139
	v_pk_mul_f32 v[128:129], v[182:183], v[128:129] op_sel_hi:[0,1]
	v_cvt_pk_bf16_f32 v128, v128, v129
	v_pk_fma_f32 v[140:141], v[138:139], s[54:55], v[246:247] op_sel_hi:[1,0,0]
	v_pk_mul_f32 v[132:133], v[104:105], v[132:133]
	v_pk_fma_f32 v[140:141], v[138:139], v[140:141], s[58:59] op_sel_hi:[1,1,0]
	v_pk_fma_f32 v[140:141], v[138:139], v[140:141], s[60:61] op_sel_hi:[1,1,0]
	v_pk_mul_f32 v[132:133], v[186:187], v[132:133] op_sel_hi:[0,1]
	v_pk_fma_f32 v[140:141], v[138:139], v[140:141], s[62:63] op_sel_hi:[1,1,0]
	v_cvt_pk_bf16_f32 v132, v132, v133
	v_lshl_add_u32 v206, v204, 2, s89
	v_pk_mul_f32 v[138:139], v[138:139], v[140:141]
	v_max_f32_e32 v140, 0, v142
	v_max_f32_e32 v141, 0, v143
	v_pk_mul_f32 v[138:139], v[144:145], v[138:139]
	v_pk_mul_f32 v[142:143], v[130:131], v[130:131]
	v_pk_fma_f32 v[136:137], v[136:137], v[138:139], v[140:141] neg_lo:[1,0,0] neg_hi:[1,0,0]
	v_and_b32_e32 v139, 0x7fffffff, v131
	v_and_b32_e32 v138, 0x7fffffff, v130
	v_pk_fma_f32 v[140:141], v[138:139], s[52:53], 1.0 op_sel_hi:[1,0,0]
	v_pk_mul_f32 v[142:143], v[142:143], s[64:65] op_sel_hi:[1,0]
	v_rcp_f32_e32 v140, v140
	v_rcp_f32_e32 v141, v141
	v_exp_f32_e32 v142, v142
	v_exp_f32_e32 v143, v143
	v_mul_f32_e32 v129, v100, v136
	v_pk_fma_f32 v[134:135], v[140:141], s[54:55], v[246:247] op_sel_hi:[1,0,0]
	v_max_f32_e32 v130, 0, v130
	v_pk_fma_f32 v[134:135], v[140:141], v[134:135], s[58:59] op_sel_hi:[1,1,0]
	v_max_f32_e32 v131, 0, v131
	v_pk_fma_f32 v[134:135], v[140:141], v[134:135], s[60:61] op_sel_hi:[1,1,0]
	v_mul_f32_e32 v129, v184, v129
	v_pk_fma_f32 v[134:135], v[140:141], v[134:135], s[62:63] op_sel_hi:[1,1,0]
	v_mul_f32_e32 v133, v101, v137
	v_pk_mul_f32 v[134:135], v[140:141], v[134:135]
	v_mul_f32_e32 v133, v184, v133
	v_pk_mul_f32 v[134:135], v[142:143], v[134:135]
	v_cvt_pk_bf16_f32 v136, v129, v133
	v_add_u32_e32 v207, 8, v206
	v_pk_fma_f32 v[130:131], v[138:139], v[134:135], v[130:131] neg_lo:[1,0,0] neg_hi:[1,0,0]
	s_and_b64 vcc, exec, s[6:7]
	v_pk_mul_f32 v[130:131], v[96:97], v[130:131]
	v_pk_mul_f32 v[130:131], v[180:181], v[130:131] op_sel_hi:[0,1]
	v_cvt_pk_bf16_f32 v140, v130, v131
	ds_read2st64_b64 v[146:149], v207 offset0:10 offset1:11
	ds_read2st64_b64 v[142:145], v207 offset0:12 offset1:13
	v_mov_b32_e32 v130, 0
	v_mov_b32_e32 v134, 0
	v_mov_b32_e32 v135, 0
	s_cbranch_vccnz .LBB0_669
	v_lshl_add_u32 v129, v204, 2, s90
	ds_read_b64 v[134:135], v129 offset:1544

.LBB0_671:
	v_mov_b32_e32 v183, v182
	v_mov_b32_e32 v187, v186
	v_pk_mul_f32 v[218:219], v[114:115], v[182:183]
	v_mov_b32_e32 v185, v184
	v_pk_mul_f32 v[210:211], v[118:119], v[186:187]
	s_waitcnt lgkmcnt(0)
	v_mov_b32_dpp v134, v218 row_shr:1 row_mask:0xf bank_mask:0xf
	v_mov_b32_dpp v135, v219 row_shr:1 row_mask:0xf bank_mask:0xf
	v_mov_b32_e32 v181, v180
	v_pk_mul_f32 v[188:189], v[126:127], v[184:185]
	v_mov_b32_dpp v216, v210 row_ror:15 row_mask:0xf bank_mask:0xf
	v_mov_b32_dpp v217, v211 row_ror:15 row_mask:0xf bank_mask:0xf
	v_mov_b32_dpp v220, v218 row_ror:1 row_mask:0xf bank_mask:0xf
	v_mov_b32_dpp v221, v219 row_ror:1 row_mask:0xf bank_mask:0xf
	v_pk_mul_f32 v[134:135], v[146:147], v[134:135]
	v_pk_mul_f32 v[138:139], v[122:123], v[180:181]
	v_mov_b32_dpp v190, v188 row_ror:1 row_mask:0xf bank_mask:0xf
	v_mov_b32_dpp v191, v189 row_ror:1 row_mask:0xf bank_mask:0xf
	v_mov_b32_dpp v214, v210 row_ror:1 row_mask:0xf bank_mask:0xf
	v_mov_b32_dpp v215, v211 row_ror:1 row_mask:0xf bank_mask:0xf
	v_pk_fma_f32 v[134:135], v[218:219], v[148:149], v[134:135]
	v_mov_b32_dpp v220, v210 row_shr:1 row_mask:0xf bank_mask:0xf
	v_mov_b32_dpp v216, v218 row_shl:1 row_mask:0xf bank_mask:0xf
	v_mov_b32_dpp v221, v211 row_shr:1 row_mask:0xf bank_mask:0xf
	v_mov_b32_dpp v217, v219 row_shl:1 row_mask:0xf bank_mask:0xf
	v_mov_b32_dpp v208, v188 row_ror:15 row_mask:0xf bank_mask:0xf
	v_mov_b32_dpp v209, v189 row_ror:15 row_mask:0xf bank_mask:0xf
	v_pk_fma_f32 v[134:135], v[142:143], v[216:217], v[134:135]
	v_pk_mul_f32 v[216:217], v[146:147], v[220:221]
	v_mov_b32_dpp v214, v188 row_shr:1 row_mask:0xf bank_mask:0xf
	v_mov_b32_dpp v215, v189 row_shr:1 row_mask:0xf bank_mask:0xf
	v_mov_b32_dpp v190, v138 row_shr:1 row_mask:0xf bank_mask:0xf
	v_mov_b32_dpp v191, v139 row_shr:1 row_mask:0xf bank_mask:0xf
	v_pk_add_f32 v[134:135], v[144:145], v[134:135]
	v_pk_fma_f32 v[216:217], v[210:211], v[148:149], v[216:217]
	v_mov_b32_dpp v208, v210 row_shl:1 row_mask:0xf bank_mask:0xf
	v_mov_b32_dpp v209, v211 row_shl:1 row_mask:0xf bank_mask:0xf
	v_pk_mul_f32 v[210:211], v[146:147], v[214:215]
	v_pk_mul_f32 v[146:147], v[146:147], v[190:191]
	v_mov_b32_dpp v150, v138 row_ror:15 row_mask:0xf bank_mask:0xf
	v_mov_b32_dpp v130, v138 row_shl:1 row_mask:0xf bank_mask:0xf
	v_mov_b32_dpp v151, v139 row_ror:15 row_mask:0xf bank_mask:0xf
	v_mov_b32_dpp v131, v139 row_shl:1 row_mask:0xf bank_mask:0xf
	v_pk_fma_f32 v[138:139], v[138:139], v[148:149], v[146:147]
	v_and_b32_e32 v147, 0x7fffffff, v135
	v_and_b32_e32 v146, 0x7fffffff, v134
	v_pk_fma_f32 v[210:211], v[188:189], v[148:149], v[210:211]
	v_pk_fma_f32 v[148:149], v[146:147], s[52:53], 1.0 op_sel_hi:[1,0,0]
	v_mov_b32_dpp v150, v188 row_shl:1 row_mask:0xf bank_mask:0xf
	v_rcp_f32_e32 v148, v148
	v_rcp_f32_e32 v149, v149
	v_mov_b32_dpp v151, v189 row_shl:1 row_mask:0xf bank_mask:0xf
	v_pk_fma_f32 v[208:209], v[142:143], v[208:209], v[216:217]
	v_pk_fma_f32 v[150:151], v[142:143], v[150:151], v[210:211]
	v_pk_fma_f32 v[130:131], v[142:143], v[130:131], v[138:139]
	v_pk_add_f32 v[208:209], v[144:145], v[208:209]
	v_pk_add_f32 v[150:151], v[144:145], v[150:151]
	v_pk_add_f32 v[130:131], v[144:145], v[130:131]
	v_pk_mul_f32 v[144:145], v[134:135], v[134:135]
	v_pk_fma_f32 v[142:143], v[148:149], s[54:55], v[246:247] op_sel_hi:[1,0,0]
	v_pk_mul_f32 v[144:145], v[144:145], s[64:65] op_sel_hi:[1,0]
	v_pk_fma_f32 v[142:143], v[148:149], v[142:143], s[58:59] op_sel_hi:[1,1,0]
	v_exp_f32_e32 v144, v144
	v_exp_f32_e32 v145, v145
	v_pk_fma_f32 v[142:143], v[148:149], v[142:143], s[60:61] op_sel_hi:[1,1,0]
	v_max_f32_e32 v134, 0, v134
	v_pk_fma_f32 v[142:143], v[148:149], v[142:143], s[62:63] op_sel_hi:[1,1,0]
	v_max_f32_e32 v135, 0, v135
	v_pk_mul_f32 v[142:143], v[148:149], v[142:143]
	s_and_b64 vcc, exec, s[6:7]
	v_pk_mul_f32 v[142:143], v[144:145], v[142:143]
	s_nop 0
	v_pk_fma_f32 v[134:135], v[146:147], v[142:143], v[134:135] neg_lo:[1,0,0] neg_hi:[1,0,0]
	v_and_b32_e32 v143, 0x7fffffff, v209
	v_and_b32_e32 v142, 0x7fffffff, v208
	v_pk_fma_f32 v[144:145], v[142:143], s[52:53], 1.0 op_sel_hi:[1,0,0]
	v_pk_mul_f32 v[146:147], v[208:209], v[208:209]
	v_rcp_f32_e32 v144, v144
	v_rcp_f32_e32 v145, v145
	v_pk_mul_f32 v[248:249], v[110:111], v[134:135]
	v_pk_mul_f32 v[146:147], v[146:147], s[64:65] op_sel_hi:[1,0]
	v_pk_fma_f32 v[134:135], v[144:145], s[54:55], v[246:247] op_sel_hi:[1,0,0]
	v_exp_f32_e32 v146, v146
	v_pk_fma_f32 v[134:135], v[144:145], v[134:135], s[58:59] op_sel_hi:[1,1,0]
	v_exp_f32_e32 v147, v147
	v_pk_fma_f32 v[134:135], v[144:145], v[134:135], s[60:61] op_sel_hi:[1,1,0]
	v_pk_mul_f32 v[248:249], v[182:183], v[248:249] op_sel_hi:[0,1]
	v_pk_fma_f32 v[134:135], v[144:145], v[134:135], s[62:63] op_sel_hi:[1,1,0]
	v_pk_mul_f32 v[134:135], v[144:145], v[134:135]
	v_max_f32_e32 v144, 0, v208
	v_max_f32_e32 v145, 0, v209
	v_pk_mul_f32 v[134:135], v[146:147], v[134:135]
	v_cvt_pk_bf16_f32 v129, v248, v249
	v_pk_mul_f32 v[146:147], v[150:151], v[150:151]
	v_pk_fma_f32 v[134:135], v[142:143], v[134:135], v[144:145] neg_lo:[1,0,0] neg_hi:[1,0,0]
	v_and_b32_e32 v143, 0x7fffffff, v151
	v_and_b32_e32 v142, 0x7fffffff, v150
	v_pk_fma_f32 v[144:145], v[142:143], s[52:53], 1.0 op_sel_hi:[1,0,0]
	v_rcp_f32_e32 v144, v144
	v_rcp_f32_e32 v145, v145
	v_pk_mul_f32 v[134:135], v[106:107], v[134:135]
	v_pk_mul_f32 v[134:135], v[186:187], v[134:135] op_sel_hi:[0,1]
	v_cvt_pk_bf16_f32 v133, v134, v135
	v_pk_fma_f32 v[134:135], v[144:145], s[54:55], v[246:247] op_sel_hi:[1,0,0]
	v_pk_mul_f32 v[146:147], v[146:147], s[64:65] op_sel_hi:[1,0]
	v_pk_fma_f32 v[134:135], v[144:145], v[134:135], s[58:59] op_sel_hi:[1,1,0]
	v_exp_f32_e32 v146, v146
	v_exp_f32_e32 v147, v147
	v_pk_fma_f32 v[134:135], v[144:145], v[134:135], s[60:61] op_sel_hi:[1,1,0]
	v_add_u32_e32 v208, 16, v206
	v_pk_fma_f32 v[134:135], v[144:145], v[134:135], s[62:63] op_sel_hi:[1,1,0]
	s_nop 0
	v_pk_mul_f32 v[134:135], v[144:145], v[134:135]
	v_max_f32_e32 v144, 0, v150
	v_max_f32_e32 v145, 0, v151
	v_pk_mul_f32 v[134:135], v[146:147], v[134:135]
	s_nop 0
	v_pk_fma_f32 v[134:135], v[142:143], v[134:135], v[144:145] neg_lo:[1,0,0] neg_hi:[1,0,0]
	v_and_b32_e32 v143, 0x7fffffff, v131
	v_and_b32_e32 v142, 0x7fffffff, v130
	v_pk_fma_f32 v[144:145], v[142:143], s[52:53], 1.0 op_sel_hi:[1,0,0]
	v_rcp_f32_e32 v144, v144
	v_rcp_f32_e32 v145, v145
	v_pk_mul_f32 v[134:135], v[102:103], v[134:135]
	v_pk_mul_f32 v[134:135], v[184:185], v[134:135] op_sel_hi:[0,1]
	v_cvt_pk_bf16_f32 v137, v134, v135
	v_pk_fma_f32 v[134:135], v[144:145], s[54:55], v[246:247] op_sel_hi:[1,0,0]
	v_pk_mul_f32 v[138:139], v[130:131], v[130:131]
	v_pk_fma_f32 v[134:135], v[144:145], v[134:135], s[58:59] op_sel_hi:[1,1,0]
	v_pk_mul_f32 v[138:139], v[138:139], s[64:65] op_sel_hi:[1,0]
	v_pk_fma_f32 v[134:135], v[144:145], v[134:135], s[60:61] op_sel_hi:[1,1,0]
	v_exp_f32_e32 v138, v138
	v_exp_f32_e32 v139, v139
	v_pk_fma_f32 v[134:135], v[144:145], v[134:135], s[62:63] op_sel_hi:[1,1,0]
	v_max_f32_e32 v130, 0, v130
	v_pk_mul_f32 v[134:135], v[144:145], v[134:135]
	v_max_f32_e32 v131, 0, v131
	v_pk_mul_f32 v[134:135], v[138:139], v[134:135]
	s_nop 0
	v_pk_fma_f32 v[130:131], v[142:143], v[134:135], v[130:131] neg_lo:[1,0,0] neg_hi:[1,0,0]
	v_mov_b32_e32 v134, 0
	v_pk_mul_f32 v[130:131], v[98:99], v[130:131]
	v_pk_mul_f32 v[130:131], v[180:181], v[130:131] op_sel_hi:[0,1]
	v_cvt_pk_bf16_f32 v141, v130, v131
	ds_read2st64_b64 v[146:149], v208 offset0:10 offset1:11
	ds_read2st64_b64 v[142:145], v208 offset0:12 offset1:13
	v_mov_b32_e32 v130, 0
	v_mov_b32_e32 v135, 0
	s_cbranch_vccnz .LBB0_673
	v_lshl_add_u32 v131, v204, 2, s90
	ds_read_b64 v[134:135], v131 offset:1552

.LBB0_675:
	v_pk_mul_f32 v[220:221], v[80:81], v[182:183]
	v_pk_mul_f32 v[214:215], v[88:89], v[186:187]
	v_pk_mul_f32 v[188:189], v[92:93], v[184:185]
	s_waitcnt lgkmcnt(0)
	v_mov_b32_dpp v134, v220 row_shr:1 row_mask:0xf bank_mask:0xf
	v_mov_b32_dpp v135, v221 row_shr:1 row_mask:0xf bank_mask:0xf
	v_mov_b32_dpp v218, v214 row_ror:15 row_mask:0xf bank_mask:0xf
	v_mov_b32_dpp v219, v215 row_ror:15 row_mask:0xf bank_mask:0xf
	v_mov_b32_dpp v222, v220 row_ror:1 row_mask:0xf bank_mask:0xf
	v_mov_b32_dpp v223, v221 row_ror:1 row_mask:0xf bank_mask:0xf
	v_pk_mul_f32 v[134:135], v[146:147], v[134:135]
	v_pk_mul_f32 v[138:139], v[84:85], v[180:181]
	v_mov_b32_dpp v190, v188 row_ror:1 row_mask:0xf bank_mask:0xf
	v_mov_b32_dpp v191, v189 row_ror:1 row_mask:0xf bank_mask:0xf
	v_mov_b32_dpp v216, v214 row_ror:1 row_mask:0xf bank_mask:0xf
	v_mov_b32_dpp v217, v215 row_ror:1 row_mask:0xf bank_mask:0xf
	v_pk_fma_f32 v[134:135], v[220:221], v[148:149], v[134:135]
	v_mov_b32_dpp v222, v214 row_shr:1 row_mask:0xf bank_mask:0xf
	v_mov_b32_dpp v218, v220 row_shl:1 row_mask:0xf bank_mask:0xf
	v_mov_b32_dpp v223, v215 row_shr:1 row_mask:0xf bank_mask:0xf
	v_mov_b32_dpp v219, v221 row_shl:1 row_mask:0xf bank_mask:0xf
	v_mov_b32_dpp v210, v188 row_ror:15 row_mask:0xf bank_mask:0xf
	v_mov_b32_dpp v211, v189 row_ror:15 row_mask:0xf bank_mask:0xf
	v_pk_fma_f32 v[134:135], v[142:143], v[218:219], v[134:135]
	v_pk_mul_f32 v[218:219], v[146:147], v[222:223]
	v_mov_b32_dpp v216, v188 row_shr:1 row_mask:0xf bank_mask:0xf
	v_mov_b32_dpp v217, v189 row_shr:1 row_mask:0xf bank_mask:0xf
	v_mov_b32_dpp v190, v138 row_shr:1 row_mask:0xf bank_mask:0xf
	v_mov_b32_dpp v191, v139 row_shr:1 row_mask:0xf bank_mask:0xf
	v_pk_add_f32 v[134:135], v[144:145], v[134:135]
	v_pk_fma_f32 v[218:219], v[214:215], v[148:149], v[218:219]
	v_mov_b32_dpp v210, v214 row_shl:1 row_mask:0xf bank_mask:0xf
	v_mov_b32_dpp v211, v215 row_shl:1 row_mask:0xf bank_mask:0xf
	v_pk_mul_f32 v[214:215], v[146:147], v[216:217]
	v_pk_mul_f32 v[146:147], v[146:147], v[190:191]
	v_mov_b32_dpp v150, v138 row_ror:15 row_mask:0xf bank_mask:0xf
	v_mov_b32_dpp v130, v138 row_shl:1 row_mask:0xf bank_mask:0xf
	v_mov_b32_dpp v151, v139 row_ror:15 row_mask:0xf bank_mask:0xf
	v_mov_b32_dpp v131, v139 row_shl:1 row_mask:0xf bank_mask:0xf
	v_pk_fma_f32 v[138:139], v[138:139], v[148:149], v[146:147]
	v_and_b32_e32 v147, 0x7fffffff, v135
	v_and_b32_e32 v146, 0x7fffffff, v134
	v_pk_fma_f32 v[214:215], v[188:189], v[148:149], v[214:215]
	v_pk_fma_f32 v[148:149], v[146:147], s[52:53], 1.0 op_sel_hi:[1,0,0]
	v_mov_b32_dpp v150, v188 row_shl:1 row_mask:0xf bank_mask:0xf
	v_rcp_f32_e32 v148, v148
	v_rcp_f32_e32 v149, v149
	v_mov_b32_dpp v151, v189 row_shl:1 row_mask:0xf bank_mask:0xf
	v_pk_fma_f32 v[210:211], v[142:143], v[210:211], v[218:219]
	v_pk_fma_f32 v[150:151], v[142:143], v[150:151], v[214:215]
	v_pk_fma_f32 v[130:131], v[142:143], v[130:131], v[138:139]
	v_pk_add_f32 v[210:211], v[144:145], v[210:211]
	v_pk_add_f32 v[150:151], v[144:145], v[150:151]
	v_pk_add_f32 v[142:143], v[144:145], v[130:131]
	v_pk_mul_f32 v[138:139], v[134:135], v[134:135]
	v_pk_fma_f32 v[130:131], v[148:149], s[54:55], v[246:247] op_sel_hi:[1,0,0]
	v_pk_mul_f32 v[138:139], v[138:139], s[64:65] op_sel_hi:[1,0]
	v_pk_fma_f32 v[130:131], v[148:149], v[130:131], s[58:59] op_sel_hi:[1,1,0]
	v_exp_f32_e32 v138, v138
	v_exp_f32_e32 v139, v139
	v_pk_fma_f32 v[130:131], v[148:149], v[130:131], s[60:61] op_sel_hi:[1,1,0]
	v_max_f32_e32 v134, 0, v134
	v_pk_fma_f32 v[130:131], v[148:149], v[130:131], s[62:63] op_sel_hi:[1,1,0]
	v_max_f32_e32 v135, 0, v135
	v_pk_mul_f32 v[130:131], v[148:149], v[130:131]
	v_pk_mul_f32 v[148:149], v[210:211], v[210:211]
	v_pk_mul_f32 v[130:131], v[138:139], v[130:131]
	v_pk_mul_f32 v[148:149], v[148:149], s[64:65] op_sel_hi:[1,0]
	v_pk_fma_f32 v[130:131], v[146:147], v[130:131], v[134:135] neg_lo:[1,0,0] neg_hi:[1,0,0]
	v_and_b32_e32 v135, 0x7fffffff, v211
	v_and_b32_e32 v134, 0x7fffffff, v210
	v_pk_fma_f32 v[138:139], v[134:135], s[52:53], 1.0 op_sel_hi:[1,0,0]
	v_exp_f32_e32 v148, v148
	v_rcp_f32_e32 v138, v138
	v_rcp_f32_e32 v139, v139
	v_exp_f32_e32 v149, v149
	v_pk_mul_f32 v[188:189], v[150:151], v[150:151]
	v_pk_fma_f32 v[146:147], v[138:139], s[54:55], v[246:247] op_sel_hi:[1,0,0]
	v_pk_mul_f32 v[188:189], v[188:189], s[64:65] op_sel_hi:[1,0]
	v_pk_fma_f32 v[146:147], v[138:139], v[146:147], s[58:59] op_sel_hi:[1,1,0]
	v_exp_f32_e32 v188, v188
	v_pk_fma_f32 v[146:147], v[138:139], v[146:147], s[60:61] op_sel_hi:[1,1,0]
	v_exp_f32_e32 v189, v189
	v_pk_fma_f32 v[146:147], v[138:139], v[146:147], s[62:63] op_sel_hi:[1,1,0]
	v_pk_mul_f32 v[130:131], v[76:77], v[130:131]
	v_pk_mul_f32 v[138:139], v[138:139], v[146:147]
	v_max_f32_e32 v146, 0, v210
	v_max_f32_e32 v147, 0, v211
	v_pk_mul_f32 v[138:139], v[148:149], v[138:139]
	v_pk_fma_f32 v[134:135], v[134:135], v[138:139], v[146:147] neg_lo:[1,0,0] neg_hi:[1,0,0]
	v_and_b32_e32 v139, 0x7fffffff, v151
	v_and_b32_e32 v138, 0x7fffffff, v150
	v_pk_fma_f32 v[146:147], v[138:139], s[52:53], 1.0 op_sel_hi:[1,0,0]
	v_pk_mul_f32 v[130:131], v[182:183], v[130:131] op_sel_hi:[0,1]
	v_rcp_f32_e32 v146, v146
	v_rcp_f32_e32 v147, v147
	v_cvt_pk_bf16_f32 v130, v130, v131
	v_pk_mul_f32 v[134:135], v[72:73], v[134:135]
	v_pk_fma_f32 v[148:149], v[146:147], s[54:55], v[246:247] op_sel_hi:[1,0,0]
	v_pk_fma_f32 v[148:149], v[146:147], v[148:149], s[58:59] op_sel_hi:[1,1,0]
	v_pk_mul_f32 v[134:135], v[186:187], v[134:135] op_sel_hi:[0,1]
	v_pk_fma_f32 v[148:149], v[146:147], v[148:149], s[60:61] op_sel_hi:[1,1,0]
	v_cvt_pk_bf16_f32 v134, v134, v135
	v_add_u32_e32 v209, 24, v206
	v_pk_fma_f32 v[148:149], v[146:147], v[148:149], s[62:63] op_sel_hi:[1,1,0]
	s_and_b64 vcc, exec, s[6:7]
	v_pk_mul_f32 v[146:147], v[146:147], v[148:149]
	v_max_f32_e32 v148, 0, v150
	v_max_f32_e32 v149, 0, v151
	v_pk_mul_f32 v[146:147], v[188:189], v[146:147]
	v_pk_mul_f32 v[150:151], v[142:143], v[142:143]
	v_pk_fma_f32 v[138:139], v[138:139], v[146:147], v[148:149] neg_lo:[1,0,0] neg_hi:[1,0,0]
	v_and_b32_e32 v147, 0x7fffffff, v143
	v_and_b32_e32 v146, 0x7fffffff, v142
	v_pk_fma_f32 v[148:149], v[146:147], s[52:53], 1.0 op_sel_hi:[1,0,0]
	v_pk_mul_f32 v[150:151], v[150:151], s[64:65] op_sel_hi:[1,0]
	v_rcp_f32_e32 v148, v148
	v_rcp_f32_e32 v149, v149
	v_exp_f32_e32 v150, v150
	v_exp_f32_e32 v151, v151
	v_pk_fma_f32 v[144:145], v[148:149], s[54:55], v[246:247] op_sel_hi:[1,0,0]
	v_pk_mul_f32 v[138:139], v[68:69], v[138:139]
	v_pk_fma_f32 v[144:145], v[148:149], v[144:145], s[58:59] op_sel_hi:[1,1,0]
	v_max_f32_e32 v142, 0, v142
	v_pk_fma_f32 v[144:145], v[148:149], v[144:145], s[60:61] op_sel_hi:[1,1,0]
	v_max_f32_e32 v143, 0, v143
	v_pk_fma_f32 v[144:145], v[148:149], v[144:145], s[62:63] op_sel_hi:[1,1,0]
	v_pk_mul_f32 v[144:145], v[148:149], v[144:145]
	v_pk_mul_f32 v[138:139], v[184:185], v[138:139] op_sel_hi:[0,1]
	v_pk_mul_f32 v[144:145], v[150:151], v[144:145]
	v_cvt_pk_bf16_f32 v138, v138, v139
	v_mov_b32_e32 v188, 0
	v_pk_fma_f32 v[142:143], v[146:147], v[144:145], v[142:143] neg_lo:[1,0,0] neg_hi:[1,0,0]
	v_mov_b32_e32 v190, 0
	v_pk_mul_f32 v[142:143], v[64:65], v[142:143]
	v_pk_mul_f32 v[142:143], v[180:181], v[142:143] op_sel_hi:[0,1]
	v_cvt_pk_bf16_f32 v142, v142, v143
	ds_read2st64_b64 v[148:151], v209 offset0:10 offset1:11
	ds_read2st64_b64 v[144:147], v209 offset0:12 offset1:13
	v_mov_b32_e32 v191, 0
	s_cbranch_vccnz .LBB0_677
	v_lshl_add_u32 v131, v204, 2, s90
	ds_read_b64 v[190:191], v131 offset:1560

.LBB0_679:
	v_pk_mul_f32 v[228:229], v[82:83], v[182:183]
	v_pk_mul_f32 v[222:223], v[90:91], v[186:187]
	v_pk_mul_f32 v[216:217], v[94:95], v[184:185]
	s_waitcnt lgkmcnt(0)
	v_mov_b32_dpp v190, v228 row_shr:1 row_mask:0xf bank_mask:0xf
	v_mov_b32_dpp v191, v229 row_shr:1 row_mask:0xf bank_mask:0xf
	v_mov_b32_dpp v226, v222 row_ror:15 row_mask:0xf bank_mask:0xf
	v_mov_b32_dpp v227, v223 row_ror:15 row_mask:0xf bank_mask:0xf
	v_mov_b32_dpp v230, v228 row_ror:1 row_mask:0xf bank_mask:0xf
	v_mov_b32_dpp v231, v229 row_ror:1 row_mask:0xf bank_mask:0xf
	v_pk_mul_f32 v[190:191], v[148:149], v[190:191]
	v_pk_mul_f32 v[210:211], v[86:87], v[180:181]
	v_mov_b32_dpp v218, v216 row_ror:1 row_mask:0xf bank_mask:0xf
	v_mov_b32_dpp v219, v217 row_ror:1 row_mask:0xf bank_mask:0xf
	v_mov_b32_dpp v224, v222 row_ror:1 row_mask:0xf bank_mask:0xf
	v_mov_b32_dpp v225, v223 row_ror:1 row_mask:0xf bank_mask:0xf
	v_pk_fma_f32 v[190:191], v[228:229], v[150:151], v[190:191]
	v_mov_b32_dpp v230, v222 row_shr:1 row_mask:0xf bank_mask:0xf
	v_mov_b32_dpp v226, v228 row_shl:1 row_mask:0xf bank_mask:0xf
	v_mov_b32_dpp v231, v223 row_shr:1 row_mask:0xf bank_mask:0xf
	v_mov_b32_dpp v227, v229 row_shl:1 row_mask:0xf bank_mask:0xf
	v_mov_b32_dpp v220, v216 row_ror:15 row_mask:0xf bank_mask:0xf
	v_mov_b32_dpp v221, v217 row_ror:15 row_mask:0xf bank_mask:0xf
	v_pk_fma_f32 v[190:191], v[144:145], v[226:227], v[190:191]
	v_pk_mul_f32 v[226:227], v[148:149], v[230:231]
	v_mov_b32_dpp v224, v216 row_shr:1 row_mask:0xf bank_mask:0xf
	v_mov_b32_dpp v225, v217 row_shr:1 row_mask:0xf bank_mask:0xf
	v_mov_b32_dpp v218, v210 row_shr:1 row_mask:0xf bank_mask:0xf
	v_mov_b32_dpp v219, v211 row_shr:1 row_mask:0xf bank_mask:0xf
	v_pk_add_f32 v[190:191], v[146:147], v[190:191]
	v_pk_fma_f32 v[226:227], v[222:223], v[150:151], v[226:227]
	v_mov_b32_dpp v220, v222 row_shl:1 row_mask:0xf bank_mask:0xf
	v_mov_b32_dpp v221, v223 row_shl:1 row_mask:0xf bank_mask:0xf
	v_pk_mul_f32 v[222:223], v[148:149], v[224:225]
	v_pk_mul_f32 v[148:149], v[148:149], v[218:219]
	v_pk_fma_f32 v[222:223], v[216:217], v[150:151], v[222:223]
	v_pk_fma_f32 v[148:149], v[210:211], v[150:151], v[148:149]
	v_and_b32_e32 v151, 0x7fffffff, v191
	v_and_b32_e32 v150, 0x7fffffff, v190
	v_mov_b32_dpp v214, v210 row_ror:15 row_mask:0xf bank_mask:0xf
	v_mov_b32_dpp v188, v210 row_shl:1 row_mask:0xf bank_mask:0xf
	v_mov_b32_dpp v215, v211 row_ror:15 row_mask:0xf bank_mask:0xf
	v_mov_b32_dpp v189, v211 row_shl:1 row_mask:0xf bank_mask:0xf
	v_pk_fma_f32 v[210:211], v[150:151], s[52:53], 1.0 op_sel_hi:[1,0,0]
	v_mov_b32_dpp v214, v216 row_shl:1 row_mask:0xf bank_mask:0xf
	v_rcp_f32_e32 v210, v210
	v_rcp_f32_e32 v211, v211
	v_mov_b32_dpp v215, v217 row_shl:1 row_mask:0xf bank_mask:0xf
	v_pk_fma_f32 v[220:221], v[144:145], v[220:221], v[226:227]
	v_pk_fma_f32 v[214:215], v[144:145], v[214:215], v[222:223]
	v_pk_fma_f32 v[144:145], v[144:145], v[188:189], v[148:149]
	v_pk_add_f32 v[220:221], v[146:147], v[220:221]
	v_pk_add_f32 v[214:215], v[146:147], v[214:215]
	v_pk_add_f32 v[144:145], v[146:147], v[144:145]
	v_pk_mul_f32 v[188:189], v[190:191], v[190:191]
	v_pk_fma_f32 v[148:149], v[210:211], s[54:55], v[246:247] op_sel_hi:[1,0,0]
	v_pk_mul_f32 v[188:189], v[188:189], s[64:65] op_sel_hi:[1,0]
	v_pk_fma_f32 v[148:149], v[210:211], v[148:149], s[58:59] op_sel_hi:[1,1,0]
	v_exp_f32_e32 v188, v188
	v_exp_f32_e32 v189, v189
	v_pk_fma_f32 v[148:149], v[210:211], v[148:149], s[60:61] op_sel_hi:[1,1,0]
	v_max_f32_e32 v190, 0, v190
	v_pk_fma_f32 v[148:149], v[210:211], v[148:149], s[62:63] op_sel_hi:[1,1,0]
	v_max_f32_e32 v191, 0, v191
	v_pk_mul_f32 v[148:149], v[210:211], v[148:149]
	v_cmp_gt_i32_e64 s[8:9], s78, v203
	v_pk_mul_f32 v[148:149], v[188:189], v[148:149]
	v_ashrrev_i32_e32 v175, 31, v174
	v_pk_fma_f32 v[148:149], v[150:151], v[148:149], v[190:191] neg_lo:[1,0,0] neg_hi:[1,0,0]
	v_and_b32_e32 v151, 0x7fffffff, v221
	v_and_b32_e32 v150, 0x7fffffff, v220
	v_pk_fma_f32 v[188:189], v[150:151], s[52:53], 1.0 op_sel_hi:[1,0,0]
	v_pk_mul_f32 v[190:191], v[220:221], v[220:221]
	v_rcp_f32_e32 v188, v188
	v_rcp_f32_e32 v189, v189
	v_pk_mul_f32 v[248:249], v[78:79], v[148:149]
	v_pk_mul_f32 v[190:191], v[190:191], s[64:65] op_sel_hi:[1,0]
	v_pk_fma_f32 v[148:149], v[188:189], s[54:55], v[246:247] op_sel_hi:[1,0,0]
	v_exp_f32_e32 v190, v190
	v_pk_fma_f32 v[148:149], v[188:189], v[148:149], s[58:59] op_sel_hi:[1,1,0]
	v_exp_f32_e32 v191, v191
	v_pk_fma_f32 v[148:149], v[188:189], v[148:149], s[60:61] op_sel_hi:[1,1,0]
	v_pk_mul_f32 v[248:249], v[182:183], v[248:249] op_sel_hi:[0,1]
	v_pk_fma_f32 v[148:149], v[188:189], v[148:149], s[62:63] op_sel_hi:[1,1,0]
	v_pk_mul_f32 v[148:149], v[188:189], v[148:149]
	v_max_f32_e32 v188, 0, v220
	v_max_f32_e32 v189, 0, v221
	v_pk_mul_f32 v[148:149], v[190:191], v[148:149]
	v_pk_mul_f32 v[190:191], v[214:215], v[214:215]
	v_pk_fma_f32 v[148:149], v[150:151], v[148:149], v[188:189] neg_lo:[1,0,0] neg_hi:[1,0,0]
	v_and_b32_e32 v151, 0x7fffffff, v215
	v_and_b32_e32 v150, 0x7fffffff, v214
	v_pk_fma_f32 v[188:189], v[150:151], s[52:53], 1.0 op_sel_hi:[1,0,0]
	v_cvt_pk_bf16_f32 v131, v248, v249
	v_pk_mul_f32 v[248:249], v[74:75], v[148:149]
	v_rcp_f32_e32 v188, v188
	v_rcp_f32_e32 v189, v189
	v_pk_mul_f32 v[190:191], v[190:191], s[64:65] op_sel_hi:[1,0]
	v_pk_mul_f32 v[248:249], v[186:187], v[248:249] op_sel_hi:[0,1]
	v_pk_fma_f32 v[148:149], v[188:189], s[54:55], v[246:247] op_sel_hi:[1,0,0]
	v_exp_f32_e32 v190, v190
	v_pk_fma_f32 v[148:149], v[188:189], v[148:149], s[58:59] op_sel_hi:[1,1,0]
	v_exp_f32_e32 v191, v191
	v_pk_fma_f32 v[148:149], v[188:189], v[148:149], s[60:61] op_sel_hi:[1,1,0]
	v_pk_fma_f32 v[148:149], v[188:189], v[148:149], s[62:63] op_sel_hi:[1,1,0]
	v_cvt_pk_bf16_f32 v135, v248, v249
	s_nop 0
	v_pk_mul_f32 v[148:149], v[188:189], v[148:149]
	v_max_f32_e32 v188, 0, v214
	v_max_f32_e32 v189, 0, v215
	v_pk_mul_f32 v[148:149], v[190:191], v[148:149]
	s_nop 0
	v_pk_fma_f32 v[148:149], v[150:151], v[148:149], v[188:189] neg_lo:[1,0,0] neg_hi:[1,0,0]
	v_and_b32_e32 v151, 0x7fffffff, v145
	v_and_b32_e32 v150, 0x7fffffff, v144
	v_pk_fma_f32 v[188:189], v[150:151], s[52:53], 1.0 op_sel_hi:[1,0,0]
	v_pk_mul_f32 v[248:249], v[70:71], v[148:149]
	v_rcp_f32_e32 v188, v188
	v_rcp_f32_e32 v189, v189
	v_pk_mul_f32 v[148:149], v[144:145], v[144:145]
	v_max_f32_e32 v144, 0, v144
	v_pk_fma_f32 v[146:147], v[188:189], s[54:55], v[246:247] op_sel_hi:[1,0,0]
	v_pk_mul_f32 v[148:149], v[148:149], s[64:65] op_sel_hi:[1,0]
	v_pk_fma_f32 v[146:147], v[188:189], v[146:147], s[58:59] op_sel_hi:[1,1,0]
	v_exp_f32_e32 v148, v148
	v_exp_f32_e32 v149, v149
	v_pk_fma_f32 v[146:147], v[188:189], v[146:147], s[60:61] op_sel_hi:[1,1,0]
	v_max_f32_e32 v145, 0, v145
	v_pk_fma_f32 v[146:147], v[188:189], v[146:147], s[62:63] op_sel_hi:[1,1,0]
	v_pk_mul_f32 v[248:249], v[184:185], v[248:249] op_sel_hi:[0,1]
	v_pk_mul_f32 v[146:147], v[188:189], v[146:147]
	v_pk_mul_f32 v[146:147], v[148:149], v[146:147]
	v_cvt_pk_bf16_f32 v139, v248, v249
	s_nop 0
	v_pk_fma_f32 v[144:145], v[150:151], v[146:147], v[144:145] neg_lo:[1,0,0] neg_hi:[1,0,0]
	s_nop 0
	v_pk_mul_f32 v[144:145], v[66:67], v[144:145]
	v_pk_mul_f32 v[144:145], v[180:181], v[144:145] op_sel_hi:[0,1]
	v_cvt_pk_bf16_f32 v143, v144, v145
	v_add_u32_e32 v144, -1, v202
	v_cmp_gt_u32_e32 vcc, s76, v144
	s_and_b64 s[10:11], vcc, s[8:9]
	s_and_saveexec_b64 s[8:9], s[10:11]
	s_cbranch_execz .LBB0_681
	v_mov_b64_e32 v[144:145], s[38:39]
	v_mad_i64_i32 v[144:145], s[10:11], v203, s31, v[144:145]
	v_lshl_add_u64 v[144:145], v[174:175], 1, v[144:145]
	global_store_dwordx4 v[144:145], v[128:131], off

.LBB0_691:
	v_pk_mul_f32 v[210:211], v[48:49], v[172:173] op_sel_hi:[1,0]
	v_pk_mul_f32 v[150:151], v[52:53], v[178:179] op_sel_hi:[1,0]
	v_pk_mul_f32 v[144:145], v[60:61], v[176:177] op_sel_hi:[1,0]
	s_waitcnt lgkmcnt(0)
	v_mov_b32_dpp v138, v210 row_shr:1 row_mask:0xf bank_mask:0xf
	v_mov_b32_dpp v139, v211 row_shr:1 row_mask:0xf bank_mask:0xf
	v_mov_b32_dpp v190, v150 row_ror:15 row_mask:0xf bank_mask:0xf
	v_mov_b32_dpp v191, v151 row_ror:15 row_mask:0xf bank_mask:0xf
	v_mov_b32_dpp v214, v210 row_ror:1 row_mask:0xf bank_mask:0xf
	v_mov_b32_dpp v215, v211 row_ror:1 row_mask:0xf bank_mask:0xf
	v_pk_mul_f32 v[138:139], v[134:135], v[138:139]
	v_pk_mul_f32 v[140:141], v[56:57], v[170:171] op_sel_hi:[1,0]
	v_mov_b32_dpp v146, v144 row_ror:1 row_mask:0xf bank_mask:0xf
	v_mov_b32_dpp v147, v145 row_ror:1 row_mask:0xf bank_mask:0xf
	v_mov_b32_dpp v188, v150 row_ror:1 row_mask:0xf bank_mask:0xf
	v_mov_b32_dpp v189, v151 row_ror:1 row_mask:0xf bank_mask:0xf
	v_pk_fma_f32 v[138:139], v[210:211], v[136:137], v[138:139]
	v_mov_b32_dpp v214, v150 row_shr:1 row_mask:0xf bank_mask:0xf
	v_mov_b32_dpp v190, v210 row_shl:1 row_mask:0xf bank_mask:0xf
	v_mov_b32_dpp v215, v151 row_shr:1 row_mask:0xf bank_mask:0xf
	v_mov_b32_dpp v191, v211 row_shl:1 row_mask:0xf bank_mask:0xf
	v_mov_b32_dpp v148, v144 row_ror:15 row_mask:0xf bank_mask:0xf
	v_mov_b32_dpp v149, v145 row_ror:15 row_mask:0xf bank_mask:0xf
	v_pk_fma_f32 v[138:139], v[128:129], v[190:191], v[138:139]
	v_pk_mul_f32 v[190:191], v[134:135], v[214:215]
	v_mov_b32_dpp v188, v144 row_shr:1 row_mask:0xf bank_mask:0xf
	v_mov_b32_dpp v189, v145 row_shr:1 row_mask:0xf bank_mask:0xf
	v_mov_b32_dpp v146, v140 row_shr:1 row_mask:0xf bank_mask:0xf
	v_mov_b32_dpp v147, v141 row_shr:1 row_mask:0xf bank_mask:0xf
	v_pk_add_f32 v[138:139], v[130:131], v[138:139]
	v_pk_fma_f32 v[190:191], v[150:151], v[136:137], v[190:191]
	v_mov_b32_dpp v148, v150 row_shl:1 row_mask:0xf bank_mask:0xf
	v_mov_b32_dpp v149, v151 row_shl:1 row_mask:0xf bank_mask:0xf
	v_pk_mul_f32 v[150:151], v[134:135], v[188:189]
	v_pk_mul_f32 v[134:135], v[134:135], v[146:147]
	v_pk_fma_f32 v[150:151], v[144:145], v[136:137], v[150:151]
	v_pk_fma_f32 v[134:135], v[140:141], v[136:137], v[134:135]
	v_and_b32_e32 v137, 0x7fffffff, v139
	v_and_b32_e32 v136, 0x7fffffff, v138
	v_mov_b32_dpp v142, v140 row_ror:15 row_mask:0xf bank_mask:0xf
	v_mov_b32_dpp v132, v140 row_shl:1 row_mask:0xf bank_mask:0xf
	v_mov_b32_dpp v143, v141 row_ror:15 row_mask:0xf bank_mask:0xf
	v_mov_b32_dpp v133, v141 row_shl:1 row_mask:0xf bank_mask:0xf
	v_pk_fma_f32 v[140:141], v[136:137], s[52:53], 1.0 op_sel_hi:[1,0,0]
	v_mov_b32_dpp v142, v144 row_shl:1 row_mask:0xf bank_mask:0xf
	v_rcp_f32_e32 v140, v140
	v_rcp_f32_e32 v141, v141
	v_mov_b32_dpp v143, v145 row_shl:1 row_mask:0xf bank_mask:0xf
	v_pk_fma_f32 v[148:149], v[128:129], v[148:149], v[190:191]
	v_pk_fma_f32 v[142:143], v[128:129], v[142:143], v[150:151]
	v_pk_fma_f32 v[128:129], v[128:129], v[132:133], v[134:135]
	v_pk_add_f32 v[148:149], v[130:131], v[148:149]
	v_pk_add_f32 v[142:143], v[130:131], v[142:143]
	v_pk_add_f32 v[128:129], v[130:131], v[128:129]
	v_pk_mul_f32 v[134:135], v[138:139], v[138:139]
	v_pk_fma_f32 v[132:133], v[140:141], s[54:55], v[246:247] op_sel_hi:[1,0,0]
	v_pk_mul_f32 v[134:135], v[134:135], s[64:65] op_sel_hi:[1,0]
	v_pk_fma_f32 v[132:133], v[140:141], v[132:133], s[58:59] op_sel_hi:[1,1,0]
	v_exp_f32_e32 v134, v134
	v_exp_f32_e32 v135, v135
	v_pk_fma_f32 v[132:133], v[140:141], v[132:133], s[60:61] op_sel_hi:[1,1,0]
	v_max_f32_e32 v138, 0, v138
	v_pk_fma_f32 v[132:133], v[140:141], v[132:133], s[62:63] op_sel_hi:[1,1,0]
	v_max_f32_e32 v139, 0, v139
	v_pk_mul_f32 v[132:133], v[140:141], v[132:133]
	v_pk_mul_f32 v[140:141], v[148:149], v[148:149]
	v_pk_mul_f32 v[132:133], v[134:135], v[132:133]
	v_and_b32_e32 v135, 0x7fffffff, v149
	v_and_b32_e32 v134, 0x7fffffff, v148
	v_pk_fma_f32 v[132:133], v[136:137], v[132:133], v[138:139] neg_lo:[1,0,0] neg_hi:[1,0,0]
	v_pk_fma_f32 v[136:137], v[134:135], s[52:53], 1.0 op_sel_hi:[1,0,0]
	v_pk_mul_f32 v[140:141], v[140:141], s[64:65] op_sel_hi:[1,0]
	v_rcp_f32_e32 v136, v136
	v_rcp_f32_e32 v137, v137
	v_exp_f32_e32 v140, v140
	v_exp_f32_e32 v141, v141
	v_pk_fma_f32 v[138:139], v[136:137], s[54:55], v[246:247] op_sel_hi:[1,0,0]
	v_pk_mul_f32 v[132:133], v[44:45], v[132:133]
	v_pk_fma_f32 v[138:139], v[136:137], v[138:139], s[58:59] op_sel_hi:[1,1,0]
	v_pk_fma_f32 v[138:139], v[136:137], v[138:139], s[60:61] op_sel_hi:[1,1,0]
	v_pk_mul_f32 v[132:133], v[172:173], v[132:133] op_sel_hi:[0,1]
	v_pk_fma_f32 v[138:139], v[136:137], v[138:139], s[62:63] op_sel_hi:[1,1,0]
	v_cvt_pk_bf16_f32 v132, v132, v133
	v_pk_mul_f32 v[144:145], v[142:143], v[142:143]
	v_pk_mul_f32 v[136:137], v[136:137], v[138:139]
	v_max_f32_e32 v138, 0, v148
	v_max_f32_e32 v139, 0, v149
	v_pk_mul_f32 v[136:137], v[140:141], v[136:137]
	v_pk_mul_f32 v[144:145], v[144:145], s[64:65] op_sel_hi:[1,0]
	v_pk_fma_f32 v[134:135], v[134:135], v[136:137], v[138:139] neg_lo:[1,0,0] neg_hi:[1,0,0]
	v_and_b32_e32 v139, 0x7fffffff, v143
	v_and_b32_e32 v138, 0x7fffffff, v142
	v_pk_fma_f32 v[136:137], v[138:139], s[52:53], 1.0 op_sel_hi:[1,0,0]
	v_rcp_f32_e32 v140, v136
	v_rcp_f32_e32 v141, v137
	v_pk_mul_f32 v[134:135], v[40:41], v[134:135]
	v_pk_mul_f32 v[134:135], v[178:179], v[134:135] op_sel_hi:[0,1]
	v_cvt_pk_bf16_f32 v136, v134, v135
	v_pk_fma_f32 v[134:135], v[140:141], s[54:55], v[246:247] op_sel_hi:[1,0,0]
	v_exp_f32_e32 v144, v144
	v_pk_fma_f32 v[134:135], v[140:141], v[134:135], s[58:59] op_sel_hi:[1,1,0]
	v_exp_f32_e32 v145, v145
	v_pk_fma_f32 v[134:135], v[140:141], v[134:135], s[60:61] op_sel_hi:[1,1,0]
	s_and_b64 vcc, exec, s[8:9]
	v_pk_fma_f32 v[134:135], v[140:141], v[134:135], s[62:63] op_sel_hi:[1,1,0]
	s_nop 0
	v_pk_mul_f32 v[134:135], v[140:141], v[134:135]
	v_max_f32_e32 v140, 0, v142
	v_max_f32_e32 v141, 0, v143
	v_pk_mul_f32 v[134:135], v[144:145], v[134:135]
	s_nop 0
	v_pk_fma_f32 v[134:135], v[138:139], v[134:135], v[140:141] neg_lo:[1,0,0] neg_hi:[1,0,0]
	v_and_b32_e32 v139, 0x7fffffff, v129
	v_and_b32_e32 v138, 0x7fffffff, v128
	v_pk_fma_f32 v[140:141], v[138:139], s[52:53], 1.0 op_sel_hi:[1,0,0]
	v_rcp_f32_e32 v142, v140
	v_rcp_f32_e32 v143, v141
	v_pk_mul_f32 v[134:135], v[36:37], v[134:135]
	v_pk_mul_f32 v[134:135], v[176:177], v[134:135] op_sel_hi:[0,1]
	v_cvt_pk_bf16_f32 v140, v134, v135
	v_pk_mul_f32 v[134:135], v[128:129], v[128:129]
	v_pk_fma_f32 v[130:131], v[142:143], s[54:55], v[246:247] op_sel_hi:[1,0,0]
	v_pk_mul_f32 v[134:135], v[134:135], s[64:65] op_sel_hi:[1,0]
	v_pk_fma_f32 v[130:131], v[142:143], v[130:131], s[58:59] op_sel_hi:[1,1,0]
	v_exp_f32_e32 v134, v134
	v_exp_f32_e32 v135, v135
	v_pk_fma_f32 v[130:131], v[142:143], v[130:131], s[60:61] op_sel_hi:[1,1,0]
	v_max_f32_e32 v128, 0, v128
	v_pk_fma_f32 v[130:131], v[142:143], v[130:131], s[62:63] op_sel_hi:[1,1,0]
	v_max_f32_e32 v129, 0, v129
	v_pk_mul_f32 v[130:131], v[142:143], v[130:131]
	s_nop 0
	v_pk_mul_f32 v[130:131], v[134:135], v[130:131]
	v_mov_b32_e32 v134, 0
	v_pk_fma_f32 v[128:129], v[138:139], v[130:131], v[128:129] neg_lo:[1,0,0] neg_hi:[1,0,0]
	v_mov_b32_e32 v130, 0
	v_mul_f32_e32 v128, v32, v128
	v_mul_f32_e32 v128, v170, v128
	v_mul_f32_e32 v129, v33, v129
	v_mul_f32_e32 v129, v170, v129
	v_cvt_pk_bf16_f32 v128, v128, v129
	ds_read2st64_b64 v[146:149], v207 offset0:10 offset1:11
	ds_read2st64_b64 v[142:145], v207 offset0:12 offset1:13
	v_mov_b32_e32 v135, 0
	s_cbranch_vccnz .LBB0_693
	v_add_u32_e32 v129, s87, v206
	ds_read_b64 v[134:135], v129 offset:1544

.LBB0_695:
	v_mov_b32_e32 v173, v172
	v_mov_b32_e32 v179, v178
	v_pk_mul_f32 v[220:221], v[50:51], v[172:173]
	v_mov_b32_e32 v177, v176
	v_pk_mul_f32 v[214:215], v[54:55], v[178:179]
	s_waitcnt lgkmcnt(0)
	v_mov_b32_dpp v134, v220 row_shr:1 row_mask:0xf bank_mask:0xf
	v_mov_b32_dpp v135, v221 row_shr:1 row_mask:0xf bank_mask:0xf
	v_mov_b32_e32 v171, v170
	v_pk_mul_f32 v[188:189], v[62:63], v[176:177]
	v_mov_b32_dpp v218, v214 row_ror:15 row_mask:0xf bank_mask:0xf
	v_mov_b32_dpp v219, v215 row_ror:15 row_mask:0xf bank_mask:0xf
	v_mov_b32_dpp v222, v220 row_ror:1 row_mask:0xf bank_mask:0xf
	v_mov_b32_dpp v223, v221 row_ror:1 row_mask:0xf bank_mask:0xf
	v_pk_mul_f32 v[134:135], v[146:147], v[134:135]
	v_pk_mul_f32 v[138:139], v[58:59], v[170:171]
	v_mov_b32_dpp v190, v188 row_ror:1 row_mask:0xf bank_mask:0xf
	v_mov_b32_dpp v191, v189 row_ror:1 row_mask:0xf bank_mask:0xf
	v_mov_b32_dpp v216, v214 row_ror:1 row_mask:0xf bank_mask:0xf
	v_mov_b32_dpp v217, v215 row_ror:1 row_mask:0xf bank_mask:0xf
	v_pk_fma_f32 v[134:135], v[220:221], v[148:149], v[134:135]
	v_mov_b32_dpp v222, v214 row_shr:1 row_mask:0xf bank_mask:0xf
	v_mov_b32_dpp v218, v220 row_shl:1 row_mask:0xf bank_mask:0xf
	v_mov_b32_dpp v223, v215 row_shr:1 row_mask:0xf bank_mask:0xf
	v_mov_b32_dpp v219, v221 row_shl:1 row_mask:0xf bank_mask:0xf
	v_mov_b32_dpp v210, v188 row_ror:15 row_mask:0xf bank_mask:0xf
	v_mov_b32_dpp v211, v189 row_ror:15 row_mask:0xf bank_mask:0xf
	v_pk_fma_f32 v[134:135], v[142:143], v[218:219], v[134:135]
	v_pk_mul_f32 v[218:219], v[146:147], v[222:223]
	v_mov_b32_dpp v216, v188 row_shr:1 row_mask:0xf bank_mask:0xf
	v_mov_b32_dpp v217, v189 row_shr:1 row_mask:0xf bank_mask:0xf
	v_mov_b32_dpp v190, v138 row_shr:1 row_mask:0xf bank_mask:0xf
	v_mov_b32_dpp v191, v139 row_shr:1 row_mask:0xf bank_mask:0xf
	v_pk_add_f32 v[134:135], v[144:145], v[134:135]
	v_pk_fma_f32 v[218:219], v[214:215], v[148:149], v[218:219]
	v_mov_b32_dpp v210, v214 row_shl:1 row_mask:0xf bank_mask:0xf
	v_mov_b32_dpp v211, v215 row_shl:1 row_mask:0xf bank_mask:0xf
	v_pk_mul_f32 v[214:215], v[146:147], v[216:217]
	v_pk_mul_f32 v[146:147], v[146:147], v[190:191]
	v_mov_b32_dpp v150, v138 row_ror:15 row_mask:0xf bank_mask:0xf
	v_mov_b32_dpp v130, v138 row_shl:1 row_mask:0xf bank_mask:0xf
	v_mov_b32_dpp v151, v139 row_ror:15 row_mask:0xf bank_mask:0xf
	v_mov_b32_dpp v131, v139 row_shl:1 row_mask:0xf bank_mask:0xf
	v_pk_fma_f32 v[138:139], v[138:139], v[148:149], v[146:147]
	v_and_b32_e32 v147, 0x7fffffff, v135
	v_and_b32_e32 v146, 0x7fffffff, v134
	v_pk_fma_f32 v[214:215], v[188:189], v[148:149], v[214:215]
	v_pk_fma_f32 v[148:149], v[146:147], s[52:53], 1.0 op_sel_hi:[1,0,0]
	v_mov_b32_dpp v150, v188 row_shl:1 row_mask:0xf bank_mask:0xf
	v_rcp_f32_e32 v148, v148
	v_rcp_f32_e32 v149, v149
	v_mov_b32_dpp v151, v189 row_shl:1 row_mask:0xf bank_mask:0xf
	v_pk_fma_f32 v[210:211], v[142:143], v[210:211], v[218:219]
	v_pk_fma_f32 v[150:151], v[142:143], v[150:151], v[214:215]
	v_pk_fma_f32 v[130:131], v[142:143], v[130:131], v[138:139]
	v_pk_add_f32 v[210:211], v[144:145], v[210:211]
	v_pk_add_f32 v[150:151], v[144:145], v[150:151]
	v_pk_add_f32 v[130:131], v[144:145], v[130:131]
	v_pk_mul_f32 v[144:145], v[134:135], v[134:135]
	v_pk_fma_f32 v[142:143], v[148:149], s[54:55], v[246:247] op_sel_hi:[1,0,0]
	v_pk_mul_f32 v[144:145], v[144:145], s[64:65] op_sel_hi:[1,0]
	v_pk_fma_f32 v[142:143], v[148:149], v[142:143], s[58:59] op_sel_hi:[1,1,0]
	v_exp_f32_e32 v144, v144
	v_exp_f32_e32 v145, v145
	v_pk_fma_f32 v[142:143], v[148:149], v[142:143], s[60:61] op_sel_hi:[1,1,0]
	v_max_f32_e32 v134, 0, v134
	v_pk_fma_f32 v[142:143], v[148:149], v[142:143], s[62:63] op_sel_hi:[1,1,0]
	v_max_f32_e32 v135, 0, v135
	v_pk_mul_f32 v[142:143], v[148:149], v[142:143]
	s_and_b64 vcc, exec, s[8:9]
	v_pk_mul_f32 v[142:143], v[144:145], v[142:143]
	s_nop 0
	v_pk_fma_f32 v[134:135], v[146:147], v[142:143], v[134:135] neg_lo:[1,0,0] neg_hi:[1,0,0]
	v_and_b32_e32 v143, 0x7fffffff, v211
	v_and_b32_e32 v142, 0x7fffffff, v210
	v_pk_fma_f32 v[144:145], v[142:143], s[52:53], 1.0 op_sel_hi:[1,0,0]
	v_pk_mul_f32 v[146:147], v[210:211], v[210:211]
	v_rcp_f32_e32 v144, v144
	v_rcp_f32_e32 v145, v145
	v_pk_mul_f32 v[248:249], v[46:47], v[134:135]
	v_pk_mul_f32 v[146:147], v[146:147], s[64:65] op_sel_hi:[1,0]
	v_pk_fma_f32 v[134:135], v[144:145], s[54:55], v[246:247] op_sel_hi:[1,0,0]
	v_exp_f32_e32 v146, v146
	v_pk_fma_f32 v[134:135], v[144:145], v[134:135], s[58:59] op_sel_hi:[1,1,0]
	v_exp_f32_e32 v147, v147
	v_pk_fma_f32 v[134:135], v[144:145], v[134:135], s[60:61] op_sel_hi:[1,1,0]
	v_pk_mul_f32 v[248:249], v[172:173], v[248:249] op_sel_hi:[0,1]
	v_pk_fma_f32 v[134:135], v[144:145], v[134:135], s[62:63] op_sel_hi:[1,1,0]
	v_pk_mul_f32 v[134:135], v[144:145], v[134:135]
	v_max_f32_e32 v144, 0, v210
	v_max_f32_e32 v145, 0, v211
	v_pk_mul_f32 v[134:135], v[146:147], v[134:135]
	v_cvt_pk_bf16_f32 v133, v248, v249
	v_pk_mul_f32 v[146:147], v[150:151], v[150:151]
	v_pk_fma_f32 v[134:135], v[142:143], v[134:135], v[144:145] neg_lo:[1,0,0] neg_hi:[1,0,0]
	v_and_b32_e32 v143, 0x7fffffff, v151
	v_and_b32_e32 v142, 0x7fffffff, v150
	v_pk_fma_f32 v[144:145], v[142:143], s[52:53], 1.0 op_sel_hi:[1,0,0]
	v_rcp_f32_e32 v144, v144
	v_rcp_f32_e32 v145, v145
	v_pk_mul_f32 v[134:135], v[42:43], v[134:135]
	v_pk_mul_f32 v[134:135], v[178:179], v[134:135] op_sel_hi:[0,1]
	v_cvt_pk_bf16_f32 v137, v134, v135
	v_pk_fma_f32 v[134:135], v[144:145], s[54:55], v[246:247] op_sel_hi:[1,0,0]
	v_pk_mul_f32 v[146:147], v[146:147], s[64:65] op_sel_hi:[1,0]
	v_pk_fma_f32 v[134:135], v[144:145], v[134:135], s[58:59] op_sel_hi:[1,1,0]
	v_exp_f32_e32 v146, v146
	v_exp_f32_e32 v147, v147
	v_pk_fma_f32 v[134:135], v[144:145], v[134:135], s[60:61] op_sel_hi:[1,1,0]
	s_nop 0
	v_pk_fma_f32 v[134:135], v[144:145], v[134:135], s[62:63] op_sel_hi:[1,1,0]
	s_nop 0
	v_pk_mul_f32 v[134:135], v[144:145], v[134:135]
	v_max_f32_e32 v144, 0, v150
	v_max_f32_e32 v145, 0, v151
	v_pk_mul_f32 v[134:135], v[146:147], v[134:135]
	s_nop 0
	v_pk_fma_f32 v[134:135], v[142:143], v[134:135], v[144:145] neg_lo:[1,0,0] neg_hi:[1,0,0]
	v_and_b32_e32 v143, 0x7fffffff, v131
	v_and_b32_e32 v142, 0x7fffffff, v130
	v_pk_fma_f32 v[144:145], v[142:143], s[52:53], 1.0 op_sel_hi:[1,0,0]
	v_rcp_f32_e32 v144, v144
	v_rcp_f32_e32 v145, v145
	v_pk_mul_f32 v[134:135], v[38:39], v[134:135]
	v_pk_mul_f32 v[134:135], v[176:177], v[134:135] op_sel_hi:[0,1]
	v_cvt_pk_bf16_f32 v141, v134, v135
	v_pk_fma_f32 v[134:135], v[144:145], s[54:55], v[246:247] op_sel_hi:[1,0,0]
	v_pk_mul_f32 v[138:139], v[130:131], v[130:131]
	v_pk_fma_f32 v[134:135], v[144:145], v[134:135], s[58:59] op_sel_hi:[1,1,0]
	v_pk_mul_f32 v[138:139], v[138:139], s[64:65] op_sel_hi:[1,0]
	v_pk_fma_f32 v[134:135], v[144:145], v[134:135], s[60:61] op_sel_hi:[1,1,0]
	v_exp_f32_e32 v138, v138
	v_exp_f32_e32 v139, v139
	v_pk_fma_f32 v[134:135], v[144:145], v[134:135], s[62:63] op_sel_hi:[1,1,0]
	v_max_f32_e32 v130, 0, v130
	v_pk_mul_f32 v[134:135], v[144:145], v[134:135]
	v_max_f32_e32 v131, 0, v131
	v_pk_mul_f32 v[134:135], v[138:139], v[134:135]
	s_nop 0
	v_pk_fma_f32 v[130:131], v[142:143], v[134:135], v[130:131] neg_lo:[1,0,0] neg_hi:[1,0,0]
	v_mov_b32_e32 v134, 0
	v_mul_f32_e32 v129, v34, v130
	v_mul_f32_e32 v129, v170, v129
	v_mul_f32_e32 v130, v35, v131
	v_mul_f32_e32 v130, v170, v130
	v_cvt_pk_bf16_f32 v129, v129, v130
	ds_read2st64_b64 v[146:149], v208 offset0:10 offset1:11
	ds_read2st64_b64 v[142:145], v208 offset0:12 offset1:13
	v_mov_b32_e32 v130, 0
	v_mov_b32_e32 v135, 0
	s_cbranch_vccnz .LBB0_697
	v_add_u32_e32 v131, s87, v206
	ds_read_b64 v[134:135], v131 offset:1552

.LBB0_699:
	v_pk_mul_f32 v[220:221], v[16:17], v[172:173]
	v_pk_mul_f32 v[214:215], v[24:25], v[178:179]
	v_pk_mul_f32 v[188:189], v[28:29], v[176:177]
	s_waitcnt lgkmcnt(0)
	v_mov_b32_dpp v134, v220 row_shr:1 row_mask:0xf bank_mask:0xf
	v_mov_b32_dpp v135, v221 row_shr:1 row_mask:0xf bank_mask:0xf
	v_mov_b32_dpp v218, v214 row_ror:15 row_mask:0xf bank_mask:0xf
	v_mov_b32_dpp v219, v215 row_ror:15 row_mask:0xf bank_mask:0xf
	v_mov_b32_dpp v222, v220 row_ror:1 row_mask:0xf bank_mask:0xf
	v_mov_b32_dpp v223, v221 row_ror:1 row_mask:0xf bank_mask:0xf
	v_pk_mul_f32 v[134:135], v[146:147], v[134:135]
	v_pk_mul_f32 v[138:139], v[20:21], v[170:171]
	v_mov_b32_dpp v190, v188 row_ror:1 row_mask:0xf bank_mask:0xf
	v_mov_b32_dpp v191, v189 row_ror:1 row_mask:0xf bank_mask:0xf
	v_mov_b32_dpp v216, v214 row_ror:1 row_mask:0xf bank_mask:0xf
	v_mov_b32_dpp v217, v215 row_ror:1 row_mask:0xf bank_mask:0xf
	v_pk_fma_f32 v[134:135], v[220:221], v[148:149], v[134:135]
	v_mov_b32_dpp v222, v214 row_shr:1 row_mask:0xf bank_mask:0xf
	v_mov_b32_dpp v218, v220 row_shl:1 row_mask:0xf bank_mask:0xf
	v_mov_b32_dpp v223, v215 row_shr:1 row_mask:0xf bank_mask:0xf
	v_mov_b32_dpp v219, v221 row_shl:1 row_mask:0xf bank_mask:0xf
	v_mov_b32_dpp v210, v188 row_ror:15 row_mask:0xf bank_mask:0xf
	v_mov_b32_dpp v211, v189 row_ror:15 row_mask:0xf bank_mask:0xf
	v_pk_fma_f32 v[134:135], v[142:143], v[218:219], v[134:135]
	v_pk_mul_f32 v[218:219], v[146:147], v[222:223]
	v_mov_b32_dpp v216, v188 row_shr:1 row_mask:0xf bank_mask:0xf
	v_mov_b32_dpp v217, v189 row_shr:1 row_mask:0xf bank_mask:0xf
	v_mov_b32_dpp v190, v138 row_shr:1 row_mask:0xf bank_mask:0xf
	v_mov_b32_dpp v191, v139 row_shr:1 row_mask:0xf bank_mask:0xf
	v_pk_add_f32 v[134:135], v[144:145], v[134:135]
	v_pk_fma_f32 v[218:219], v[214:215], v[148:149], v[218:219]
	v_mov_b32_dpp v210, v214 row_shl:1 row_mask:0xf bank_mask:0xf
	v_mov_b32_dpp v211, v215 row_shl:1 row_mask:0xf bank_mask:0xf
	v_pk_mul_f32 v[214:215], v[146:147], v[216:217]
	v_pk_mul_f32 v[146:147], v[146:147], v[190:191]
	v_mov_b32_dpp v150, v138 row_ror:15 row_mask:0xf bank_mask:0xf
	v_mov_b32_dpp v130, v138 row_shl:1 row_mask:0xf bank_mask:0xf
	v_mov_b32_dpp v151, v139 row_ror:15 row_mask:0xf bank_mask:0xf
	v_mov_b32_dpp v131, v139 row_shl:1 row_mask:0xf bank_mask:0xf
	v_pk_fma_f32 v[138:139], v[138:139], v[148:149], v[146:147]
	v_and_b32_e32 v147, 0x7fffffff, v135
	v_and_b32_e32 v146, 0x7fffffff, v134
	v_pk_fma_f32 v[214:215], v[188:189], v[148:149], v[214:215]
	v_pk_fma_f32 v[148:149], v[146:147], s[52:53], 1.0 op_sel_hi:[1,0,0]
	v_mov_b32_dpp v150, v188 row_shl:1 row_mask:0xf bank_mask:0xf
	v_rcp_f32_e32 v148, v148
	v_rcp_f32_e32 v149, v149
	v_mov_b32_dpp v151, v189 row_shl:1 row_mask:0xf bank_mask:0xf
	v_pk_fma_f32 v[210:211], v[142:143], v[210:211], v[218:219]
	v_pk_fma_f32 v[150:151], v[142:143], v[150:151], v[214:215]
	v_pk_fma_f32 v[130:131], v[142:143], v[130:131], v[138:139]
	v_pk_add_f32 v[210:211], v[144:145], v[210:211]
	v_pk_add_f32 v[150:151], v[144:145], v[150:151]
	v_pk_add_f32 v[130:131], v[144:145], v[130:131]
	v_pk_mul_f32 v[142:143], v[134:135], v[134:135]
	v_pk_fma_f32 v[138:139], v[148:149], s[54:55], v[246:247] op_sel_hi:[1,0,0]
	v_pk_mul_f32 v[142:143], v[142:143], s[64:65] op_sel_hi:[1,0]
	v_pk_fma_f32 v[138:139], v[148:149], v[138:139], s[58:59] op_sel_hi:[1,1,0]
	v_exp_f32_e32 v142, v142
	v_exp_f32_e32 v143, v143
	v_pk_fma_f32 v[138:139], v[148:149], v[138:139], s[60:61] op_sel_hi:[1,1,0]
	v_max_f32_e32 v134, 0, v134
	v_pk_fma_f32 v[138:139], v[148:149], v[138:139], s[62:63] op_sel_hi:[1,1,0]
	v_max_f32_e32 v135, 0, v135
	v_pk_mul_f32 v[138:139], v[148:149], v[138:139]
	v_pk_mul_f32 v[148:149], v[210:211], v[210:211]
	v_pk_mul_f32 v[138:139], v[142:143], v[138:139]
	v_pk_mul_f32 v[148:149], v[148:149], s[64:65] op_sel_hi:[1,0]
	v_pk_fma_f32 v[134:135], v[146:147], v[138:139], v[134:135] neg_lo:[1,0,0] neg_hi:[1,0,0]
	v_and_b32_e32 v139, 0x7fffffff, v211
	v_and_b32_e32 v138, 0x7fffffff, v210
	v_pk_fma_f32 v[142:143], v[138:139], s[52:53], 1.0 op_sel_hi:[1,0,0]
	v_exp_f32_e32 v148, v148
	v_rcp_f32_e32 v142, v142
	v_rcp_f32_e32 v143, v143
	v_exp_f32_e32 v149, v149
	v_pk_mul_f32 v[188:189], v[150:151], v[150:151]
	v_pk_fma_f32 v[146:147], v[142:143], s[54:55], v[246:247] op_sel_hi:[1,0,0]
	v_pk_mul_f32 v[188:189], v[188:189], s[64:65] op_sel_hi:[1,0]
	v_pk_fma_f32 v[146:147], v[142:143], v[146:147], s[58:59] op_sel_hi:[1,1,0]
	v_exp_f32_e32 v188, v188
	v_pk_fma_f32 v[146:147], v[142:143], v[146:147], s[60:61] op_sel_hi:[1,1,0]
	v_exp_f32_e32 v189, v189
	v_pk_fma_f32 v[146:147], v[142:143], v[146:147], s[62:63] op_sel_hi:[1,1,0]
	v_pk_mul_f32 v[134:135], v[12:13], v[134:135]
	v_pk_mul_f32 v[142:143], v[142:143], v[146:147]
	v_max_f32_e32 v146, 0, v210
	v_max_f32_e32 v147, 0, v211
	v_pk_mul_f32 v[142:143], v[148:149], v[142:143]
	v_pk_fma_f32 v[138:139], v[138:139], v[142:143], v[146:147] neg_lo:[1,0,0] neg_hi:[1,0,0]
	v_and_b32_e32 v143, 0x7fffffff, v151
	v_and_b32_e32 v142, 0x7fffffff, v150
	v_pk_fma_f32 v[146:147], v[142:143], s[52:53], 1.0 op_sel_hi:[1,0,0]
	v_pk_mul_f32 v[134:135], v[172:173], v[134:135] op_sel_hi:[0,1]
	v_rcp_f32_e32 v146, v146
	v_rcp_f32_e32 v147, v147
	v_cvt_pk_bf16_f32 v134, v134, v135
	v_pk_mul_f32 v[138:139], v[8:9], v[138:139]
	v_pk_fma_f32 v[148:149], v[146:147], s[54:55], v[246:247] op_sel_hi:[1,0,0]
	v_pk_fma_f32 v[148:149], v[146:147], v[148:149], s[58:59] op_sel_hi:[1,1,0]
	v_pk_mul_f32 v[138:139], v[178:179], v[138:139] op_sel_hi:[0,1]
	v_pk_fma_f32 v[148:149], v[146:147], v[148:149], s[60:61] op_sel_hi:[1,1,0]
	v_cvt_pk_bf16_f32 v138, v138, v139
	s_and_b64 vcc, exec, s[8:9]
	v_pk_fma_f32 v[148:149], v[146:147], v[148:149], s[62:63] op_sel_hi:[1,1,0]
	v_mov_b32_e32 v190, 0
	v_pk_mul_f32 v[146:147], v[146:147], v[148:149]
	v_max_f32_e32 v148, 0, v150
	v_max_f32_e32 v149, 0, v151
	v_pk_mul_f32 v[146:147], v[188:189], v[146:147]
	v_pk_mul_f32 v[150:151], v[130:131], v[130:131]
	v_pk_fma_f32 v[142:143], v[142:143], v[146:147], v[148:149] neg_lo:[1,0,0] neg_hi:[1,0,0]
	v_and_b32_e32 v147, 0x7fffffff, v131
	v_and_b32_e32 v146, 0x7fffffff, v130
	v_pk_fma_f32 v[148:149], v[146:147], s[52:53], 1.0 op_sel_hi:[1,0,0]
	v_pk_mul_f32 v[150:151], v[150:151], s[64:65] op_sel_hi:[1,0]
	v_rcp_f32_e32 v148, v148
	v_rcp_f32_e32 v149, v149
	v_exp_f32_e32 v150, v150
	v_exp_f32_e32 v151, v151
	v_max_f32_e32 v130, 0, v130
	v_pk_fma_f32 v[144:145], v[148:149], s[54:55], v[246:247] op_sel_hi:[1,0,0]
	v_max_f32_e32 v131, 0, v131
	v_pk_fma_f32 v[144:145], v[148:149], v[144:145], s[58:59] op_sel_hi:[1,1,0]
	v_pk_fma_f32 v[144:145], v[148:149], v[144:145], s[60:61] op_sel_hi:[1,1,0]
	v_pk_mul_f32 v[142:143], v[4:5], v[142:143]
	v_pk_fma_f32 v[144:145], v[148:149], v[144:145], s[62:63] op_sel_hi:[1,1,0]
	v_pk_mul_f32 v[144:145], v[148:149], v[144:145]
	v_pk_mul_f32 v[142:143], v[176:177], v[142:143] op_sel_hi:[0,1]
	v_pk_mul_f32 v[144:145], v[150:151], v[144:145]
	v_cvt_pk_bf16_f32 v142, v142, v143
	v_mov_b32_e32 v188, 0
	v_pk_fma_f32 v[130:131], v[146:147], v[144:145], v[130:131] neg_lo:[1,0,0] neg_hi:[1,0,0]
	v_mov_b32_e32 v191, 0
	v_mul_f32_e32 v130, v0, v130
	v_mul_f32_e32 v130, v170, v130
	v_mul_f32_e32 v131, v1, v131
	v_mul_f32_e32 v131, v170, v131
	v_cvt_pk_bf16_f32 v130, v130, v131
	ds_read2st64_b64 v[148:151], v209 offset0:10 offset1:11
	ds_read2st64_b64 v[144:147], v209 offset0:12 offset1:13
	s_cbranch_vccnz .LBB0_701
	v_add_u32_e32 v131, s87, v206
	ds_read_b64 v[190:191], v131 offset:1560

.LBB0_703:
	v_pk_mul_f32 v[224:225], v[18:19], v[172:173]
	v_pk_mul_f32 v[218:219], v[26:27], v[178:179]
	v_pk_mul_f32 v[210:211], v[30:31], v[176:177]
	s_waitcnt lgkmcnt(0)
	v_mov_b32_dpp v190, v224 row_shr:1 row_mask:0xf bank_mask:0xf
	v_mov_b32_dpp v191, v225 row_shr:1 row_mask:0xf bank_mask:0xf
	v_mov_b32_dpp v222, v218 row_ror:15 row_mask:0xf bank_mask:0xf
	v_mov_b32_dpp v223, v219 row_ror:15 row_mask:0xf bank_mask:0xf
	v_mov_b32_dpp v226, v224 row_ror:1 row_mask:0xf bank_mask:0xf
	v_mov_b32_dpp v227, v225 row_ror:1 row_mask:0xf bank_mask:0xf
	v_pk_mul_f32 v[190:191], v[148:149], v[190:191]
	v_pk_mul_f32 v[206:207], v[22:23], v[170:171]
	v_mov_b32_dpp v214, v210 row_ror:1 row_mask:0xf bank_mask:0xf
	v_mov_b32_dpp v215, v211 row_ror:1 row_mask:0xf bank_mask:0xf
	v_mov_b32_dpp v220, v218 row_ror:1 row_mask:0xf bank_mask:0xf
	v_mov_b32_dpp v221, v219 row_ror:1 row_mask:0xf bank_mask:0xf
	v_pk_fma_f32 v[190:191], v[224:225], v[150:151], v[190:191]
	v_mov_b32_dpp v226, v218 row_shr:1 row_mask:0xf bank_mask:0xf
	v_mov_b32_dpp v222, v224 row_shl:1 row_mask:0xf bank_mask:0xf
	v_mov_b32_dpp v227, v219 row_shr:1 row_mask:0xf bank_mask:0xf
	v_mov_b32_dpp v223, v225 row_shl:1 row_mask:0xf bank_mask:0xf
	v_mov_b32_dpp v216, v210 row_ror:15 row_mask:0xf bank_mask:0xf
	v_mov_b32_dpp v217, v211 row_ror:15 row_mask:0xf bank_mask:0xf
	v_pk_fma_f32 v[190:191], v[144:145], v[222:223], v[190:191]
	v_pk_mul_f32 v[222:223], v[148:149], v[226:227]
	v_mov_b32_dpp v220, v210 row_shr:1 row_mask:0xf bank_mask:0xf
	v_mov_b32_dpp v221, v211 row_shr:1 row_mask:0xf bank_mask:0xf
	v_mov_b32_dpp v214, v206 row_shr:1 row_mask:0xf bank_mask:0xf
	v_mov_b32_dpp v215, v207 row_shr:1 row_mask:0xf bank_mask:0xf
	v_pk_add_f32 v[190:191], v[146:147], v[190:191]
	v_pk_fma_f32 v[222:223], v[218:219], v[150:151], v[222:223]
	v_mov_b32_dpp v216, v218 row_shl:1 row_mask:0xf bank_mask:0xf
	v_mov_b32_dpp v217, v219 row_shl:1 row_mask:0xf bank_mask:0xf
	v_pk_mul_f32 v[218:219], v[148:149], v[220:221]
	v_pk_mul_f32 v[148:149], v[148:149], v[214:215]
	v_pk_fma_f32 v[218:219], v[210:211], v[150:151], v[218:219]
	v_pk_fma_f32 v[148:149], v[206:207], v[150:151], v[148:149]
	v_and_b32_e32 v151, 0x7fffffff, v191
	v_and_b32_e32 v150, 0x7fffffff, v190
	v_mov_b32_dpp v208, v206 row_ror:15 row_mask:0xf bank_mask:0xf
	v_mov_b32_dpp v188, v206 row_shl:1 row_mask:0xf bank_mask:0xf
	v_mov_b32_dpp v209, v207 row_ror:15 row_mask:0xf bank_mask:0xf
	v_mov_b32_dpp v189, v207 row_shl:1 row_mask:0xf bank_mask:0xf
	v_pk_fma_f32 v[206:207], v[150:151], s[52:53], 1.0 op_sel_hi:[1,0,0]
	v_mov_b32_dpp v208, v210 row_shl:1 row_mask:0xf bank_mask:0xf
	v_rcp_f32_e32 v206, v206
	v_rcp_f32_e32 v207, v207
	v_mov_b32_dpp v209, v211 row_shl:1 row_mask:0xf bank_mask:0xf
	v_pk_fma_f32 v[216:217], v[144:145], v[216:217], v[222:223]
	v_pk_fma_f32 v[208:209], v[144:145], v[208:209], v[218:219]
	v_pk_fma_f32 v[144:145], v[144:145], v[188:189], v[148:149]
	v_pk_add_f32 v[216:217], v[146:147], v[216:217]
	v_pk_add_f32 v[208:209], v[146:147], v[208:209]
	v_pk_add_f32 v[144:145], v[146:147], v[144:145]
	v_pk_mul_f32 v[188:189], v[190:191], v[190:191]
	v_pk_fma_f32 v[148:149], v[206:207], s[54:55], v[246:247] op_sel_hi:[1,0,0]
	v_pk_mul_f32 v[188:189], v[188:189], s[64:65] op_sel_hi:[1,0]
	v_pk_fma_f32 v[148:149], v[206:207], v[148:149], s[58:59] op_sel_hi:[1,1,0]
	v_exp_f32_e32 v188, v188
	v_exp_f32_e32 v189, v189
	v_pk_fma_f32 v[148:149], v[206:207], v[148:149], s[60:61] op_sel_hi:[1,1,0]
	v_max_f32_e32 v190, 0, v190
	v_pk_fma_f32 v[148:149], v[206:207], v[148:149], s[62:63] op_sel_hi:[1,1,0]
	v_max_f32_e32 v191, 0, v191
	v_pk_mul_f32 v[148:149], v[206:207], v[148:149]
	s_nop 0
	v_pk_mul_f32 v[148:149], v[188:189], v[148:149]
	s_nop 0
	v_pk_fma_f32 v[148:149], v[150:151], v[148:149], v[190:191] neg_lo:[1,0,0] neg_hi:[1,0,0]
	v_and_b32_e32 v151, 0x7fffffff, v217
	v_and_b32_e32 v150, 0x7fffffff, v216
	v_pk_fma_f32 v[188:189], v[150:151], s[52:53], 1.0 op_sel_hi:[1,0,0]
	v_pk_mul_f32 v[190:191], v[216:217], v[216:217]
	v_rcp_f32_e32 v188, v188
	v_rcp_f32_e32 v189, v189
	v_pk_mul_f32 v[248:249], v[14:15], v[148:149]
	v_pk_mul_f32 v[190:191], v[190:191], s[64:65] op_sel_hi:[1,0]
	v_pk_fma_f32 v[148:149], v[188:189], s[54:55], v[246:247] op_sel_hi:[1,0,0]
	v_exp_f32_e32 v190, v190
	v_pk_fma_f32 v[148:149], v[188:189], v[148:149], s[58:59] op_sel_hi:[1,1,0]
	v_exp_f32_e32 v191, v191
	v_pk_fma_f32 v[148:149], v[188:189], v[148:149], s[60:61] op_sel_hi:[1,1,0]
	v_pk_mul_f32 v[248:249], v[172:173], v[248:249] op_sel_hi:[0,1]
	v_pk_fma_f32 v[148:149], v[188:189], v[148:149], s[62:63] op_sel_hi:[1,1,0]
	v_pk_mul_f32 v[148:149], v[188:189], v[148:149]
	v_max_f32_e32 v188, 0, v216
	v_max_f32_e32 v189, 0, v217
	v_pk_mul_f32 v[148:149], v[190:191], v[148:149]
	v_pk_mul_f32 v[190:191], v[208:209], v[208:209]
	v_pk_fma_f32 v[148:149], v[150:151], v[148:149], v[188:189] neg_lo:[1,0,0] neg_hi:[1,0,0]
	v_and_b32_e32 v151, 0x7fffffff, v209
	v_and_b32_e32 v150, 0x7fffffff, v208
	v_pk_fma_f32 v[188:189], v[150:151], s[52:53], 1.0 op_sel_hi:[1,0,0]
	v_cvt_pk_bf16_f32 v135, v248, v249
	v_pk_mul_f32 v[248:249], v[10:11], v[148:149]
	v_rcp_f32_e32 v188, v188
	v_rcp_f32_e32 v189, v189
	v_pk_mul_f32 v[190:191], v[190:191], s[64:65] op_sel_hi:[1,0]
	v_pk_mul_f32 v[248:249], v[178:179], v[248:249] op_sel_hi:[0,1]
	v_pk_fma_f32 v[148:149], v[188:189], s[54:55], v[246:247] op_sel_hi:[1,0,0]
	v_exp_f32_e32 v190, v190
	v_pk_fma_f32 v[148:149], v[188:189], v[148:149], s[58:59] op_sel_hi:[1,1,0]
	v_exp_f32_e32 v191, v191
	v_pk_fma_f32 v[148:149], v[188:189], v[148:149], s[60:61] op_sel_hi:[1,1,0]
	v_pk_fma_f32 v[148:149], v[188:189], v[148:149], s[62:63] op_sel_hi:[1,1,0]
	v_cvt_pk_bf16_f32 v139, v248, v249
	s_nop 0
	v_pk_mul_f32 v[148:149], v[188:189], v[148:149]
	v_max_f32_e32 v188, 0, v208
	v_max_f32_e32 v189, 0, v209
	v_pk_mul_f32 v[148:149], v[190:191], v[148:149]
	s_nop 0
	v_pk_fma_f32 v[148:149], v[150:151], v[148:149], v[188:189] neg_lo:[1,0,0] neg_hi:[1,0,0]
	v_and_b32_e32 v151, 0x7fffffff, v145
	v_and_b32_e32 v150, 0x7fffffff, v144
	v_pk_fma_f32 v[188:189], v[150:151], s[52:53], 1.0 op_sel_hi:[1,0,0]
	v_pk_mul_f32 v[248:249], v[6:7], v[148:149]
	v_rcp_f32_e32 v188, v188
	v_rcp_f32_e32 v189, v189
	v_pk_mul_f32 v[148:149], v[144:145], v[144:145]
	v_max_f32_e32 v144, 0, v144
	v_pk_fma_f32 v[146:147], v[188:189], s[54:55], v[246:247] op_sel_hi:[1,0,0]
	v_pk_mul_f32 v[148:149], v[148:149], s[64:65] op_sel_hi:[1,0]
	v_pk_fma_f32 v[146:147], v[188:189], v[146:147], s[58:59] op_sel_hi:[1,1,0]
	v_exp_f32_e32 v148, v148
	v_exp_f32_e32 v149, v149
	v_pk_fma_f32 v[146:147], v[188:189], v[146:147], s[60:61] op_sel_hi:[1,1,0]
	v_max_f32_e32 v145, 0, v145
	v_pk_fma_f32 v[146:147], v[188:189], v[146:147], s[62:63] op_sel_hi:[1,1,0]
	v_pk_mul_f32 v[248:249], v[176:177], v[248:249] op_sel_hi:[0,1]
	v_pk_mul_f32 v[146:147], v[188:189], v[146:147]
	v_pk_mul_f32 v[146:147], v[148:149], v[146:147]
	v_cvt_pk_bf16_f32 v143, v248, v249
	s_nop 0
	v_pk_fma_f32 v[144:145], v[150:151], v[146:147], v[144:145] neg_lo:[1,0,0] neg_hi:[1,0,0]
	s_nop 0
	v_pk_mul_f32 v[144:145], v[2:3], v[144:145]
	v_pk_mul_f32 v[144:145], v[170:171], v[144:145] op_sel_hi:[0,1]
	v_cvt_pk_bf16_f32 v131, v144, v145
	v_add_u32_e32 v144, s86, v201
	v_add_u32_e32 v145, s29, v144
	v_add_u32_e32 v146, -1, v144
	v_cmp_gt_u32_e32 vcc, s76, v146
	v_cmp_gt_i32_e64 s[8:9], s78, v145
	s_and_b64 s[10:11], vcc, s[8:9]
	s_and_saveexec_b64 s[8:9], s[10:11]
	s_cbranch_execz .LBB0_705
	v_mov_b64_e32 v[146:147], s[38:39]
	v_mad_i64_i32 v[146:147], s[10:11], v145, s31, v[146:147]
	v_lshl_add_u64 v[146:147], v[174:175], 1, v[146:147]
	global_store_dwordx4 v[146:147], v[132:135], off

.LBB0_720:
	v_sub_u32_e32 v146, 0x1fef, v203
	v_and_b32_e32 v146, 0x1fff, v146
	v_cmp_eq_u32_e64 s[20:21], 0, v146
	v_sub_u32_e32 v146, 0x1fdf, v203
	v_and_b32_e32 v146, 0x1fff, v146
	v_pk_mul_f32 v[124:125], v[124:125], v[184:185] op_sel_hi:[1,0]
	v_pk_mul_f32 v[148:149], v[112:113], v[182:183] op_sel_hi:[1,0]
	v_and_b32_e32 v145, 0x1fff, v203
	v_cmp_eq_u32_e64 s[22:23], 0, v146
	v_mul_f32_e32 v120, v120, v180
	v_mul_f32_e32 v146, v121, v180
	v_mov_b32_dpp v121, v124 row_ror:1 row_mask:0xf bank_mask:0xf
	v_pk_mul_f32 v[116:117], v[116:117], v[186:187] op_sel_hi:[1,0]
	v_mov_b32_dpp v112, v148 row_ror:1 row_mask:0xf bank_mask:0xf
	v_mov_b32_dpp v181, v149 row_ror:1 row_mask:0xf bank_mask:0xf
	v_cmp_eq_u32_e64 s[16:17], 0, v145
	v_cmp_eq_u32_e64 s[18:19], s80, v145
	v_cmp_eq_u32_e64 s[8:9], s81, v145
	v_cmp_eq_u32_e64 s[10:11], s26, v145
	v_cmp_eq_u32_e64 s[12:13], s27, v145
	v_sub_u32_e32 v145, 0x1fcf, v203
	v_mov_b32_dpp v121, v120 row_shr:1 row_mask:0xf bank_mask:0xf
	v_mov_b32_dpp v175, v116 row_ror:1 row_mask:0xf bank_mask:0xf
	v_mov_b32_dpp v177, v117 row_ror:1 row_mask:0xf bank_mask:0xf
	s_waitcnt lgkmcnt(0)
	v_mov_b32_dpp v138, v148 row_shr:1 row_mask:0xf bank_mask:0xf
	v_mov_b32_dpp v139, v149 row_shr:1 row_mask:0xf bank_mask:0xf
	v_mov_b32_dpp v112, v116 row_shr:1 row_mask:0xf bank_mask:0xf
	v_mov_b32_dpp v181, v117 row_shr:1 row_mask:0xf bank_mask:0xf
	v_and_b32_e32 v145, 0x1fff, v145
	v_mov_b32_dpp v147, v146 row_ror:15 row_mask:0xf bank_mask:0xf
	v_mov_b32_dpp v151, v124 row_ror:15 row_mask:0xf bank_mask:0xf
	v_mov_b32_dpp v171, v125 row_ror:1 row_mask:0xf bank_mask:0xf
	v_mov_b32_dpp v150, v116 row_ror:15 row_mask:0xf bank_mask:0xf
	v_mov_b32_dpp v179, v117 row_ror:15 row_mask:0xf bank_mask:0xf
	v_mov_b32_dpp v175, v124 row_shr:1 row_mask:0xf bank_mask:0xf
	v_mov_b32_dpp v177, v125 row_shr:1 row_mask:0xf bank_mask:0xf
	v_cndmask_b32_e64 v138, v138, 0, s[16:17]
	v_cndmask_b32_e64 v188, v112, 0, s[8:9]
	v_cndmask_b32_e64 v121, v121, 0, s[12:13]
	v_mov_b32_e32 v112, v134
	v_mov_b32_e32 v113, v132
	v_cndmask_b32_e64 v139, v139, 0, s[16:17]
	v_cndmask_b32_e64 v189, v181, 0, s[8:9]
	v_cmp_eq_u32_e64 s[14:15], 0, v145
	v_mov_b32_dpp v145, v120 row_ror:15 row_mask:0xf bank_mask:0xf
	v_mov_b32_dpp v136, v120 row_shl:1 row_mask:0xf bank_mask:0xf
	v_mov_b32_dpp v171, v146 row_shr:1 row_mask:0xf bank_mask:0xf
	v_mov_b32_dpp v173, v125 row_ror:15 row_mask:0xf bank_mask:0xf
	v_mov_b32_dpp v147, v125 row_shl:1 row_mask:0xf bank_mask:0xf
	v_mov_b32_dpp v151, v116 row_shl:1 row_mask:0xf bank_mask:0xf
	v_mov_b32_dpp v150, v148 row_shl:1 row_mask:0xf bank_mask:0xf
	v_mov_b32_dpp v179, v149 row_shl:1 row_mask:0xf bank_mask:0xf
	v_cndmask_b32_e64 v206, v175, 0, s[10:11]
	v_pk_mul_f32 v[112:113], v[120:121], v[112:113]
	v_pk_mul_f32 v[120:121], v[132:133], v[138:139]
	v_pk_mul_f32 v[138:139], v[132:133], v[188:189]
	v_cndmask_b32_e64 v207, v177, 0, s[10:11]
	v_mov_b32_dpp v145, v124 row_shl:1 row_mask:0xf bank_mask:0xf
	v_mov_b32_dpp v173, v117 row_shl:1 row_mask:0xf bank_mask:0xf
	v_cndmask_b32_e64 v150, v150, 0, s[18:19]
	v_cndmask_b32_e64 v190, v151, 0, s[20:21]
	v_cndmask_b32_e64 v151, v179, 0, s[18:19]
	v_pk_fma_f32 v[120:121], v[148:149], v[134:135], v[120:121]
	v_pk_fma_f32 v[116:117], v[116:117], v[134:135], v[138:139]
	v_cndmask_b32_e64 v209, v147, 0, s[22:23]
	v_pk_mul_f32 v[138:139], v[132:133], v[206:207]
	v_cndmask_b32_e64 v147, v171, 0, s[12:13]
	v_mov_b32_e32 v132, v135
	v_mov_b32_dpp v137, v146 row_shl:1 row_mask:0xf bank_mask:0xf
	v_cndmask_b32_e64 v208, v145, 0, s[22:23]
	v_add_f32_e32 v112, v112, v113
	v_cndmask_b32_e64 v113, v136, 0, s[14:15]
	v_pk_fma_f32 v[120:121], v[128:129], v[150:151], v[120:121]
	v_cndmask_b32_e64 v191, v173, 0, s[20:21]
	v_pk_fma_f32 v[124:125], v[124:125], v[134:135], v[138:139]
	v_pk_mul_f32 v[132:133], v[146:147], v[132:133]
	v_fmac_f32_e32 v112, v128, v113
	v_pk_add_f32 v[120:121], v[130:131], v[120:121]
	v_pk_fma_f32 v[116:117], v[128:129], v[190:191], v[116:117]
	v_pk_fma_f32 v[124:125], v[128:129], v[208:209], v[124:125]
	v_add_f32_e32 v113, v132, v133
	v_cndmask_b32_e64 v128, v137, 0, s[14:15]
	v_fmac_f32_e32 v113, v129, v128
	v_and_b32_e32 v129, 0x7fffffff, v121
	v_and_b32_e32 v128, 0x7fffffff, v120
	v_add_f32_e32 v112, v130, v112
	v_pk_add_f32 v[116:117], v[130:131], v[116:117]
	v_pk_add_f32 v[124:125], v[130:131], v[124:125]
	v_add_f32_e32 v113, v131, v113
	v_pk_fma_f32 v[130:131], v[128:129], s[52:53], 1.0 op_sel_hi:[1,0,0]
	v_rcp_f32_e32 v130, v130
	v_rcp_f32_e32 v131, v131
	s_and_b64 vcc, exec, s[6:7]
	v_pk_fma_f32 v[134:135], v[130:131], s[54:55], v[246:247] op_sel_hi:[1,0,0]
	s_nop 0
	v_pk_fma_f32 v[134:135], v[130:131], v[134:135], s[58:59] op_sel_hi:[1,1,0]
	s_nop 0
	v_pk_fma_f32 v[134:135], v[130:131], v[134:135], s[60:61] op_sel_hi:[1,1,0]
	s_nop 0
	v_pk_fma_f32 v[134:135], v[130:131], v[134:135], s[62:63] op_sel_hi:[1,1,0]
	s_nop 0
	v_pk_mul_f32 v[130:131], v[130:131], v[134:135]
	v_pk_mul_f32 v[134:135], v[120:121], v[120:121]
	v_max_f32_e32 v120, 0, v120
	v_pk_mul_f32 v[134:135], v[134:135], s[64:65] op_sel_hi:[1,0]
	v_max_f32_e32 v121, 0, v121
	v_exp_f32_e32 v134, v134
	v_exp_f32_e32 v135, v135
	s_nop 0
	v_pk_mul_f32 v[130:131], v[134:135], v[130:131]
	s_nop 0
	v_pk_fma_f32 v[120:121], v[128:129], v[130:131], v[120:121] neg_lo:[1,0,0] neg_hi:[1,0,0]
	s_nop 0
	v_mul_f32_e32 v108, v108, v120
	v_mul_f32_e32 v109, v109, v121
	v_and_b32_e32 v121, 0x7fffffff, v117
	v_and_b32_e32 v120, 0x7fffffff, v116
	v_pk_fma_f32 v[128:129], v[120:121], s[52:53], 1.0 op_sel_hi:[1,0,0]
	v_mul_f32_e32 v108, v182, v108
	v_rcp_f32_e32 v128, v128
	v_rcp_f32_e32 v129, v129
	v_mul_f32_e32 v109, v182, v109
	v_cvt_pk_bf16_f32 v108, v108, v109
	v_pk_fma_f32 v[130:131], v[128:129], s[54:55], v[246:247] op_sel_hi:[1,0,0]
	s_nop 0
	v_pk_fma_f32 v[130:131], v[128:129], v[130:131], s[58:59] op_sel_hi:[1,1,0]
	s_nop 0
	v_pk_fma_f32 v[130:131], v[128:129], v[130:131], s[60:61] op_sel_hi:[1,1,0]
	s_nop 0
	v_pk_fma_f32 v[130:131], v[128:129], v[130:131], s[62:63] op_sel_hi:[1,1,0]
	s_nop 0
	v_pk_mul_f32 v[128:129], v[128:129], v[130:131]
	v_pk_mul_f32 v[130:131], v[116:117], v[116:117]
	v_max_f32_e32 v116, 0, v116
	v_pk_mul_f32 v[130:131], v[130:131], s[64:65] op_sel_hi:[1,0]
	v_max_f32_e32 v117, 0, v117
	v_exp_f32_e32 v130, v130
	v_exp_f32_e32 v131, v131
	s_nop 0
	v_pk_mul_f32 v[128:129], v[130:131], v[128:129]
	s_nop 0
	v_pk_fma_f32 v[116:117], v[120:121], v[128:129], v[116:117] neg_lo:[1,0,0] neg_hi:[1,0,0]
	s_nop 0
	v_mul_f32_e32 v104, v104, v116
	v_mul_f32_e32 v105, v105, v117
	v_and_b32_e32 v117, 0x7fffffff, v125
	v_and_b32_e32 v116, 0x7fffffff, v124
	v_pk_fma_f32 v[120:121], v[116:117], s[52:53], 1.0 op_sel_hi:[1,0,0]
	v_mul_f32_e32 v104, v186, v104
	v_rcp_f32_e32 v120, v120
	v_rcp_f32_e32 v121, v121
	v_mul_f32_e32 v105, v186, v105
	v_cvt_pk_bf16_f32 v104, v104, v105
	v_pk_fma_f32 v[128:129], v[120:121], s[54:55], v[246:247] op_sel_hi:[1,0,0]
	s_nop 0
	v_pk_fma_f32 v[128:129], v[120:121], v[128:129], s[58:59] op_sel_hi:[1,1,0]
	s_nop 0
	v_pk_fma_f32 v[128:129], v[120:121], v[128:129], s[60:61] op_sel_hi:[1,1,0]
	s_nop 0
	v_pk_fma_f32 v[128:129], v[120:121], v[128:129], s[62:63] op_sel_hi:[1,1,0]
	s_nop 0
	v_pk_mul_f32 v[120:121], v[120:121], v[128:129]
	v_pk_mul_f32 v[128:129], v[124:125], v[124:125]
	v_max_f32_e32 v124, 0, v124
	v_pk_mul_f32 v[128:129], v[128:129], s[64:65] op_sel_hi:[1,0]
	v_max_f32_e32 v125, 0, v125
	v_exp_f32_e32 v128, v128
	v_exp_f32_e32 v129, v129
	s_nop 0
	v_pk_mul_f32 v[120:121], v[128:129], v[120:121]
	s_nop 0
	v_pk_fma_f32 v[116:117], v[116:117], v[120:121], v[124:125] neg_lo:[1,0,0] neg_hi:[1,0,0]
	s_nop 0
	v_mul_f32_e32 v100, v100, v116
	v_mul_f32_e32 v101, v101, v117
	v_and_b32_e32 v117, 0x7fffffff, v113
	v_and_b32_e32 v116, 0x7fffffff, v112
	v_pk_fma_f32 v[120:121], v[116:117], s[52:53], 1.0 op_sel_hi:[1,0,0]
	v_mul_f32_e32 v100, v184, v100
	v_rcp_f32_e32 v120, v120
	v_rcp_f32_e32 v121, v121
	v_mul_f32_e32 v101, v184, v101
	v_cvt_pk_bf16_f32 v100, v100, v101
	v_pk_fma_f32 v[124:125], v[120:121], s[54:55], v[246:247] op_sel_hi:[1,0,0]
	s_nop 0
	v_pk_fma_f32 v[124:125], v[120:121], v[124:125], s[58:59] op_sel_hi:[1,1,0]
	s_nop 0
	v_pk_fma_f32 v[124:125], v[120:121], v[124:125], s[60:61] op_sel_hi:[1,1,0]
	s_nop 0
	v_pk_fma_f32 v[124:125], v[120:121], v[124:125], s[62:63] op_sel_hi:[1,1,0]
	s_nop 0
	v_pk_mul_f32 v[120:121], v[120:121], v[124:125]
	v_pk_mul_f32 v[124:125], v[112:113], v[112:113]
	v_max_f32_e32 v112, 0, v112
	v_pk_mul_f32 v[124:125], v[124:125], s[64:65] op_sel_hi:[1,0]
	v_max_f32_e32 v113, 0, v113
	v_exp_f32_e32 v124, v124
	v_exp_f32_e32 v125, v125
	s_nop 0
	v_pk_mul_f32 v[120:121], v[124:125], v[120:121]
	s_nop 0
	v_pk_fma_f32 v[112:113], v[116:117], v[120:121], v[112:113] neg_lo:[1,0,0] neg_hi:[1,0,0]
	v_lshl_add_u32 v120, v204, 2, s89
	v_mul_f32_e32 v96, v96, v112
	v_mul_f32_e32 v96, v180, v96
	v_mul_f32_e32 v97, v97, v113
	v_add_u32_e32 v121, 8, v120
	v_mul_f32_e32 v97, v180, v97
	v_cvt_pk_bf16_f32 v96, v96, v97
	ds_read2st64_b64 v[132:135], v121 offset0:10 offset1:11
	ds_read2st64_b64 v[128:131], v121 offset0:12 offset1:13
	s_cbranch_vccnz .LBB0_760
	ds_read_b64 v[116:117], v144 offset:1544
	v_mov_b32_e32 v112, 0
	s_and_b64 vcc, exec, s[24:25]
	v_mov_b32_e32 v113, 0
	s_cbranch_vccnz .LBB0_723

.LBB0_723:
	v_mov_b32_e32 v185, v184
	v_mov_b32_e32 v187, v186
	v_mov_b32_e32 v183, v182
	v_pk_mul_f32 v[126:127], v[126:127], v[184:185]
	v_pk_mul_f32 v[118:119], v[118:119], v[186:187]
	v_pk_mul_f32 v[114:115], v[114:115], v[182:183]
	v_mul_f32_e32 v122, v122, v180
	v_mul_f32_e32 v124, v123, v180
	v_mov_b32_dpp v105, v126 row_ror:1 row_mask:0xf bank_mask:0xf
	v_mov_b32_dpp v123, v118 row_ror:1 row_mask:0xf bank_mask:0xf
	s_waitcnt lgkmcnt(0)
	v_mov_b32_dpp v116, v114 row_shr:1 row_mask:0xf bank_mask:0xf
	v_mov_b32_dpp v138, v114 row_ror:1 row_mask:0xf bank_mask:0xf
	v_mov_b32_dpp v117, v115 row_shr:1 row_mask:0xf bank_mask:0xf
	v_mov_b32_dpp v139, v115 row_ror:1 row_mask:0xf bank_mask:0xf
	v_mov_b32_dpp v105, v122 row_shr:1 row_mask:0xf bank_mask:0xf
	v_mov_b32_dpp v136, v118 row_ror:15 row_mask:0xf bank_mask:0xf
	v_mov_b32_dpp v149, v119 row_ror:1 row_mask:0xf bank_mask:0xf
	v_mov_b32_dpp v137, v119 row_ror:15 row_mask:0xf bank_mask:0xf
	v_mov_b32_dpp v123, v126 row_shr:1 row_mask:0xf bank_mask:0xf
	v_mov_b32_dpp v138, v118 row_shr:1 row_mask:0xf bank_mask:0xf
	v_mov_b32_dpp v139, v119 row_shr:1 row_mask:0xf bank_mask:0xf
	v_cndmask_b32_e64 v116, v116, 0, s[16:17]
	v_cndmask_b32_e64 v117, v117, 0, s[16:17]
	v_mov_b32_dpp v97, v122 row_ror:15 row_mask:0xf bank_mask:0xf
	v_mov_b32_dpp v125, v127 row_ror:1 row_mask:0xf bank_mask:0xf
	v_mov_b32_dpp v149, v127 row_shr:1 row_mask:0xf bank_mask:0xf
	v_mov_b32_dpp v136, v114 row_shl:1 row_mask:0xf bank_mask:0xf
	v_mov_b32_dpp v137, v115 row_shl:1 row_mask:0xf bank_mask:0xf
	v_cndmask_b32_e64 v138, v138, 0, s[8:9]
	v_cndmask_b32_e64 v148, v123, 0, s[10:11]
	v_cndmask_b32_e64 v123, v105, 0, s[12:13]
	v_mov_b32_e32 v188, v134
	v_mov_b32_e32 v189, v132
	v_pk_mul_f32 v[116:117], v[132:133], v[116:117]
	v_cndmask_b32_e64 v139, v139, 0, s[8:9]
	v_mov_b32_dpp v112, v122 row_shl:1 row_mask:0xf bank_mask:0xf
	v_mov_b32_dpp v109, v126 row_ror:15 row_mask:0xf bank_mask:0xf
	v_mov_b32_dpp v97, v126 row_shl:1 row_mask:0xf bank_mask:0xf
	v_mov_b32_dpp v125, v124 row_shr:1 row_mask:0xf bank_mask:0xf
	v_mov_b32_dpp v145, v127 row_ror:15 row_mask:0xf bank_mask:0xf
	v_cndmask_b32_e64 v136, v136, 0, s[18:19]
	v_pk_mul_f32 v[122:123], v[122:123], v[188:189]
	v_cndmask_b32_e64 v137, v137, 0, s[18:19]
	v_pk_fma_f32 v[114:115], v[114:115], v[134:135], v[116:117]
	v_pk_mul_f32 v[116:117], v[132:133], v[138:139]
	v_cndmask_b32_e64 v149, v149, 0, s[10:11]
	v_mov_b32_dpp v109, v118 row_shl:1 row_mask:0xf bank_mask:0xf
	v_mov_b32_dpp v145, v119 row_shl:1 row_mask:0xf bank_mask:0xf
	v_cndmask_b32_e64 v150, v97, 0, s[22:23]
	v_add_f32_e32 v97, v122, v123
	v_cndmask_b32_e64 v105, v112, 0, s[14:15]
	v_pk_fma_f32 v[114:115], v[128:129], v[136:137], v[114:115]
	v_pk_fma_f32 v[116:117], v[118:119], v[134:135], v[116:117]
	v_pk_mul_f32 v[118:119], v[132:133], v[148:149]
	v_cndmask_b32_e64 v125, v125, 0, s[12:13]
	v_mov_b32_e32 v132, v135
	v_fmac_f32_e32 v97, v128, v105
	v_pk_add_f32 v[114:115], v[130:131], v[114:115]
	v_pk_mul_f32 v[122:123], v[124:125], v[132:133]
	v_add_f32_e32 v112, v130, v97
	v_add_f32_e32 v97, v122, v123
	v_and_b32_e32 v123, 0x7fffffff, v115
	v_and_b32_e32 v122, 0x7fffffff, v114
	v_mov_b32_dpp v101, v124 row_ror:15 row_mask:0xf bank_mask:0xf
	v_mov_b32_dpp v113, v124 row_shl:1 row_mask:0xf bank_mask:0xf
	v_pk_fma_f32 v[124:125], v[122:123], s[52:53], 1.0 op_sel_hi:[1,0,0]
	v_mov_b32_dpp v101, v127 row_shl:1 row_mask:0xf bank_mask:0xf
	v_rcp_f32_e32 v124, v124
	v_rcp_f32_e32 v125, v125
	v_cndmask_b32_e64 v146, v109, 0, s[20:21]
	v_cndmask_b32_e64 v147, v145, 0, s[20:21]
	v_cndmask_b32_e64 v151, v101, 0, s[22:23]
	v_pk_fma_f32 v[118:119], v[126:127], v[134:135], v[118:119]
	v_cndmask_b32_e64 v101, v113, 0, s[14:15]
	v_pk_fma_f32 v[116:117], v[128:129], v[146:147], v[116:117]
	v_pk_fma_f32 v[118:119], v[128:129], v[150:151], v[118:119]
	v_fmac_f32_e32 v97, v129, v101
	v_pk_add_f32 v[116:117], v[130:131], v[116:117]
	v_pk_add_f32 v[118:119], v[130:131], v[118:119]
	v_add_f32_e32 v113, v131, v97
	v_pk_mul_f32 v[130:131], v[114:115], v[114:115]
	v_pk_fma_f32 v[128:129], v[124:125], s[54:55], v[246:247] op_sel_hi:[1,0,0]
	v_pk_mul_f32 v[130:131], v[130:131], s[64:65] op_sel_hi:[1,0]
	v_pk_fma_f32 v[128:129], v[124:125], v[128:129], s[58:59] op_sel_hi:[1,1,0]
	v_exp_f32_e32 v130, v130
	v_exp_f32_e32 v131, v131
	v_pk_fma_f32 v[128:129], v[124:125], v[128:129], s[60:61] op_sel_hi:[1,1,0]
	v_max_f32_e32 v114, 0, v114
	v_pk_fma_f32 v[128:129], v[124:125], v[128:129], s[62:63] op_sel_hi:[1,1,0]
	v_max_f32_e32 v115, 0, v115
	v_pk_mul_f32 v[124:125], v[124:125], v[128:129]
	s_and_b64 vcc, exec, s[6:7]
	v_pk_mul_f32 v[124:125], v[130:131], v[124:125]
	s_nop 0
	v_pk_fma_f32 v[114:115], v[122:123], v[124:125], v[114:115] neg_lo:[1,0,0] neg_hi:[1,0,0]
	v_and_b32_e32 v123, 0x7fffffff, v117
	v_and_b32_e32 v122, 0x7fffffff, v116
	v_pk_fma_f32 v[124:125], v[122:123], s[52:53], 1.0 op_sel_hi:[1,0,0]
	v_mul_f32_e32 v97, v110, v114
	v_rcp_f32_e32 v124, v124
	v_rcp_f32_e32 v125, v125
	v_mul_f32_e32 v101, v111, v115
	v_pk_mul_f32 v[114:115], v[116:117], v[116:117]
	v_max_f32_e32 v116, 0, v116
	v_pk_fma_f32 v[110:111], v[124:125], s[54:55], v[246:247] op_sel_hi:[1,0,0]
	v_pk_mul_f32 v[114:115], v[114:115], s[64:65] op_sel_hi:[1,0]
	v_pk_fma_f32 v[110:111], v[124:125], v[110:111], s[58:59] op_sel_hi:[1,1,0]
	v_exp_f32_e32 v114, v114
	v_exp_f32_e32 v115, v115
	v_pk_fma_f32 v[110:111], v[124:125], v[110:111], s[60:61] op_sel_hi:[1,1,0]
	v_max_f32_e32 v117, 0, v117
	v_pk_fma_f32 v[110:111], v[124:125], v[110:111], s[62:63] op_sel_hi:[1,1,0]
	v_mul_f32_e32 v97, v182, v97
	v_pk_mul_f32 v[110:111], v[124:125], v[110:111]
	v_mul_f32_e32 v101, v182, v101
	v_pk_mul_f32 v[110:111], v[114:115], v[110:111]
	v_and_b32_e32 v115, 0x7fffffff, v119
	v_and_b32_e32 v114, 0x7fffffff, v118
	v_pk_fma_f32 v[110:111], v[122:123], v[110:111], v[116:117] neg_lo:[1,0,0] neg_hi:[1,0,0]
	v_pk_fma_f32 v[116:117], v[114:115], s[52:53], 1.0 op_sel_hi:[1,0,0]
	v_cvt_pk_bf16_f32 v109, v97, v101
	v_mul_f32_e32 v97, v106, v110
	v_rcp_f32_e32 v116, v116
	v_rcp_f32_e32 v117, v117
	v_mul_f32_e32 v101, v107, v111
	v_pk_mul_f32 v[110:111], v[118:119], v[118:119]
	v_mul_f32_e32 v97, v186, v97
	v_pk_fma_f32 v[106:107], v[116:117], s[54:55], v[246:247] op_sel_hi:[1,0,0]
	v_pk_mul_f32 v[110:111], v[110:111], s[64:65] op_sel_hi:[1,0]
	v_pk_fma_f32 v[106:107], v[116:117], v[106:107], s[58:59] op_sel_hi:[1,1,0]
	v_exp_f32_e32 v110, v110
	v_exp_f32_e32 v111, v111
	v_pk_fma_f32 v[106:107], v[116:117], v[106:107], s[60:61] op_sel_hi:[1,1,0]
	v_mul_f32_e32 v101, v186, v101
	v_pk_fma_f32 v[106:107], v[116:117], v[106:107], s[62:63] op_sel_hi:[1,1,0]
	v_cvt_pk_bf16_f32 v105, v97, v101
	v_add_u32_e32 v122, 16, v120
	v_pk_mul_f32 v[106:107], v[116:117], v[106:107]
	v_max_f32_e32 v116, 0, v118
	v_max_f32_e32 v117, 0, v119
	v_pk_mul_f32 v[106:107], v[110:111], v[106:107]
	v_and_b32_e32 v111, 0x7fffffff, v113
	v_and_b32_e32 v110, 0x7fffffff, v112
	v_pk_fma_f32 v[106:107], v[114:115], v[106:107], v[116:117] neg_lo:[1,0,0] neg_hi:[1,0,0]
	v_pk_fma_f32 v[114:115], v[110:111], s[52:53], 1.0 op_sel_hi:[1,0,0]
	v_mul_f32_e32 v97, v102, v106
	v_rcp_f32_e32 v114, v114
	v_rcp_f32_e32 v115, v115
	v_mul_f32_e32 v101, v103, v107
	v_pk_mul_f32 v[106:107], v[112:113], v[112:113]
	v_max_f32_e32 v112, 0, v112
	v_pk_fma_f32 v[102:103], v[114:115], s[54:55], v[246:247] op_sel_hi:[1,0,0]
	v_pk_mul_f32 v[106:107], v[106:107], s[64:65] op_sel_hi:[1,0]
	v_pk_fma_f32 v[102:103], v[114:115], v[102:103], s[58:59] op_sel_hi:[1,1,0]
	v_exp_f32_e32 v106, v106
	v_exp_f32_e32 v107, v107
	v_pk_fma_f32 v[102:103], v[114:115], v[102:103], s[60:61] op_sel_hi:[1,1,0]
	v_max_f32_e32 v113, 0, v113
	v_pk_fma_f32 v[102:103], v[114:115], v[102:103], s[62:63] op_sel_hi:[1,1,0]
	v_mul_f32_e32 v97, v184, v97
	v_pk_mul_f32 v[102:103], v[114:115], v[102:103]
	v_mul_f32_e32 v101, v184, v101
	v_pk_mul_f32 v[102:103], v[106:107], v[102:103]
	v_cvt_pk_bf16_f32 v101, v97, v101
	s_nop 0
	v_pk_fma_f32 v[102:103], v[110:111], v[102:103], v[112:113] neg_lo:[1,0,0] neg_hi:[1,0,0]
	s_nop 0
	v_mul_f32_e32 v97, v98, v102
	v_mul_f32_e32 v97, v180, v97
	v_mul_f32_e32 v98, v99, v103
	v_mul_f32_e32 v98, v180, v98
	v_cvt_pk_bf16_f32 v97, v97, v98
	ds_read2st64_b64 v[114:117], v122 offset0:10 offset1:11
	ds_read2st64_b64 v[110:113], v122 offset0:12 offset1:13
	s_cbranch_vccnz .LBB0_761
	ds_read_b64 v[102:103], v144 offset:1552
	v_mov_b32_e32 v98, 0
	s_and_b64 vcc, exec, s[24:25]
	v_mov_b32_e32 v99, 0
	s_cbranch_vccnz .LBB0_726

.LBB0_726:
	v_pk_mul_f32 v[80:81], v[80:81], v[182:183]
	v_pk_mul_f32 v[92:93], v[92:93], v[184:185]
	v_pk_mul_f32 v[88:89], v[88:89], v[186:187]
	s_waitcnt lgkmcnt(0)
	v_mov_b32_dpp v102, v80 row_shr:1 row_mask:0xf bank_mask:0xf
	v_mov_b32_dpp v103, v81 row_shr:1 row_mask:0xf bank_mask:0xf
	v_mov_b32_dpp v119, v92 row_ror:15 row_mask:0xf bank_mask:0xf
	v_mov_b32_dpp v125, v88 row_ror:1 row_mask:0xf bank_mask:0xf
	v_mov_b32_dpp v118, v88 row_ror:15 row_mask:0xf bank_mask:0xf
	v_mov_b32_dpp v131, v89 row_ror:15 row_mask:0xf bank_mask:0xf
	v_mov_b32_dpp v124, v80 row_ror:1 row_mask:0xf bank_mask:0xf
	v_mov_b32_dpp v135, v81 row_ror:1 row_mask:0xf bank_mask:0xf
	v_cndmask_b32_e64 v102, v102, 0, s[16:17]
	v_cndmask_b32_e64 v103, v103, 0, s[16:17]
	v_mul_f32_e32 v84, v84, v180
	v_mul_f32_e32 v106, v85, v180
	v_mov_b32_dpp v85, v92 row_ror:1 row_mask:0xf bank_mask:0xf
	v_mov_b32_dpp v129, v89 row_ror:1 row_mask:0xf bank_mask:0xf
	v_mov_b32_dpp v125, v92 row_shr:1 row_mask:0xf bank_mask:0xf
	v_mov_b32_dpp v119, v88 row_shl:1 row_mask:0xf bank_mask:0xf
	v_mov_b32_dpp v124, v88 row_shr:1 row_mask:0xf bank_mask:0xf
	v_mov_b32_dpp v118, v80 row_shl:1 row_mask:0xf bank_mask:0xf
	v_mov_b32_dpp v135, v89 row_shr:1 row_mask:0xf bank_mask:0xf
	v_mov_b32_dpp v131, v81 row_shl:1 row_mask:0xf bank_mask:0xf
	v_pk_mul_f32 v[102:103], v[114:115], v[102:103]
	v_mov_b32_dpp v107, v84 row_ror:15 row_mask:0xf bank_mask:0xf
	v_mov_b32_dpp v85, v84 row_shr:1 row_mask:0xf bank_mask:0xf
	v_mov_b32_dpp v134, v93 row_ror:1 row_mask:0xf bank_mask:0xf
	v_mov_b32_dpp v129, v93 row_shr:1 row_mask:0xf bank_mask:0xf
	v_cndmask_b32_e64 v118, v118, 0, s[18:19]
	v_cndmask_b32_e64 v124, v124, 0, s[8:9]
	v_cndmask_b32_e64 v126, v119, 0, s[20:21]
	v_cndmask_b32_e64 v128, v125, 0, s[10:11]
	v_cndmask_b32_e64 v119, v131, 0, s[18:19]
	v_pk_fma_f32 v[80:81], v[80:81], v[116:117], v[102:103]
	v_cndmask_b32_e64 v125, v135, 0, s[8:9]
	v_mov_b32_dpp v107, v92 row_shl:1 row_mask:0xf bank_mask:0xf
	v_mov_b32_dpp v134, v106 row_shr:1 row_mask:0xf bank_mask:0xf
	v_mov_b32_dpp v127, v93 row_ror:15 row_mask:0xf bank_mask:0xf
	v_cndmask_b32_e64 v85, v85, 0, s[12:13]
	v_mov_b32_e32 v132, v116
	v_mov_b32_e32 v133, v114
	v_pk_fma_f32 v[80:81], v[110:111], v[118:119], v[80:81]
	v_pk_mul_f32 v[102:103], v[114:115], v[124:125]
	v_cndmask_b32_e64 v129, v129, 0, s[10:11]
	v_mov_b32_dpp v98, v84 row_shl:1 row_mask:0xf bank_mask:0xf
	v_mov_b32_dpp v123, v106 row_ror:15 row_mask:0xf bank_mask:0xf
	v_mov_b32_dpp v99, v106 row_shl:1 row_mask:0xf bank_mask:0xf
	v_mov_b32_dpp v127, v89 row_shl:1 row_mask:0xf bank_mask:0xf
	v_cndmask_b32_e64 v130, v107, 0, s[22:23]
	v_pk_mul_f32 v[84:85], v[84:85], v[132:133]
	v_pk_add_f32 v[80:81], v[112:113], v[80:81]
	v_pk_fma_f32 v[88:89], v[88:89], v[116:117], v[102:103]
	v_pk_mul_f32 v[102:103], v[114:115], v[128:129]
	v_cndmask_b32_e64 v107, v134, 0, s[12:13]
	v_mov_b32_e32 v114, v117
	v_mov_b32_dpp v123, v93 row_shl:1 row_mask:0xf bank_mask:0xf
	v_add_f32_e32 v84, v84, v85
	v_cndmask_b32_e64 v85, v98, 0, s[14:15]
	v_pk_fma_f32 v[92:93], v[92:93], v[116:117], v[102:103]
	v_pk_mul_f32 v[102:103], v[106:107], v[114:115]
	v_cndmask_b32_e64 v106, v99, 0, s[14:15]
	v_and_b32_e32 v99, 0x7fffffff, v81
	v_and_b32_e32 v98, 0x7fffffff, v80
	v_fmac_f32_e32 v84, v110, v85
	v_add_f32_e32 v85, v102, v103
	v_pk_fma_f32 v[102:103], v[98:99], s[52:53], 1.0 op_sel_hi:[1,0,0]
	v_cndmask_b32_e64 v127, v127, 0, s[20:21]
	v_rcp_f32_e32 v102, v102
	v_rcp_f32_e32 v103, v103
	v_cndmask_b32_e64 v131, v123, 0, s[22:23]
	v_pk_fma_f32 v[88:89], v[110:111], v[126:127], v[88:89]
	v_pk_fma_f32 v[92:93], v[110:111], v[130:131], v[92:93]
	v_fmac_f32_e32 v85, v111, v106
	v_add_f32_e32 v84, v112, v84
	v_pk_add_f32 v[88:89], v[112:113], v[88:89]
	v_pk_add_f32 v[92:93], v[112:113], v[92:93]
	v_add_f32_e32 v85, v113, v85
	v_pk_mul_f32 v[110:111], v[80:81], v[80:81]
	v_pk_fma_f32 v[106:107], v[102:103], s[54:55], v[246:247] op_sel_hi:[1,0,0]
	v_pk_mul_f32 v[110:111], v[110:111], s[64:65] op_sel_hi:[1,0]
	v_pk_fma_f32 v[106:107], v[102:103], v[106:107], s[58:59] op_sel_hi:[1,1,0]
	v_exp_f32_e32 v110, v110
	v_exp_f32_e32 v111, v111
	v_pk_fma_f32 v[106:107], v[102:103], v[106:107], s[60:61] op_sel_hi:[1,1,0]
	v_max_f32_e32 v80, 0, v80
	v_pk_fma_f32 v[106:107], v[102:103], v[106:107], s[62:63] op_sel_hi:[1,1,0]
	v_max_f32_e32 v81, 0, v81
	v_pk_mul_f32 v[102:103], v[102:103], v[106:107]
	s_and_b64 vcc, exec, s[6:7]
	v_pk_mul_f32 v[102:103], v[110:111], v[102:103]
	s_nop 0
	v_pk_fma_f32 v[80:81], v[98:99], v[102:103], v[80:81] neg_lo:[1,0,0] neg_hi:[1,0,0]
	v_and_b32_e32 v99, 0x7fffffff, v89
	v_and_b32_e32 v98, 0x7fffffff, v88
	v_pk_fma_f32 v[102:103], v[98:99], s[52:53], 1.0 op_sel_hi:[1,0,0]
	v_mul_f32_e32 v76, v76, v80
	v_rcp_f32_e32 v102, v102
	v_rcp_f32_e32 v103, v103
	v_mul_f32_e32 v77, v77, v81
	v_mul_f32_e32 v76, v182, v76
	v_mul_f32_e32 v77, v182, v77
	v_pk_mul_f32 v[80:81], v[88:89], v[88:89]
	v_cvt_pk_bf16_f32 v110, v76, v77
	v_pk_fma_f32 v[76:77], v[102:103], s[54:55], v[246:247] op_sel_hi:[1,0,0]
	v_pk_mul_f32 v[80:81], v[80:81], s[64:65] op_sel_hi:[1,0]
	v_pk_fma_f32 v[76:77], v[102:103], v[76:77], s[58:59] op_sel_hi:[1,1,0]
	v_exp_f32_e32 v80, v80
	v_exp_f32_e32 v81, v81
	v_pk_fma_f32 v[76:77], v[102:103], v[76:77], s[60:61] op_sel_hi:[1,1,0]
	v_max_f32_e32 v88, 0, v88
	v_pk_fma_f32 v[76:77], v[102:103], v[76:77], s[62:63] op_sel_hi:[1,1,0]
	v_max_f32_e32 v89, 0, v89
	v_pk_mul_f32 v[76:77], v[102:103], v[76:77]
	s_nop 0
	v_pk_mul_f32 v[76:77], v[80:81], v[76:77]
	v_and_b32_e32 v81, 0x7fffffff, v93
	v_and_b32_e32 v80, 0x7fffffff, v92
	v_pk_fma_f32 v[76:77], v[98:99], v[76:77], v[88:89] neg_lo:[1,0,0] neg_hi:[1,0,0]
	v_pk_fma_f32 v[88:89], v[80:81], s[52:53], 1.0 op_sel_hi:[1,0,0]
	v_mul_f32_e32 v72, v72, v76
	v_rcp_f32_e32 v88, v88
	v_rcp_f32_e32 v89, v89
	v_mul_f32_e32 v73, v73, v77
	v_mul_f32_e32 v72, v186, v72
	v_mul_f32_e32 v73, v186, v73
	v_pk_mul_f32 v[76:77], v[92:93], v[92:93]
	v_cvt_pk_bf16_f32 v106, v72, v73
	v_pk_fma_f32 v[72:73], v[88:89], s[54:55], v[246:247] op_sel_hi:[1,0,0]
	v_pk_mul_f32 v[76:77], v[76:77], s[64:65] op_sel_hi:[1,0]
	v_pk_fma_f32 v[72:73], v[88:89], v[72:73], s[58:59] op_sel_hi:[1,1,0]
	v_exp_f32_e32 v76, v76
	v_exp_f32_e32 v77, v77
	v_pk_fma_f32 v[72:73], v[88:89], v[72:73], s[60:61] op_sel_hi:[1,1,0]
	s_nop 0
	v_pk_fma_f32 v[72:73], v[88:89], v[72:73], s[62:63] op_sel_hi:[1,1,0]
	s_nop 0
	v_pk_mul_f32 v[72:73], v[88:89], v[72:73]
	v_max_f32_e32 v88, 0, v92
	v_max_f32_e32 v89, 0, v93
	v_pk_mul_f32 v[72:73], v[76:77], v[72:73]
	v_and_b32_e32 v77, 0x7fffffff, v85
	v_and_b32_e32 v76, 0x7fffffff, v84
	v_pk_fma_f32 v[72:73], v[80:81], v[72:73], v[88:89] neg_lo:[1,0,0] neg_hi:[1,0,0]
	v_pk_fma_f32 v[80:81], v[76:77], s[52:53], 1.0 op_sel_hi:[1,0,0]
	v_mul_f32_e32 v68, v68, v72
	v_rcp_f32_e32 v80, v80
	v_rcp_f32_e32 v81, v81
	v_mul_f32_e32 v69, v69, v73
	v_mul_f32_e32 v68, v184, v68
	v_mul_f32_e32 v69, v184, v69
	v_pk_mul_f32 v[72:73], v[84:85], v[84:85]
	v_cvt_pk_bf16_f32 v102, v68, v69
	v_pk_fma_f32 v[68:69], v[80:81], s[54:55], v[246:247] op_sel_hi:[1,0,0]
	v_pk_mul_f32 v[72:73], v[72:73], s[64:65] op_sel_hi:[1,0]
	v_pk_fma_f32 v[68:69], v[80:81], v[68:69], s[58:59] op_sel_hi:[1,1,0]
	v_exp_f32_e32 v72, v72
	v_exp_f32_e32 v73, v73
	v_pk_fma_f32 v[68:69], v[80:81], v[68:69], s[60:61] op_sel_hi:[1,1,0]
	s_nop 0
	v_pk_fma_f32 v[68:69], v[80:81], v[68:69], s[62:63] op_sel_hi:[1,1,0]
	s_nop 0
	v_pk_mul_f32 v[68:69], v[80:81], v[68:69]
	v_max_f32_e32 v80, 0, v84
	v_max_f32_e32 v81, 0, v85
	v_pk_mul_f32 v[68:69], v[72:73], v[68:69]
	s_nop 0
	v_pk_fma_f32 v[68:69], v[76:77], v[68:69], v[80:81] neg_lo:[1,0,0] neg_hi:[1,0,0]
	v_add_u32_e32 v76, 24, v120
	v_pk_mul_f32 v[68:69], v[64:65], v[68:69]
	v_pk_mul_f32 v[68:69], v[180:181], v[68:69] op_sel_hi:[0,1]
	v_cvt_pk_bf16_f32 v98, v68, v69
	ds_read2st64_b64 v[116:119], v76 offset0:10 offset1:11
	ds_read2st64_b64 v[112:115], v76 offset0:12 offset1:13
	s_cbranch_vccnz .LBB0_762
	ds_read_b64 v[68:69], v144 offset:1560
	v_mov_b32_e32 v64, 0
	s_and_b64 vcc, exec, s[24:25]
	v_mov_b32_e32 v65, 0
	s_cbranch_vccnz .LBB0_729

.LBB0_729:
	v_mul_f32_e32 v72, v86, v180
	v_pk_mul_f32 v[84:85], v[94:95], v[184:185]
	v_pk_mul_f32 v[82:83], v[82:83], v[182:183]
	v_mov_b32_dpp v73, v72 row_ror:15 row_mask:0xf bank_mask:0xf
	v_mov_b32_dpp v81, v84 row_ror:1 row_mask:0xf bank_mask:0xf
	v_mul_f32_e32 v80, v87, v180
	v_mov_b32_dpp v73, v84 row_shl:1 row_mask:0xf bank_mask:0xf
	v_mov_b32_dpp v81, v72 row_shr:1 row_mask:0xf bank_mask:0xf
	v_pk_mul_f32 v[86:87], v[90:91], v[186:187]
	s_waitcnt lgkmcnt(0)
	v_mov_b32_dpp v68, v82 row_shr:1 row_mask:0xf bank_mask:0xf
	v_mov_b32_dpp v69, v83 row_shr:1 row_mask:0xf bank_mask:0xf
	v_cndmask_b32_e64 v124, v73, 0, s[22:23]
	v_cndmask_b32_e64 v73, v81, 0, s[12:13]
	v_mov_b32_e32 v126, v118
	v_mov_b32_e32 v127, v116
	v_mov_b32_dpp v64, v72 row_shl:1 row_mask:0xf bank_mask:0xf
	v_mov_b32_dpp v89, v84 row_ror:15 row_mask:0xf bank_mask:0xf
	v_mov_b32_dpp v91, v86 row_ror:1 row_mask:0xf bank_mask:0xf
	v_mov_b32_dpp v88, v86 row_ror:15 row_mask:0xf bank_mask:0xf
	v_mov_b32_dpp v95, v87 row_ror:1 row_mask:0xf bank_mask:0xf
	v_mov_b32_dpp v103, v87 row_ror:15 row_mask:0xf bank_mask:0xf
	v_mov_b32_dpp v90, v82 row_ror:1 row_mask:0xf bank_mask:0xf
	v_mov_b32_dpp v107, v83 row_ror:1 row_mask:0xf bank_mask:0xf
	v_cndmask_b32_e64 v68, v68, 0, s[16:17]
	v_pk_mul_f32 v[72:73], v[72:73], v[126:127]
	v_cndmask_b32_e64 v69, v69, 0, s[16:17]
	v_mov_b32_dpp v99, v85 row_ror:1 row_mask:0xf bank_mask:0xf
	v_mov_b32_dpp v91, v84 row_shr:1 row_mask:0xf bank_mask:0xf
	v_mov_b32_dpp v89, v86 row_shl:1 row_mask:0xf bank_mask:0xf
	v_mov_b32_dpp v95, v85 row_shr:1 row_mask:0xf bank_mask:0xf
	v_mov_b32_dpp v90, v86 row_shr:1 row_mask:0xf bank_mask:0xf
	v_mov_b32_dpp v88, v82 row_shl:1 row_mask:0xf bank_mask:0xf
	v_mov_b32_dpp v107, v87 row_shr:1 row_mask:0xf bank_mask:0xf
	v_mov_b32_dpp v103, v83 row_shl:1 row_mask:0xf bank_mask:0xf
	v_add_f32_e32 v72, v72, v73
	v_cndmask_b32_e64 v64, v64, 0, s[14:15]
	v_pk_mul_f32 v[68:69], v[116:117], v[68:69]
	v_mov_b32_dpp v99, v80 row_shr:1 row_mask:0xf bank_mask:0xf
	v_cndmask_b32_e64 v88, v88, 0, s[18:19]
	v_cndmask_b32_e64 v90, v90, 0, s[8:9]
	v_cndmask_b32_e64 v92, v89, 0, s[20:21]
	v_cndmask_b32_e64 v94, v91, 0, s[10:11]
	v_fmac_f32_e32 v72, v112, v64
	v_cndmask_b32_e64 v89, v103, 0, s[18:19]
	v_pk_fma_f32 v[68:69], v[82:83], v[118:119], v[68:69]
	v_cndmask_b32_e64 v91, v107, 0, s[8:9]
	v_cndmask_b32_e64 v95, v95, 0, s[10:11]
	v_mov_b32_dpp v77, v80 row_ror:15 row_mask:0xf bank_mask:0xf
	v_add_f32_e32 v64, v114, v72
	v_pk_fma_f32 v[68:69], v[112:113], v[88:89], v[68:69]
	v_pk_mul_f32 v[72:73], v[116:117], v[90:91]
	v_pk_mul_f32 v[82:83], v[116:117], v[94:95]
	v_cndmask_b32_e64 v81, v99, 0, s[12:13]
	v_mov_b32_e32 v116, v119
	v_mov_b32_dpp v65, v80 row_shl:1 row_mask:0xf bank_mask:0xf
	v_mov_b32_dpp v77, v85 row_shl:1 row_mask:0xf bank_mask:0xf
	v_pk_add_f32 v[68:69], v[114:115], v[68:69]
	v_pk_mul_f32 v[80:81], v[80:81], v[116:117]
	v_cndmask_b32_e64 v125, v77, 0, s[22:23]
	v_add_f32_e32 v77, v80, v81
	v_and_b32_e32 v81, 0x7fffffff, v69
	v_and_b32_e32 v80, 0x7fffffff, v68
	v_mov_b32_dpp v93, v85 row_ror:15 row_mask:0xf bank_mask:0xf
	v_pk_fma_f32 v[82:83], v[84:85], v[118:119], v[82:83]
	v_pk_fma_f32 v[84:85], v[80:81], s[52:53], 1.0 op_sel_hi:[1,0,0]
	v_mov_b32_dpp v93, v87 row_shl:1 row_mask:0xf bank_mask:0xf
	v_rcp_f32_e32 v84, v84
	v_rcp_f32_e32 v85, v85
	v_pk_fma_f32 v[72:73], v[86:87], v[118:119], v[72:73]
	v_pk_mul_f32 v[90:91], v[68:69], v[68:69]
	v_pk_fma_f32 v[88:89], v[84:85], s[54:55], v[246:247] op_sel_hi:[1,0,0]
	v_pk_mul_f32 v[90:91], v[90:91], s[64:65] op_sel_hi:[1,0]
	v_pk_fma_f32 v[88:89], v[84:85], v[88:89], s[58:59] op_sel_hi:[1,1,0]
	v_exp_f32_e32 v90, v90
	v_exp_f32_e32 v91, v91
	v_pk_fma_f32 v[88:89], v[84:85], v[88:89], s[60:61] op_sel_hi:[1,1,0]
	v_cndmask_b32_e64 v93, v93, 0, s[20:21]
	v_pk_fma_f32 v[88:89], v[84:85], v[88:89], s[62:63] op_sel_hi:[1,1,0]
	v_pk_fma_f32 v[72:73], v[112:113], v[92:93], v[72:73]
	v_pk_mul_f32 v[84:85], v[84:85], v[88:89]
	v_pk_add_f32 v[72:73], v[114:115], v[72:73]
	v_max_f32_e32 v68, 0, v68
	v_max_f32_e32 v69, 0, v69
	v_pk_mul_f32 v[84:85], v[90:91], v[84:85]
	v_pk_fma_f32 v[82:83], v[112:113], v[124:125], v[82:83]
	v_pk_fma_f32 v[68:69], v[80:81], v[84:85], v[68:69] neg_lo:[1,0,0] neg_hi:[1,0,0]
	v_and_b32_e32 v81, 0x7fffffff, v73
	v_and_b32_e32 v80, 0x7fffffff, v72
	v_pk_fma_f32 v[84:85], v[80:81], s[52:53], 1.0 op_sel_hi:[1,0,0]
	v_rcp_f32_e32 v84, v84
	v_rcp_f32_e32 v85, v85
	v_pk_mul_f32 v[68:69], v[78:79], v[68:69]
	v_pk_mul_f32 v[68:69], v[182:183], v[68:69] op_sel_hi:[0,1]
	v_pk_mul_f32 v[78:79], v[72:73], v[72:73]
	v_cvt_pk_bf16_f32 v111, v68, v69
	v_pk_fma_f32 v[68:69], v[84:85], s[54:55], v[246:247] op_sel_hi:[1,0,0]
	v_pk_mul_f32 v[78:79], v[78:79], s[64:65] op_sel_hi:[1,0]
	v_pk_fma_f32 v[68:69], v[84:85], v[68:69], s[58:59] op_sel_hi:[1,1,0]
	v_exp_f32_e32 v78, v78
	v_exp_f32_e32 v79, v79
	v_pk_fma_f32 v[68:69], v[84:85], v[68:69], s[60:61] op_sel_hi:[1,1,0]
	v_pk_add_f32 v[82:83], v[114:115], v[82:83]
	v_pk_fma_f32 v[68:69], v[84:85], v[68:69], s[62:63] op_sel_hi:[1,1,0]
	v_max_f32_e32 v72, 0, v72
	v_pk_mul_f32 v[68:69], v[84:85], v[68:69]
	v_max_f32_e32 v73, 0, v73
	v_pk_mul_f32 v[68:69], v[78:79], v[68:69]
	v_cndmask_b32_e64 v65, v65, 0, s[14:15]
	v_pk_fma_f32 v[68:69], v[80:81], v[68:69], v[72:73] neg_lo:[1,0,0] neg_hi:[1,0,0]
	v_and_b32_e32 v73, 0x7fffffff, v83
	v_and_b32_e32 v72, 0x7fffffff, v82
	v_pk_fma_f32 v[78:79], v[72:73], s[52:53], 1.0 op_sel_hi:[1,0,0]
	v_rcp_f32_e32 v78, v78
	v_rcp_f32_e32 v79, v79
	v_pk_mul_f32 v[68:69], v[74:75], v[68:69]
	v_pk_mul_f32 v[68:69], v[186:187], v[68:69] op_sel_hi:[0,1]
	v_pk_mul_f32 v[74:75], v[82:83], v[82:83]
	v_cvt_pk_bf16_f32 v107, v68, v69
	v_pk_fma_f32 v[68:69], v[78:79], s[54:55], v[246:247] op_sel_hi:[1,0,0]
	v_pk_mul_f32 v[74:75], v[74:75], s[64:65] op_sel_hi:[1,0]
	v_pk_fma_f32 v[68:69], v[78:79], v[68:69], s[58:59] op_sel_hi:[1,1,0]
	v_exp_f32_e32 v74, v74
	v_exp_f32_e32 v75, v75
	v_pk_fma_f32 v[68:69], v[78:79], v[68:69], s[60:61] op_sel_hi:[1,1,0]
	v_fmac_f32_e32 v77, v113, v65
	v_pk_fma_f32 v[68:69], v[78:79], v[68:69], s[62:63] op_sel_hi:[1,1,0]
	v_add_f32_e32 v65, v115, v77
	v_pk_mul_f32 v[68:69], v[78:79], v[68:69]
	v_max_f32_e32 v78, 0, v82
	v_max_f32_e32 v79, 0, v83
	v_pk_mul_f32 v[68:69], v[74:75], v[68:69]
	v_cmp_gt_i32_e64 s[6:7], s78, v203
	v_pk_fma_f32 v[68:69], v[72:73], v[68:69], v[78:79] neg_lo:[1,0,0] neg_hi:[1,0,0]
	v_and_b32_e32 v73, 0x7fffffff, v65
	v_and_b32_e32 v72, 0x7fffffff, v64
	v_pk_fma_f32 v[74:75], v[72:73], s[52:53], 1.0 op_sel_hi:[1,0,0]
	v_rcp_f32_e32 v74, v74
	v_rcp_f32_e32 v75, v75
	v_pk_mul_f32 v[68:69], v[70:71], v[68:69]
	v_pk_mul_f32 v[68:69], v[184:185], v[68:69] op_sel_hi:[0,1]
	v_pk_mul_f32 v[70:71], v[64:65], v[64:65]
	v_cvt_pk_bf16_f32 v103, v68, v69
	v_pk_fma_f32 v[68:69], v[74:75], s[54:55], v[246:247] op_sel_hi:[1,0,0]
	v_pk_mul_f32 v[70:71], v[70:71], s[64:65] op_sel_hi:[1,0]
	v_pk_fma_f32 v[68:69], v[74:75], v[68:69], s[58:59] op_sel_hi:[1,1,0]
	v_exp_f32_e32 v70, v70
	v_exp_f32_e32 v71, v71
	v_pk_fma_f32 v[68:69], v[74:75], v[68:69], s[60:61] op_sel_hi:[1,1,0]
	v_max_f32_e32 v64, 0, v64
	v_pk_fma_f32 v[68:69], v[74:75], v[68:69], s[62:63] op_sel_hi:[1,1,0]
	v_max_f32_e32 v65, 0, v65
	v_pk_mul_f32 v[68:69], v[74:75], v[68:69]
	v_ashrrev_i32_e32 v175, 31, v174
	v_pk_mul_f32 v[68:69], v[70:71], v[68:69]
	s_nop 0
	v_pk_fma_f32 v[64:65], v[72:73], v[68:69], v[64:65] neg_lo:[1,0,0] neg_hi:[1,0,0]
	s_nop 0
	v_mul_f32_e32 v64, v66, v64
	v_mul_f32_e32 v64, v180, v64
	v_mul_f32_e32 v65, v67, v65
	v_mul_f32_e32 v65, v180, v65
	v_cvt_pk_bf16_f32 v99, v64, v65
	v_add_u32_e32 v64, -1, v202
	v_cmp_gt_u32_e32 vcc, s76, v64
	s_and_b64 s[8:9], vcc, s[6:7]
	s_and_saveexec_b64 s[6:7], s[8:9]
	s_cbranch_execz .LBB0_731
	v_mov_b64_e32 v[64:65], s[38:39]
	v_mad_i64_i32 v[64:65], s[8:9], v203, s31, v[64:65]
	v_lshl_add_u64 v[64:65], v[174:175], 1, v[64:65]
	global_store_dwordx4 v[64:65], v[108:111], off

.LBB0_741:
	v_add_u32_e32 v77, s86, v201
	v_add_u32_e32 v78, s29, v77
	v_sub_u32_e32 v80, 0x1fef, v78
	v_and_b32_e32 v80, 0x1fff, v80
	v_cmp_eq_u32_e64 s[18:19], 0, v80
	v_sub_u32_e32 v80, 0x1fdf, v78
	v_and_b32_e32 v80, 0x1fff, v80
	v_pk_mul_f32 v[60:61], v[60:61], v[176:177] op_sel_hi:[1,0]
	v_pk_mul_f32 v[52:53], v[52:53], v[178:179] op_sel_hi:[1,0]
	v_pk_mul_f32 v[82:83], v[48:49], v[172:173] op_sel_hi:[1,0]
	v_and_b32_e32 v79, 0x1fff, v78
	v_cmp_eq_u32_e64 s[20:21], 0, v80
	v_mul_f32_e32 v56, v56, v170
	v_mul_f32_e32 v80, v57, v170
	v_mov_b32_dpp v57, v60 row_ror:1 row_mask:0xf bank_mask:0xf
	v_mov_b32_dpp v87, v52 row_ror:1 row_mask:0xf bank_mask:0xf
	v_mov_b32_dpp v48, v82 row_ror:1 row_mask:0xf bank_mask:0xf
	v_mov_b32_dpp v95, v83 row_ror:1 row_mask:0xf bank_mask:0xf
	v_cmp_eq_u32_e64 s[14:15], 0, v79
	v_cmp_eq_u32_e64 s[16:17], s80, v79
	v_cmp_eq_u32_e64 s[6:7], s81, v79
	v_cmp_eq_u32_e64 s[8:9], s26, v79
	v_cmp_eq_u32_e64 s[10:11], s27, v79
	v_sub_u32_e32 v79, 0x1fcf, v78
	v_mov_b32_dpp v57, v56 row_shr:1 row_mask:0xf bank_mask:0xf
	v_mov_b32_dpp v91, v53 row_ror:1 row_mask:0xf bank_mask:0xf
	v_mov_b32_dpp v87, v60 row_shr:1 row_mask:0xf bank_mask:0xf
	s_waitcnt lgkmcnt(0)
	v_mov_b32_dpp v74, v82 row_shr:1 row_mask:0xf bank_mask:0xf
	v_mov_b32_dpp v75, v83 row_shr:1 row_mask:0xf bank_mask:0xf
	v_mov_b32_dpp v48, v52 row_shr:1 row_mask:0xf bank_mask:0xf
	v_mov_b32_dpp v95, v53 row_shr:1 row_mask:0xf bank_mask:0xf
	v_and_b32_e32 v79, 0x1fff, v79
	v_mov_b32_dpp v81, v80 row_ror:15 row_mask:0xf bank_mask:0xf
	v_mov_b32_dpp v85, v60 row_ror:15 row_mask:0xf bank_mask:0xf
	v_mov_b32_dpp v94, v61 row_ror:1 row_mask:0xf bank_mask:0xf
	v_mov_b32_dpp v84, v52 row_ror:15 row_mask:0xf bank_mask:0xf
	v_mov_b32_dpp v93, v53 row_ror:15 row_mask:0xf bank_mask:0xf
	v_mov_b32_dpp v91, v61 row_shr:1 row_mask:0xf bank_mask:0xf
	v_cndmask_b32_e64 v74, v74, 0, s[14:15]
	v_cndmask_b32_e64 v86, v48, 0, s[6:7]
	v_cndmask_b32_e64 v90, v87, 0, s[8:9]
	v_cndmask_b32_e64 v57, v57, 0, s[10:11]
	v_mov_b32_e32 v48, v70
	v_mov_b32_e32 v49, v68
	v_cndmask_b32_e64 v75, v75, 0, s[14:15]
	v_cndmask_b32_e64 v87, v95, 0, s[6:7]
	v_cmp_eq_u32_e64 s[12:13], 0, v79
	v_mov_b32_dpp v79, v56 row_ror:15 row_mask:0xf bank_mask:0xf
	v_mov_b32_dpp v72, v56 row_shl:1 row_mask:0xf bank_mask:0xf
	v_mov_b32_dpp v94, v80 row_shr:1 row_mask:0xf bank_mask:0xf
	v_mov_b32_dpp v89, v61 row_ror:15 row_mask:0xf bank_mask:0xf
	v_mov_b32_dpp v81, v61 row_shl:1 row_mask:0xf bank_mask:0xf
	v_mov_b32_dpp v85, v52 row_shl:1 row_mask:0xf bank_mask:0xf
	v_mov_b32_dpp v84, v82 row_shl:1 row_mask:0xf bank_mask:0xf
	v_mov_b32_dpp v93, v83 row_shl:1 row_mask:0xf bank_mask:0xf
	v_pk_mul_f32 v[48:49], v[56:57], v[48:49]
	v_pk_mul_f32 v[56:57], v[68:69], v[74:75]
	v_pk_mul_f32 v[74:75], v[68:69], v[86:87]
	v_cndmask_b32_e64 v91, v91, 0, s[8:9]
	v_mov_b32_dpp v79, v60 row_shl:1 row_mask:0xf bank_mask:0xf
	v_mov_b32_dpp v89, v53 row_shl:1 row_mask:0xf bank_mask:0xf
	v_cndmask_b32_e64 v84, v84, 0, s[16:17]
	v_cndmask_b32_e64 v88, v85, 0, s[18:19]
	v_cndmask_b32_e64 v85, v93, 0, s[16:17]
	v_pk_fma_f32 v[56:57], v[82:83], v[70:71], v[56:57]
	v_pk_fma_f32 v[52:53], v[52:53], v[70:71], v[74:75]
	v_cndmask_b32_e64 v93, v81, 0, s[20:21]
	v_pk_mul_f32 v[74:75], v[68:69], v[90:91]
	v_cndmask_b32_e64 v81, v94, 0, s[10:11]
	v_mov_b32_e32 v68, v71
	v_mov_b32_dpp v73, v80 row_shl:1 row_mask:0xf bank_mask:0xf
	v_cndmask_b32_e64 v92, v79, 0, s[20:21]
	v_add_f32_e32 v48, v48, v49
	v_cndmask_b32_e64 v49, v72, 0, s[12:13]
	v_pk_fma_f32 v[56:57], v[64:65], v[84:85], v[56:57]
	v_cndmask_b32_e64 v89, v89, 0, s[18:19]
	v_pk_fma_f32 v[60:61], v[60:61], v[70:71], v[74:75]
	v_pk_mul_f32 v[68:69], v[80:81], v[68:69]
	v_fmac_f32_e32 v48, v64, v49
	v_pk_add_f32 v[56:57], v[66:67], v[56:57]
	v_pk_fma_f32 v[52:53], v[64:65], v[88:89], v[52:53]
	v_pk_fma_f32 v[60:61], v[64:65], v[92:93], v[60:61]
	v_add_f32_e32 v49, v68, v69
	v_cndmask_b32_e64 v64, v73, 0, s[12:13]
	v_fmac_f32_e32 v49, v65, v64
	v_and_b32_e32 v65, 0x7fffffff, v57
	v_and_b32_e32 v64, 0x7fffffff, v56
	v_add_f32_e32 v48, v66, v48
	v_pk_add_f32 v[52:53], v[66:67], v[52:53]
	v_pk_add_f32 v[60:61], v[66:67], v[60:61]
	v_add_f32_e32 v49, v67, v49
	v_pk_fma_f32 v[66:67], v[64:65], s[52:53], 1.0 op_sel_hi:[1,0,0]
	v_rcp_f32_e32 v66, v66
	v_rcp_f32_e32 v67, v67
	s_and_b64 vcc, exec, s[22:23]
	v_pk_fma_f32 v[70:71], v[66:67], s[54:55], v[246:247] op_sel_hi:[1,0,0]
	s_nop 0
	v_pk_fma_f32 v[70:71], v[66:67], v[70:71], s[58:59] op_sel_hi:[1,1,0]
	s_nop 0
	v_pk_fma_f32 v[70:71], v[66:67], v[70:71], s[60:61] op_sel_hi:[1,1,0]
	s_nop 0
	v_pk_fma_f32 v[70:71], v[66:67], v[70:71], s[62:63] op_sel_hi:[1,1,0]
	s_nop 0
	v_pk_mul_f32 v[66:67], v[66:67], v[70:71]
	v_pk_mul_f32 v[70:71], v[56:57], v[56:57]
	v_max_f32_e32 v56, 0, v56
	v_pk_mul_f32 v[70:71], v[70:71], s[64:65] op_sel_hi:[1,0]
	v_max_f32_e32 v57, 0, v57
	v_exp_f32_e32 v70, v70
	v_exp_f32_e32 v71, v71
	s_nop 0
	v_pk_mul_f32 v[66:67], v[70:71], v[66:67]
	s_nop 0
	v_pk_fma_f32 v[56:57], v[64:65], v[66:67], v[56:57] neg_lo:[1,0,0] neg_hi:[1,0,0]
	s_nop 0
	v_mul_f32_e32 v44, v44, v56
	v_mul_f32_e32 v45, v45, v57
	v_and_b32_e32 v57, 0x7fffffff, v53
	v_and_b32_e32 v56, 0x7fffffff, v52
	v_pk_fma_f32 v[64:65], v[56:57], s[52:53], 1.0 op_sel_hi:[1,0,0]
	v_mul_f32_e32 v44, v172, v44
	v_rcp_f32_e32 v64, v64
	v_rcp_f32_e32 v65, v65
	v_mul_f32_e32 v45, v172, v45
	v_cvt_pk_bf16_f32 v44, v44, v45
	v_pk_fma_f32 v[66:67], v[64:65], s[54:55], v[246:247] op_sel_hi:[1,0,0]
	s_nop 0
	v_pk_fma_f32 v[66:67], v[64:65], v[66:67], s[58:59] op_sel_hi:[1,1,0]
	s_nop 0
	v_pk_fma_f32 v[66:67], v[64:65], v[66:67], s[60:61] op_sel_hi:[1,1,0]
	s_nop 0
	v_pk_fma_f32 v[66:67], v[64:65], v[66:67], s[62:63] op_sel_hi:[1,1,0]
	s_nop 0
	v_pk_mul_f32 v[64:65], v[64:65], v[66:67]
	v_pk_mul_f32 v[66:67], v[52:53], v[52:53]
	v_max_f32_e32 v52, 0, v52
	v_pk_mul_f32 v[66:67], v[66:67], s[64:65] op_sel_hi:[1,0]
	v_max_f32_e32 v53, 0, v53
	v_exp_f32_e32 v66, v66
	v_exp_f32_e32 v67, v67
	s_nop 0
	v_pk_mul_f32 v[64:65], v[66:67], v[64:65]
	s_nop 0
	v_pk_fma_f32 v[52:53], v[56:57], v[64:65], v[52:53] neg_lo:[1,0,0] neg_hi:[1,0,0]
	s_nop 0
	v_mul_f32_e32 v40, v40, v52
	v_mul_f32_e32 v41, v41, v53
	v_and_b32_e32 v53, 0x7fffffff, v61
	v_and_b32_e32 v52, 0x7fffffff, v60
	v_pk_fma_f32 v[56:57], v[52:53], s[52:53], 1.0 op_sel_hi:[1,0,0]
	v_mul_f32_e32 v40, v178, v40
	v_rcp_f32_e32 v56, v56
	v_rcp_f32_e32 v57, v57
	v_mul_f32_e32 v41, v178, v41
	v_cvt_pk_bf16_f32 v40, v40, v41
	v_pk_fma_f32 v[64:65], v[56:57], s[54:55], v[246:247] op_sel_hi:[1,0,0]
	s_nop 0
	v_pk_fma_f32 v[64:65], v[56:57], v[64:65], s[58:59] op_sel_hi:[1,1,0]
	s_nop 0
	v_pk_fma_f32 v[64:65], v[56:57], v[64:65], s[60:61] op_sel_hi:[1,1,0]
	s_nop 0
	v_pk_fma_f32 v[64:65], v[56:57], v[64:65], s[62:63] op_sel_hi:[1,1,0]
	s_nop 0
	v_pk_mul_f32 v[56:57], v[56:57], v[64:65]
	v_pk_mul_f32 v[64:65], v[60:61], v[60:61]
	v_max_f32_e32 v60, 0, v60
	v_pk_mul_f32 v[64:65], v[64:65], s[64:65] op_sel_hi:[1,0]
	v_max_f32_e32 v61, 0, v61
	v_exp_f32_e32 v64, v64
	v_exp_f32_e32 v65, v65
	s_nop 0
	v_pk_mul_f32 v[56:57], v[64:65], v[56:57]
	s_nop 0
	v_pk_fma_f32 v[52:53], v[52:53], v[56:57], v[60:61] neg_lo:[1,0,0] neg_hi:[1,0,0]
	s_nop 0
	v_mul_f32_e32 v36, v36, v52
	v_mul_f32_e32 v37, v37, v53
	v_and_b32_e32 v53, 0x7fffffff, v49
	v_and_b32_e32 v52, 0x7fffffff, v48
	v_pk_fma_f32 v[56:57], v[52:53], s[52:53], 1.0 op_sel_hi:[1,0,0]
	v_mul_f32_e32 v36, v176, v36
	v_rcp_f32_e32 v56, v56
	v_rcp_f32_e32 v57, v57
	v_mul_f32_e32 v37, v176, v37
	v_cvt_pk_bf16_f32 v36, v36, v37
	v_pk_fma_f32 v[60:61], v[56:57], s[54:55], v[246:247] op_sel_hi:[1,0,0]
	s_nop 0
	v_pk_fma_f32 v[60:61], v[56:57], v[60:61], s[58:59] op_sel_hi:[1,1,0]
	s_nop 0
	v_pk_fma_f32 v[60:61], v[56:57], v[60:61], s[60:61] op_sel_hi:[1,1,0]
	s_nop 0
	v_pk_fma_f32 v[60:61], v[56:57], v[60:61], s[62:63] op_sel_hi:[1,1,0]
	s_nop 0
	v_pk_mul_f32 v[56:57], v[56:57], v[60:61]
	v_pk_mul_f32 v[60:61], v[48:49], v[48:49]
	v_max_f32_e32 v48, 0, v48
	v_pk_mul_f32 v[60:61], v[60:61], s[64:65] op_sel_hi:[1,0]
	v_max_f32_e32 v49, 0, v49
	v_exp_f32_e32 v60, v60
	v_exp_f32_e32 v61, v61
	s_nop 0
	v_pk_mul_f32 v[56:57], v[60:61], v[56:57]
	s_nop 0
	v_pk_fma_f32 v[48:49], v[52:53], v[56:57], v[48:49] neg_lo:[1,0,0] neg_hi:[1,0,0]
	s_nop 0
	v_pk_mul_f32 v[48:49], v[32:33], v[48:49]
	v_pk_mul_f32 v[48:49], v[170:171], v[48:49] op_sel_hi:[0,1]
	v_cvt_pk_bf16_f32 v128, v48, v49
	ds_read2st64_b64 v[68:71], v121 offset0:10 offset1:11
	ds_read2st64_b64 v[64:67], v121 offset0:12 offset1:13
	v_mov_b32_e32 v32, 0
	v_mov_b32_e32 v48, 0
	v_mov_b32_e32 v49, 0
	s_cbranch_vccnz .LBB0_743
	v_add_u32_e32 v33, s87, v120
	ds_read_b64 v[48:49], v33 offset:1544

.LBB0_745:
	v_mov_b32_e32 v177, v176
	v_mov_b32_e32 v173, v172
	v_mov_b32_e32 v179, v178
	v_mul_f32_e32 v52, v58, v170
	v_mul_f32_e32 v56, v59, v170
	v_pk_mul_f32 v[58:59], v[62:63], v[176:177]
	v_pk_mul_f32 v[50:51], v[50:51], v[172:173]
	v_pk_mul_f32 v[54:55], v[54:55], v[178:179]
	v_mov_b32_dpp v45, v58 row_ror:1 row_mask:0xf bank_mask:0xf
	v_mov_b32_dpp v53, v58 row_ror:15 row_mask:0xf bank_mask:0xf
	s_waitcnt lgkmcnt(0)
	v_mov_b32_dpp v48, v50 row_shr:1 row_mask:0xf bank_mask:0xf
	v_mov_b32_dpp v49, v51 row_shr:1 row_mask:0xf bank_mask:0xf
	v_mov_b32_dpp v45, v52 row_shr:1 row_mask:0xf bank_mask:0xf
	v_mov_b32_dpp v61, v54 row_ror:1 row_mask:0xf bank_mask:0xf
	v_mov_b32_dpp v60, v54 row_ror:15 row_mask:0xf bank_mask:0xf
	v_mov_b32_dpp v75, v55 row_ror:1 row_mask:0xf bank_mask:0xf
	v_mov_b32_dpp v63, v55 row_ror:15 row_mask:0xf bank_mask:0xf
	v_mov_b32_dpp v53, v54 row_shl:1 row_mask:0xf bank_mask:0xf
	v_mov_b32_dpp v62, v50 row_ror:1 row_mask:0xf bank_mask:0xf
	v_mov_b32_dpp v79, v51 row_ror:1 row_mask:0xf bank_mask:0xf
	v_cndmask_b32_e64 v48, v48, 0, s[14:15]
	v_cndmask_b32_e64 v49, v49, 0, s[14:15]
	v_mov_b32_dpp v37, v52 row_ror:15 row_mask:0xf bank_mask:0xf
	v_mov_b32_dpp v57, v59 row_ror:1 row_mask:0xf bank_mask:0xf
	v_mov_b32_dpp v61, v58 row_shr:1 row_mask:0xf bank_mask:0xf
	v_mov_b32_dpp v75, v59 row_shr:1 row_mask:0xf bank_mask:0xf
	v_mov_b32_dpp v62, v54 row_shr:1 row_mask:0xf bank_mask:0xf
	v_mov_b32_dpp v60, v50 row_shl:1 row_mask:0xf bank_mask:0xf
	v_mov_b32_dpp v79, v55 row_shr:1 row_mask:0xf bank_mask:0xf
	v_mov_b32_dpp v63, v51 row_shl:1 row_mask:0xf bank_mask:0xf
	v_cndmask_b32_e64 v72, v53, 0, s[18:19]
	v_cndmask_b32_e64 v53, v45, 0, s[10:11]
	v_mov_b32_e32 v82, v70
	v_mov_b32_e32 v83, v68
	v_pk_mul_f32 v[48:49], v[68:69], v[48:49]
	v_mov_b32_dpp v32, v52 row_shl:1 row_mask:0xf bank_mask:0xf
	v_mov_b32_dpp v37, v58 row_shl:1 row_mask:0xf bank_mask:0xf
	v_mov_b32_dpp v57, v56 row_shr:1 row_mask:0xf bank_mask:0xf
	v_cndmask_b32_e64 v60, v60, 0, s[16:17]
	v_cndmask_b32_e64 v62, v62, 0, s[6:7]
	v_cndmask_b32_e64 v74, v61, 0, s[8:9]
	v_pk_mul_f32 v[52:53], v[52:53], v[82:83]
	v_cndmask_b32_e64 v61, v63, 0, s[16:17]
	v_pk_fma_f32 v[48:49], v[50:51], v[70:71], v[48:49]
	v_cndmask_b32_e64 v63, v79, 0, s[6:7]
	v_cndmask_b32_e64 v75, v75, 0, s[8:9]
	v_mov_b32_dpp v73, v59 row_ror:15 row_mask:0xf bank_mask:0xf
	v_cndmask_b32_e64 v80, v37, 0, s[20:21]
	v_add_f32_e32 v37, v52, v53
	v_cndmask_b32_e64 v32, v32, 0, s[12:13]
	v_pk_fma_f32 v[48:49], v[64:65], v[60:61], v[48:49]
	v_pk_mul_f32 v[50:51], v[68:69], v[62:63]
	v_pk_mul_f32 v[52:53], v[68:69], v[74:75]
	v_cndmask_b32_e64 v57, v57, 0, s[10:11]
	v_mov_b32_e32 v68, v71
	v_mov_b32_dpp v73, v55 row_shl:1 row_mask:0xf bank_mask:0xf
	v_fmac_f32_e32 v37, v64, v32
	v_pk_add_f32 v[48:49], v[66:67], v[48:49]
	v_pk_fma_f32 v[50:51], v[54:55], v[70:71], v[50:51]
	v_pk_mul_f32 v[54:55], v[56:57], v[68:69]
	v_add_f32_e32 v32, v66, v37
	v_add_f32_e32 v37, v54, v55
	v_and_b32_e32 v55, 0x7fffffff, v49
	v_and_b32_e32 v54, 0x7fffffff, v48
	v_mov_b32_dpp v41, v56 row_ror:15 row_mask:0xf bank_mask:0xf
	v_mov_b32_dpp v33, v56 row_shl:1 row_mask:0xf bank_mask:0xf
	v_pk_fma_f32 v[56:57], v[54:55], s[52:53], 1.0 op_sel_hi:[1,0,0]
	v_mov_b32_dpp v41, v59 row_shl:1 row_mask:0xf bank_mask:0xf
	v_rcp_f32_e32 v56, v56
	v_rcp_f32_e32 v57, v57
	v_pk_fma_f32 v[52:53], v[58:59], v[70:71], v[52:53]
	v_pk_mul_f32 v[62:63], v[48:49], v[48:49]
	v_pk_fma_f32 v[60:61], v[56:57], s[54:55], v[246:247] op_sel_hi:[1,0,0]
	v_pk_mul_f32 v[62:63], v[62:63], s[64:65] op_sel_hi:[1,0]
	v_pk_fma_f32 v[60:61], v[56:57], v[60:61], s[58:59] op_sel_hi:[1,1,0]
	v_exp_f32_e32 v62, v62
	v_exp_f32_e32 v63, v63
	v_pk_fma_f32 v[60:61], v[56:57], v[60:61], s[60:61] op_sel_hi:[1,1,0]
	v_cndmask_b32_e64 v73, v73, 0, s[18:19]
	v_pk_fma_f32 v[60:61], v[56:57], v[60:61], s[62:63] op_sel_hi:[1,1,0]
	v_pk_fma_f32 v[50:51], v[64:65], v[72:73], v[50:51]
	v_pk_mul_f32 v[56:57], v[56:57], v[60:61]
	v_pk_add_f32 v[50:51], v[66:67], v[50:51]
	v_max_f32_e32 v48, 0, v48
	v_max_f32_e32 v49, 0, v49
	v_pk_mul_f32 v[56:57], v[62:63], v[56:57]
	v_cndmask_b32_e64 v33, v33, 0, s[12:13]
	v_pk_fma_f32 v[48:49], v[54:55], v[56:57], v[48:49] neg_lo:[1,0,0] neg_hi:[1,0,0]
	v_and_b32_e32 v55, 0x7fffffff, v51
	v_and_b32_e32 v54, 0x7fffffff, v50
	v_pk_fma_f32 v[56:57], v[54:55], s[52:53], 1.0 op_sel_hi:[1,0,0]
	v_fmac_f32_e32 v37, v65, v33
	v_rcp_f32_e32 v56, v56
	v_rcp_f32_e32 v57, v57
	v_cndmask_b32_e64 v81, v41, 0, s[20:21]
	v_add_f32_e32 v33, v67, v37
	v_mul_f32_e32 v37, v46, v48
	v_mul_f32_e32 v41, v47, v49
	v_pk_mul_f32 v[48:49], v[50:51], v[50:51]
	v_pk_fma_f32 v[46:47], v[56:57], s[54:55], v[246:247] op_sel_hi:[1,0,0]
	v_pk_mul_f32 v[48:49], v[48:49], s[64:65] op_sel_hi:[1,0]
	v_pk_fma_f32 v[46:47], v[56:57], v[46:47], s[58:59] op_sel_hi:[1,1,0]
	v_exp_f32_e32 v48, v48
	v_exp_f32_e32 v49, v49
	v_pk_fma_f32 v[46:47], v[56:57], v[46:47], s[60:61] op_sel_hi:[1,1,0]
	v_pk_fma_f32 v[52:53], v[64:65], v[80:81], v[52:53]
	v_pk_fma_f32 v[46:47], v[56:57], v[46:47], s[62:63] op_sel_hi:[1,1,0]
	v_pk_add_f32 v[52:53], v[66:67], v[52:53]
	v_pk_mul_f32 v[46:47], v[56:57], v[46:47]
	v_max_f32_e32 v50, 0, v50
	v_max_f32_e32 v51, 0, v51
	v_pk_mul_f32 v[46:47], v[48:49], v[46:47]
	v_and_b32_e32 v49, 0x7fffffff, v53
	v_and_b32_e32 v48, 0x7fffffff, v52
	v_pk_fma_f32 v[46:47], v[54:55], v[46:47], v[50:51] neg_lo:[1,0,0] neg_hi:[1,0,0]
	v_pk_fma_f32 v[50:51], v[48:49], s[52:53], 1.0 op_sel_hi:[1,0,0]
	v_mul_f32_e32 v37, v172, v37
	v_rcp_f32_e32 v50, v50
	v_rcp_f32_e32 v51, v51
	v_mul_f32_e32 v41, v172, v41
	v_cvt_pk_bf16_f32 v45, v37, v41
	v_mul_f32_e32 v37, v42, v46
	v_mul_f32_e32 v41, v43, v47
	v_pk_mul_f32 v[46:47], v[52:53], v[52:53]
	v_pk_fma_f32 v[42:43], v[50:51], s[54:55], v[246:247] op_sel_hi:[1,0,0]
	v_pk_mul_f32 v[46:47], v[46:47], s[64:65] op_sel_hi:[1,0]
	v_pk_fma_f32 v[42:43], v[50:51], v[42:43], s[58:59] op_sel_hi:[1,1,0]
	v_exp_f32_e32 v46, v46
	v_exp_f32_e32 v47, v47
	v_pk_fma_f32 v[42:43], v[50:51], v[42:43], s[60:61] op_sel_hi:[1,1,0]
	v_mul_f32_e32 v37, v178, v37
	v_pk_fma_f32 v[42:43], v[50:51], v[42:43], s[62:63] op_sel_hi:[1,1,0]
	v_mul_f32_e32 v41, v178, v41
	v_pk_mul_f32 v[42:43], v[50:51], v[42:43]
	v_max_f32_e32 v50, 0, v52
	v_max_f32_e32 v51, 0, v53
	v_pk_mul_f32 v[42:43], v[46:47], v[42:43]
	v_and_b32_e32 v47, 0x7fffffff, v33
	v_and_b32_e32 v46, 0x7fffffff, v32
	v_pk_fma_f32 v[42:43], v[48:49], v[42:43], v[50:51] neg_lo:[1,0,0] neg_hi:[1,0,0]
	v_pk_fma_f32 v[48:49], v[46:47], s[52:53], 1.0 op_sel_hi:[1,0,0]
	v_cvt_pk_bf16_f32 v41, v37, v41
	v_mul_f32_e32 v37, v38, v42
	v_rcp_f32_e32 v48, v48
	v_rcp_f32_e32 v49, v49
	v_mul_f32_e32 v38, v39, v43
	v_mul_f32_e32 v37, v176, v37
	v_mul_f32_e32 v38, v176, v38
	v_pk_mul_f32 v[42:43], v[32:33], v[32:33]
	v_cvt_pk_bf16_f32 v37, v37, v38
	v_pk_fma_f32 v[38:39], v[48:49], s[54:55], v[246:247] op_sel_hi:[1,0,0]
	v_pk_mul_f32 v[42:43], v[42:43], s[64:65] op_sel_hi:[1,0]
	v_pk_fma_f32 v[38:39], v[48:49], v[38:39], s[58:59] op_sel_hi:[1,1,0]
	v_exp_f32_e32 v42, v42
	v_exp_f32_e32 v43, v43
	v_pk_fma_f32 v[38:39], v[48:49], v[38:39], s[60:61] op_sel_hi:[1,1,0]
	v_max_f32_e32 v32, 0, v32
	v_pk_fma_f32 v[38:39], v[48:49], v[38:39], s[62:63] op_sel_hi:[1,1,0]
	v_max_f32_e32 v33, 0, v33
	v_pk_mul_f32 v[38:39], v[48:49], v[38:39]
	s_and_b64 vcc, exec, s[22:23]
	v_pk_mul_f32 v[38:39], v[42:43], v[38:39]
	v_mov_b32_e32 v42, 0
	v_pk_fma_f32 v[32:33], v[46:47], v[38:39], v[32:33] neg_lo:[1,0,0] neg_hi:[1,0,0]
	v_mov_b32_e32 v38, 0
	v_pk_mul_f32 v[32:33], v[34:35], v[32:33]
	v_pk_mul_f32 v[32:33], v[170:171], v[32:33] op_sel_hi:[0,1]
	v_cvt_pk_bf16_f32 v129, v32, v33
	ds_read2st64_b64 v[46:49], v122 offset0:10 offset1:11
	ds_read2st64_b64 v[32:35], v122 offset0:12 offset1:13
	v_mov_b32_e32 v43, 0
	s_cbranch_vccnz .LBB0_747
	v_add_u32_e32 v39, s87, v120
	ds_read_b64 v[42:43], v39 offset:1552

.LBB0_749:
	v_pk_mul_f32 v[24:25], v[24:25], v[178:179]
	v_pk_mul_f32 v[16:17], v[16:17], v[172:173]
	v_pk_mul_f32 v[28:29], v[28:29], v[176:177]
	v_mov_b32_dpp v55, v24 row_ror:1 row_mask:0xf bank_mask:0xf
	s_waitcnt lgkmcnt(0)
	v_mov_b32_dpp v42, v16 row_shr:1 row_mask:0xf bank_mask:0xf
	v_mov_b32_dpp v54, v16 row_ror:1 row_mask:0xf bank_mask:0xf
	v_mov_b32_dpp v43, v17 row_shr:1 row_mask:0xf bank_mask:0xf
	v_mov_b32_dpp v66, v17 row_ror:1 row_mask:0xf bank_mask:0xf
	v_mul_f32_e32 v20, v20, v170
	v_mul_f32_e32 v50, v21, v170
	v_mov_b32_dpp v21, v28 row_ror:1 row_mask:0xf bank_mask:0xf
	v_mov_b32_dpp v53, v28 row_ror:15 row_mask:0xf bank_mask:0xf
	v_mov_b32_dpp v52, v24 row_ror:15 row_mask:0xf bank_mask:0xf
	v_mov_b32_dpp v59, v25 row_ror:1 row_mask:0xf bank_mask:0xf
	v_mov_b32_dpp v65, v25 row_ror:15 row_mask:0xf bank_mask:0xf
	v_mov_b32_dpp v55, v28 row_shr:1 row_mask:0xf bank_mask:0xf
	v_mov_b32_dpp v54, v24 row_shr:1 row_mask:0xf bank_mask:0xf
	v_mov_b32_dpp v66, v25 row_shr:1 row_mask:0xf bank_mask:0xf
	v_cndmask_b32_e64 v42, v42, 0, s[14:15]
	v_cndmask_b32_e64 v43, v43, 0, s[14:15]
	v_mov_b32_dpp v21, v20 row_shr:1 row_mask:0xf bank_mask:0xf
	v_mov_b32_dpp v53, v24 row_shl:1 row_mask:0xf bank_mask:0xf
	v_mov_b32_dpp v59, v29 row_shr:1 row_mask:0xf bank_mask:0xf
	v_mov_b32_dpp v52, v16 row_shl:1 row_mask:0xf bank_mask:0xf
	v_mov_b32_dpp v65, v17 row_shl:1 row_mask:0xf bank_mask:0xf
	v_cndmask_b32_e64 v54, v54, 0, s[6:7]
	v_cndmask_b32_e64 v58, v55, 0, s[8:9]
	v_pk_mul_f32 v[42:43], v[46:47], v[42:43]
	v_cndmask_b32_e64 v55, v66, 0, s[6:7]
	v_mov_b32_dpp v51, v20 row_ror:15 row_mask:0xf bank_mask:0xf
	v_mov_b32_dpp v61, v50 row_ror:15 row_mask:0xf bank_mask:0xf
	v_mov_b32_dpp v64, v29 row_ror:1 row_mask:0xf bank_mask:0xf
	v_mov_b32_dpp v57, v29 row_ror:15 row_mask:0xf bank_mask:0xf
	v_cndmask_b32_e64 v52, v52, 0, s[16:17]
	v_cndmask_b32_e64 v56, v53, 0, s[18:19]
	v_cndmask_b32_e64 v21, v21, 0, s[10:11]
	v_mov_b32_e32 v62, v48
	v_mov_b32_e32 v63, v46
	v_cndmask_b32_e64 v53, v65, 0, s[16:17]
	v_pk_fma_f32 v[16:17], v[16:17], v[48:49], v[42:43]
	v_pk_mul_f32 v[42:43], v[46:47], v[54:55]
	v_cndmask_b32_e64 v59, v59, 0, s[8:9]
	v_mov_b32_dpp v38, v20 row_shl:1 row_mask:0xf bank_mask:0xf
	v_mov_b32_dpp v51, v28 row_shl:1 row_mask:0xf bank_mask:0xf
	v_mov_b32_dpp v64, v50 row_shr:1 row_mask:0xf bank_mask:0xf
	v_mov_b32_dpp v61, v29 row_shl:1 row_mask:0xf bank_mask:0xf
	v_mov_b32_dpp v57, v25 row_shl:1 row_mask:0xf bank_mask:0xf
	v_pk_mul_f32 v[20:21], v[20:21], v[62:63]
	v_pk_fma_f32 v[16:17], v[32:33], v[52:53], v[16:17]
	v_pk_fma_f32 v[24:25], v[24:25], v[48:49], v[42:43]
	v_pk_mul_f32 v[42:43], v[46:47], v[58:59]
	v_mov_b32_dpp v39, v50 row_shl:1 row_mask:0xf bank_mask:0xf
	v_cndmask_b32_e64 v60, v51, 0, s[20:21]
	v_add_f32_e32 v20, v20, v21
	v_cndmask_b32_e64 v21, v38, 0, s[12:13]
	v_pk_add_f32 v[16:17], v[34:35], v[16:17]
	v_cndmask_b32_e64 v57, v57, 0, s[18:19]
	v_cndmask_b32_e64 v61, v61, 0, s[20:21]
	v_pk_fma_f32 v[28:29], v[28:29], v[48:49], v[42:43]
	v_cndmask_b32_e64 v51, v64, 0, s[10:11]
	v_mov_b32_e32 v46, v49
	v_fmac_f32_e32 v20, v32, v21
	v_pk_fma_f32 v[24:25], v[32:33], v[56:57], v[24:25]
	v_pk_fma_f32 v[28:29], v[32:33], v[60:61], v[28:29]
	v_pk_mul_f32 v[42:43], v[50:51], v[46:47]
	v_cndmask_b32_e64 v32, v39, 0, s[12:13]
	v_and_b32_e32 v39, 0x7fffffff, v17
	v_and_b32_e32 v38, 0x7fffffff, v16
	v_add_f32_e32 v21, v42, v43
	v_pk_fma_f32 v[42:43], v[38:39], s[52:53], 1.0 op_sel_hi:[1,0,0]
	v_fmac_f32_e32 v21, v33, v32
	v_rcp_f32_e32 v42, v42
	v_rcp_f32_e32 v43, v43
	v_pk_mul_f32 v[46:47], v[16:17], v[16:17]
	v_add_f32_e32 v20, v34, v20
	v_pk_add_f32 v[24:25], v[34:35], v[24:25]
	v_pk_add_f32 v[28:29], v[34:35], v[28:29]
	v_add_f32_e32 v21, v35, v21
	v_pk_fma_f32 v[34:35], v[42:43], s[54:55], v[246:247] op_sel_hi:[1,0,0]
	v_pk_mul_f32 v[46:47], v[46:47], s[64:65] op_sel_hi:[1,0]
	v_pk_fma_f32 v[34:35], v[42:43], v[34:35], s[58:59] op_sel_hi:[1,1,0]
	v_exp_f32_e32 v46, v46
	v_exp_f32_e32 v47, v47
	v_pk_fma_f32 v[34:35], v[42:43], v[34:35], s[60:61] op_sel_hi:[1,1,0]
	v_max_f32_e32 v16, 0, v16
	v_pk_fma_f32 v[34:35], v[42:43], v[34:35], s[62:63] op_sel_hi:[1,1,0]
	v_max_f32_e32 v17, 0, v17
	v_pk_mul_f32 v[34:35], v[42:43], v[34:35]
	s_and_b64 vcc, exec, s[22:23]
	v_pk_mul_f32 v[34:35], v[46:47], v[34:35]
	s_nop 0
	v_pk_fma_f32 v[16:17], v[38:39], v[34:35], v[16:17] neg_lo:[1,0,0] neg_hi:[1,0,0]
	v_and_b32_e32 v35, 0x7fffffff, v25
	v_and_b32_e32 v34, 0x7fffffff, v24
	v_pk_fma_f32 v[38:39], v[34:35], s[52:53], 1.0 op_sel_hi:[1,0,0]
	v_mul_f32_e32 v12, v12, v16
	v_rcp_f32_e32 v38, v38
	v_rcp_f32_e32 v39, v39
	v_mul_f32_e32 v13, v13, v17
	v_mul_f32_e32 v12, v172, v12
	v_mul_f32_e32 v13, v172, v13
	v_pk_mul_f32 v[16:17], v[24:25], v[24:25]
	v_cvt_pk_bf16_f32 v46, v12, v13
	v_pk_fma_f32 v[12:13], v[38:39], s[54:55], v[246:247] op_sel_hi:[1,0,0]
	v_pk_mul_f32 v[16:17], v[16:17], s[64:65] op_sel_hi:[1,0]
	v_pk_fma_f32 v[12:13], v[38:39], v[12:13], s[58:59] op_sel_hi:[1,1,0]
	v_exp_f32_e32 v16, v16
	v_exp_f32_e32 v17, v17
	v_pk_fma_f32 v[12:13], v[38:39], v[12:13], s[60:61] op_sel_hi:[1,1,0]
	v_max_f32_e32 v24, 0, v24
	v_pk_fma_f32 v[12:13], v[38:39], v[12:13], s[62:63] op_sel_hi:[1,1,0]
	v_max_f32_e32 v25, 0, v25
	v_pk_mul_f32 v[12:13], v[38:39], v[12:13]
	s_nop 0
	v_pk_mul_f32 v[12:13], v[16:17], v[12:13]
	v_and_b32_e32 v17, 0x7fffffff, v29
	v_and_b32_e32 v16, 0x7fffffff, v28
	v_pk_fma_f32 v[12:13], v[34:35], v[12:13], v[24:25] neg_lo:[1,0,0] neg_hi:[1,0,0]
	v_pk_fma_f32 v[24:25], v[16:17], s[52:53], 1.0 op_sel_hi:[1,0,0]
	v_mul_f32_e32 v8, v8, v12
	v_rcp_f32_e32 v24, v24
	v_rcp_f32_e32 v25, v25
	v_mul_f32_e32 v9, v9, v13
	v_mul_f32_e32 v8, v178, v8
	v_mul_f32_e32 v9, v178, v9
	v_pk_mul_f32 v[12:13], v[28:29], v[28:29]
	v_cvt_pk_bf16_f32 v42, v8, v9
	v_pk_fma_f32 v[8:9], v[24:25], s[54:55], v[246:247] op_sel_hi:[1,0,0]
	v_pk_mul_f32 v[12:13], v[12:13], s[64:65] op_sel_hi:[1,0]
	v_pk_fma_f32 v[8:9], v[24:25], v[8:9], s[58:59] op_sel_hi:[1,1,0]
	v_exp_f32_e32 v12, v12
	v_exp_f32_e32 v13, v13
	v_pk_fma_f32 v[8:9], v[24:25], v[8:9], s[60:61] op_sel_hi:[1,1,0]
	s_nop 0
	v_pk_fma_f32 v[8:9], v[24:25], v[8:9], s[62:63] op_sel_hi:[1,1,0]
	s_nop 0
	v_pk_mul_f32 v[8:9], v[24:25], v[8:9]
	v_max_f32_e32 v24, 0, v28
	v_max_f32_e32 v25, 0, v29
	v_pk_mul_f32 v[8:9], v[12:13], v[8:9]
	v_and_b32_e32 v13, 0x7fffffff, v21
	v_and_b32_e32 v12, 0x7fffffff, v20
	v_pk_fma_f32 v[8:9], v[16:17], v[8:9], v[24:25] neg_lo:[1,0,0] neg_hi:[1,0,0]
	v_pk_fma_f32 v[16:17], v[12:13], s[52:53], 1.0 op_sel_hi:[1,0,0]
	v_mul_f32_e32 v4, v4, v8
	v_rcp_f32_e32 v16, v16
	v_rcp_f32_e32 v17, v17
	v_mul_f32_e32 v5, v5, v9
	v_mul_f32_e32 v4, v176, v4
	v_mul_f32_e32 v5, v176, v5
	v_pk_mul_f32 v[8:9], v[20:21], v[20:21]
	v_cvt_pk_bf16_f32 v38, v4, v5
	v_pk_fma_f32 v[4:5], v[16:17], s[54:55], v[246:247] op_sel_hi:[1,0,0]
	v_pk_mul_f32 v[8:9], v[8:9], s[64:65] op_sel_hi:[1,0]
	v_pk_fma_f32 v[4:5], v[16:17], v[4:5], s[58:59] op_sel_hi:[1,1,0]
	v_exp_f32_e32 v8, v8
	v_exp_f32_e32 v9, v9
	v_pk_fma_f32 v[4:5], v[16:17], v[4:5], s[60:61] op_sel_hi:[1,1,0]
	s_nop 0
	v_pk_fma_f32 v[4:5], v[16:17], v[4:5], s[62:63] op_sel_hi:[1,1,0]
	s_nop 0
	v_pk_mul_f32 v[4:5], v[16:17], v[4:5]
	v_max_f32_e32 v16, 0, v20
	v_max_f32_e32 v17, 0, v21
	v_pk_mul_f32 v[4:5], v[8:9], v[4:5]
	s_nop 0
	v_pk_fma_f32 v[4:5], v[12:13], v[4:5], v[16:17] neg_lo:[1,0,0] neg_hi:[1,0,0]
	s_nop 0
	v_pk_mul_f32 v[4:5], v[0:1], v[4:5]
	v_pk_mul_f32 v[4:5], v[170:171], v[4:5] op_sel_hi:[0,1]
	v_cvt_pk_bf16_f32 v130, v4, v5
	ds_read2st64_b64 v[48:51], v76 offset0:10 offset1:11
	ds_read2st64_b64 v[32:35], v76 offset0:12 offset1:13
	v_mov_b32_e32 v0, 0
	v_mov_b32_e32 v4, 0
	v_mov_b32_e32 v5, 0
	s_cbranch_vccnz .LBB0_751
	v_add_u32_e32 v1, s87, v120
	ds_read_b64 v[4:5], v1 offset:1560

.LBB0_753:
	v_mul_f32_e32 v8, v22, v170
	v_pk_mul_f32 v[16:17], v[30:31], v[176:177]
	v_mul_f32_e32 v12, v23, v170
	v_mov_b32_dpp v9, v8 row_ror:15 row_mask:0xf bank_mask:0xf
	v_mov_b32_dpp v23, v16 row_ror:1 row_mask:0xf bank_mask:0xf
	v_pk_mul_f32 v[18:19], v[18:19], v[172:173]
	v_mov_b32_dpp v9, v16 row_shl:1 row_mask:0xf bank_mask:0xf
	v_mov_b32_dpp v23, v8 row_shr:1 row_mask:0xf bank_mask:0xf
	v_pk_mul_f32 v[20:21], v[26:27], v[178:179]
	s_waitcnt lgkmcnt(0)
	v_mov_b32_dpp v4, v18 row_shr:1 row_mask:0xf bank_mask:0xf
	v_mov_b32_dpp v5, v19 row_shr:1 row_mask:0xf bank_mask:0xf
	v_cndmask_b32_e64 v30, v9, 0, s[20:21]
	v_cndmask_b32_e64 v9, v23, 0, s[10:11]
	v_mov_b32_e32 v52, v50
	v_mov_b32_e32 v53, v48
	v_mov_b32_dpp v0, v8 row_shl:1 row_mask:0xf bank_mask:0xf
	v_mov_b32_dpp v25, v16 row_ror:15 row_mask:0xf bank_mask:0xf
	v_mov_b32_dpp v29, v17 row_ror:15 row_mask:0xf bank_mask:0xf
	v_mov_b32_dpp v27, v20 row_ror:1 row_mask:0xf bank_mask:0xf
	v_mov_b32_dpp v22, v20 row_ror:15 row_mask:0xf bank_mask:0xf
	v_mov_b32_dpp v31, v21 row_ror:1 row_mask:0xf bank_mask:0xf
	v_mov_b32_dpp v43, v21 row_ror:15 row_mask:0xf bank_mask:0xf
	v_mov_b32_dpp v24, v18 row_ror:1 row_mask:0xf bank_mask:0xf
	v_mov_b32_dpp v47, v19 row_ror:1 row_mask:0xf bank_mask:0xf
	v_cndmask_b32_e64 v4, v4, 0, s[14:15]
	v_pk_mul_f32 v[8:9], v[8:9], v[52:53]
	v_cndmask_b32_e64 v5, v5, 0, s[14:15]
	v_mov_b32_dpp v13, v12 row_ror:15 row_mask:0xf bank_mask:0xf
	v_mov_b32_dpp v39, v17 row_ror:1 row_mask:0xf bank_mask:0xf
	v_mov_b32_dpp v27, v16 row_shr:1 row_mask:0xf bank_mask:0xf
	v_mov_b32_dpp v25, v20 row_shl:1 row_mask:0xf bank_mask:0xf
	v_mov_b32_dpp v31, v17 row_shr:1 row_mask:0xf bank_mask:0xf
	v_mov_b32_dpp v29, v21 row_shl:1 row_mask:0xf bank_mask:0xf
	v_mov_b32_dpp v24, v20 row_shr:1 row_mask:0xf bank_mask:0xf
	v_mov_b32_dpp v22, v18 row_shl:1 row_mask:0xf bank_mask:0xf
	v_mov_b32_dpp v47, v21 row_shr:1 row_mask:0xf bank_mask:0xf
	v_mov_b32_dpp v43, v19 row_shl:1 row_mask:0xf bank_mask:0xf
	v_add_f32_e32 v8, v8, v9
	v_cndmask_b32_e64 v0, v0, 0, s[12:13]
	v_pk_mul_f32 v[4:5], v[48:49], v[4:5]
	v_mov_b32_dpp v39, v12 row_shr:1 row_mask:0xf bank_mask:0xf
	v_mov_b32_dpp v13, v17 row_shl:1 row_mask:0xf bank_mask:0xf
	v_cndmask_b32_e64 v22, v22, 0, s[16:17]
	v_cndmask_b32_e64 v24, v24, 0, s[6:7]
	v_cndmask_b32_e64 v26, v25, 0, s[18:19]
	v_cndmask_b32_e64 v28, v27, 0, s[8:9]
	v_fmac_f32_e32 v8, v32, v0
	v_cndmask_b32_e64 v23, v43, 0, s[16:17]
	v_pk_fma_f32 v[4:5], v[18:19], v[50:51], v[4:5]
	v_cndmask_b32_e64 v25, v47, 0, s[6:7]
	v_cndmask_b32_e64 v27, v29, 0, s[18:19]
	v_cndmask_b32_e64 v29, v31, 0, s[8:9]
	v_add_f32_e32 v0, v34, v8
	v_pk_fma_f32 v[4:5], v[32:33], v[22:23], v[4:5]
	v_pk_mul_f32 v[8:9], v[48:49], v[24:25]
	v_cndmask_b32_e64 v31, v13, 0, s[20:21]
	v_pk_mul_f32 v[18:19], v[48:49], v[28:29]
	v_cndmask_b32_e64 v13, v39, 0, s[10:11]
	v_mov_b32_e32 v48, v51
	v_mov_b32_dpp v1, v12 row_shl:1 row_mask:0xf bank_mask:0xf
	v_pk_add_f32 v[4:5], v[34:35], v[4:5]
	v_pk_mul_f32 v[12:13], v[12:13], v[48:49]
	v_pk_fma_f32 v[8:9], v[20:21], v[50:51], v[8:9]
	v_add_f32_e32 v20, v12, v13
	v_and_b32_e32 v13, 0x7fffffff, v5
	v_and_b32_e32 v12, 0x7fffffff, v4
	v_pk_fma_f32 v[16:17], v[16:17], v[50:51], v[18:19]
	v_pk_fma_f32 v[18:19], v[12:13], s[52:53], 1.0 op_sel_hi:[1,0,0]
	v_cndmask_b32_e64 v1, v1, 0, s[12:13]
	v_rcp_f32_e32 v18, v18
	v_rcp_f32_e32 v19, v19
	v_fmac_f32_e32 v20, v33, v1
	v_add_f32_e32 v1, v35, v20
	v_pk_mul_f32 v[24:25], v[4:5], v[4:5]
	v_pk_fma_f32 v[22:23], v[18:19], s[54:55], v[246:247] op_sel_hi:[1,0,0]
	v_pk_mul_f32 v[24:25], v[24:25], s[64:65] op_sel_hi:[1,0]
	v_pk_fma_f32 v[22:23], v[18:19], v[22:23], s[58:59] op_sel_hi:[1,1,0]
	v_exp_f32_e32 v24, v24
	v_exp_f32_e32 v25, v25
	v_pk_fma_f32 v[22:23], v[18:19], v[22:23], s[60:61] op_sel_hi:[1,1,0]
	v_pk_fma_f32 v[8:9], v[32:33], v[26:27], v[8:9]
	v_pk_fma_f32 v[22:23], v[18:19], v[22:23], s[62:63] op_sel_hi:[1,1,0]
	v_pk_add_f32 v[8:9], v[34:35], v[8:9]
	v_pk_mul_f32 v[18:19], v[18:19], v[22:23]
	v_max_f32_e32 v4, 0, v4
	v_max_f32_e32 v5, 0, v5
	v_pk_mul_f32 v[18:19], v[24:25], v[18:19]
	v_pk_fma_f32 v[16:17], v[32:33], v[30:31], v[16:17]
	v_pk_fma_f32 v[4:5], v[12:13], v[18:19], v[4:5] neg_lo:[1,0,0] neg_hi:[1,0,0]
	v_and_b32_e32 v13, 0x7fffffff, v9
	v_and_b32_e32 v12, 0x7fffffff, v8
	v_pk_fma_f32 v[18:19], v[12:13], s[52:53], 1.0 op_sel_hi:[1,0,0]
	v_rcp_f32_e32 v18, v18
	v_rcp_f32_e32 v19, v19
	v_pk_mul_f32 v[4:5], v[14:15], v[4:5]
	v_pk_mul_f32 v[4:5], v[172:173], v[4:5] op_sel_hi:[0,1]
	v_pk_mul_f32 v[14:15], v[8:9], v[8:9]
	v_cvt_pk_bf16_f32 v47, v4, v5
	v_pk_fma_f32 v[4:5], v[18:19], s[54:55], v[246:247] op_sel_hi:[1,0,0]
	v_pk_mul_f32 v[14:15], v[14:15], s[64:65] op_sel_hi:[1,0]
	v_pk_fma_f32 v[4:5], v[18:19], v[4:5], s[58:59] op_sel_hi:[1,1,0]
	v_exp_f32_e32 v14, v14
	v_exp_f32_e32 v15, v15
	v_pk_fma_f32 v[4:5], v[18:19], v[4:5], s[60:61] op_sel_hi:[1,1,0]
	v_pk_add_f32 v[16:17], v[34:35], v[16:17]
	v_pk_fma_f32 v[4:5], v[18:19], v[4:5], s[62:63] op_sel_hi:[1,1,0]
	v_max_f32_e32 v8, 0, v8
	v_pk_mul_f32 v[4:5], v[18:19], v[4:5]
	v_max_f32_e32 v9, 0, v9
	v_pk_mul_f32 v[4:5], v[14:15], v[4:5]
	v_cmp_gt_i32_e64 s[6:7], s78, v78
	v_pk_fma_f32 v[4:5], v[12:13], v[4:5], v[8:9] neg_lo:[1,0,0] neg_hi:[1,0,0]
	v_and_b32_e32 v9, 0x7fffffff, v17
	v_and_b32_e32 v8, 0x7fffffff, v16
	v_pk_fma_f32 v[12:13], v[8:9], s[52:53], 1.0 op_sel_hi:[1,0,0]
	v_rcp_f32_e32 v12, v12
	v_rcp_f32_e32 v13, v13
	v_pk_mul_f32 v[4:5], v[10:11], v[4:5]
	v_pk_mul_f32 v[4:5], v[178:179], v[4:5] op_sel_hi:[0,1]
	v_pk_mul_f32 v[10:11], v[16:17], v[16:17]
	v_cvt_pk_bf16_f32 v43, v4, v5
	v_pk_fma_f32 v[4:5], v[12:13], s[54:55], v[246:247] op_sel_hi:[1,0,0]
	v_pk_mul_f32 v[10:11], v[10:11], s[64:65] op_sel_hi:[1,0]
	v_pk_fma_f32 v[4:5], v[12:13], v[4:5], s[58:59] op_sel_hi:[1,1,0]
	v_exp_f32_e32 v10, v10
	v_exp_f32_e32 v11, v11
	v_pk_fma_f32 v[4:5], v[12:13], v[4:5], s[60:61] op_sel_hi:[1,1,0]
	s_nop 0
	v_pk_fma_f32 v[4:5], v[12:13], v[4:5], s[62:63] op_sel_hi:[1,1,0]
	s_nop 0
	v_pk_mul_f32 v[4:5], v[12:13], v[4:5]
	v_max_f32_e32 v12, 0, v16
	v_max_f32_e32 v13, 0, v17
	v_pk_mul_f32 v[4:5], v[10:11], v[4:5]
	s_nop 0
	v_pk_fma_f32 v[4:5], v[8:9], v[4:5], v[12:13] neg_lo:[1,0,0] neg_hi:[1,0,0]
	v_and_b32_e32 v9, 0x7fffffff, v1
	v_and_b32_e32 v8, 0x7fffffff, v0
	v_pk_fma_f32 v[10:11], v[8:9], s[52:53], 1.0 op_sel_hi:[1,0,0]
	v_rcp_f32_e32 v10, v10
	v_rcp_f32_e32 v11, v11
	v_pk_mul_f32 v[4:5], v[6:7], v[4:5]
	v_pk_mul_f32 v[4:5], v[176:177], v[4:5] op_sel_hi:[0,1]
	v_pk_mul_f32 v[6:7], v[0:1], v[0:1]
	v_cvt_pk_bf16_f32 v39, v4, v5
	v_pk_fma_f32 v[4:5], v[10:11], s[54:55], v[246:247] op_sel_hi:[1,0,0]
	v_pk_mul_f32 v[6:7], v[6:7], s[64:65] op_sel_hi:[1,0]
	v_pk_fma_f32 v[4:5], v[10:11], v[4:5], s[58:59] op_sel_hi:[1,1,0]
	v_exp_f32_e32 v6, v6
	v_exp_f32_e32 v7, v7
	v_pk_fma_f32 v[4:5], v[10:11], v[4:5], s[60:61] op_sel_hi:[1,1,0]
	v_max_f32_e32 v0, 0, v0
	v_pk_fma_f32 v[4:5], v[10:11], v[4:5], s[62:63] op_sel_hi:[1,1,0]
	v_max_f32_e32 v1, 0, v1
	v_pk_mul_f32 v[4:5], v[10:11], v[4:5]
	s_nop 0
	v_pk_mul_f32 v[4:5], v[6:7], v[4:5]
	s_nop 0
	v_pk_fma_f32 v[0:1], v[8:9], v[4:5], v[0:1] neg_lo:[1,0,0] neg_hi:[1,0,0]
	s_nop 0
	v_mul_f32_e32 v0, v2, v0
	v_mul_f32_e32 v0, v170, v0
	v_mul_f32_e32 v1, v3, v1
	v_mul_f32_e32 v1, v170, v1
	v_cvt_pk_bf16_f32 v131, v0, v1
	v_add_u32_e32 v0, -1, v77
	v_cmp_gt_u32_e32 vcc, s76, v0
	s_and_b64 s[8:9], vcc, s[6:7]
	s_and_saveexec_b64 s[6:7], s[8:9]
	s_cbranch_execz .LBB0_755
	v_mov_b64_e32 v[0:1], s[38:39]
	v_mad_i64_i32 v[0:1], s[8:9], v78, s31, v[0:1]
	v_lshl_add_u64 v[0:1], v[174:175], 1, v[0:1]
	global_store_dwordx4 v[0:1], v[44:47], off
